# scan: chunk-parity LDS addresses precomputed per phase (K=4 unrolled phases have static parity); y flush address = per-lane part + scalar chunk offset
# baseline (speedup 1.0000x reference)
; #define SC_GLOAD(ci_) { rg0 = SC_G1(ci_, 0); rg1 = SC_G1(ci_, 1); rg2 = SC_G1(ci_, 2); }
; #define SC_LSTORE(st_) { SC_S1(st_, 0, rg0) SC_S1(st_, 1, rg1) SC_S1(st_, 2, rg2) }
; __device__ __forceinline__ void rwkv_scan_unit(const Params& p, int unit, char* smem) {
;     ...
;     __syncthreads();
;     SC_GLOAD(0)
;     SC_LSTORE(0)
;     __syncthreads();
;     for (int ci = 0; ci < NCH; ++ci) {
;         const int st = (ci & 1) * STG;
;         if (ci + 1 < NCH) { SC_GLOAD(ci + 1) }
;         __builtin_amdgcn_sched_barrier(0);
;         const char* lb = smem + st + ks * 16;
;         const char* vb = smem + st + 1280 + rl * 4;
;         float* yl = (float*)(smem + YOFF + (ci & 1) * 1024) + rl;
;     ...
;             Yb[((size_t)b * TT + step_tok(ci * SCH + u, d)) * 1024 + r] = f2bf(*((const float*)(smem + YOFF + (ci & 1) * 1024) + u * 16 + r));
.LBB0_380:
	global_load_dword v39, v[152:153], off
	v_add_u32_e32 v87, 16, v87
	v_add_u32_e32 v85, 16, v85
	v_add_u32_e32 v83, 16, v83
	v_add_u32_e32 v88, -16, v88
	v_add_u32_e32 v86, -16, v86
	v_add_u32_e32 v84, -16, v84
	v_add_u32_e32 v142, s55, v87
	v_cmp_lt_i32_e32 vcc, s2, v142
	s_nop 1
	v_cndmask_b32_e32 v143, v196, v197, vcc
	v_add_u32_e32 v143, v143, v88
	v_cndmask_b32_e64 v142, v143, v142, s[44:45]
	v_ashrrev_i32_e32 v143, 31, v142
	v_lshl_add_u64 v[142:143], v[142:143], 0, s[88:89]
	v_lshlrev_b64 v[142:143], 9, v[142:143]
	v_lshl_add_u64 v[140:141], v[152:153], 0, v[142:143]
	global_load_dwordx4 v[140:143], v[140:141], off
	v_add_u32_e32 v146, s55, v85
	v_cmp_lt_i32_e32 vcc, s2, v146
	s_nop 1
	v_cndmask_b32_e32 v147, v196, v197, vcc
	v_add_u32_e32 v147, v147, v86
	v_cndmask_b32_e64 v146, v147, v146, s[44:45]
	v_ashrrev_i32_e32 v147, 31, v146
	v_lshl_add_u64 v[146:147], v[146:147], 0, s[88:89]
	v_lshlrev_b64 v[146:147], 9, v[146:147]
	v_lshl_add_u64 v[144:145], v[154:155], 0, v[146:147]
	global_load_dwordx4 v[144:147], v[144:145], off
	v_add_u32_e32 v150, s55, v83
	v_cmp_lt_i32_e32 vcc, s2, v150
	s_nop 1
	v_cndmask_b32_e32 v151, v196, v197, vcc
	v_add_u32_e32 v151, v151, v84
	v_cndmask_b32_e64 v150, v151, v150, s[44:45]
	v_ashrrev_i32_e32 v151, 31, v150
	v_lshl_add_u64 v[150:151], v[150:151], 0, s[88:89]
	v_lshlrev_b64 v[150:151], 9, v[150:151]
	v_lshl_add_u64 v[148:149], v[156:157], 0, v[150:151]
	global_load_dwordx4 v[148:151], v[148:149], off
	global_load_dword v39, v[152:153], off
	v_add_u32_e32 v87, 16, v87
	v_add_u32_e32 v85, 16, v85
	v_add_u32_e32 v83, 16, v83
	v_add_u32_e32 v88, -16, v88
	v_add_u32_e32 v86, -16, v86
	v_add_u32_e32 v84, -16, v84
	v_add_u32_e32 v126, s55, v87
	v_cmp_lt_i32_e32 vcc, s2, v126
	s_nop 1
	v_cndmask_b32_e32 v127, v196, v197, vcc
	v_add_u32_e32 v127, v127, v88
	v_cndmask_b32_e64 v126, v127, v126, s[44:45]
	v_ashrrev_i32_e32 v127, 31, v126
	v_lshl_add_u64 v[126:127], v[126:127], 0, s[88:89]
	v_lshlrev_b64 v[126:127], 9, v[126:127]
	v_lshl_add_u64 v[124:125], v[152:153], 0, v[126:127]
	global_load_dwordx4 v[124:127], v[124:125], off
	v_add_u32_e32 v130, s55, v85
	v_cmp_lt_i32_e32 vcc, s2, v130
	s_nop 1
	v_cndmask_b32_e32 v131, v196, v197, vcc
	v_add_u32_e32 v131, v131, v86
	v_cndmask_b32_e64 v130, v131, v130, s[44:45]
	v_ashrrev_i32_e32 v131, 31, v130
	v_lshl_add_u64 v[130:131], v[130:131], 0, s[88:89]
	v_lshlrev_b64 v[130:131], 9, v[130:131]
	v_lshl_add_u64 v[128:129], v[154:155], 0, v[130:131]
	global_load_dwordx4 v[128:131], v[128:129], off
	v_add_u32_e32 v134, s55, v83
	v_cmp_lt_i32_e32 vcc, s2, v134
	s_nop 1
	v_cndmask_b32_e32 v135, v196, v197, vcc
	v_add_u32_e32 v135, v135, v84
	v_cndmask_b32_e64 v134, v135, v134, s[44:45]
	v_ashrrev_i32_e32 v135, 31, v134
	v_lshl_add_u64 v[134:135], v[134:135], 0, s[88:89]
	v_lshlrev_b64 v[134:135], 9, v[134:135]
	v_lshl_add_u64 v[132:133], v[156:157], 0, v[134:135]
	global_load_dwordx4 v[132:135], v[132:133], off
	global_load_dword v39, v[152:153], off
	v_add_u32_e32 v87, 16, v87
	v_add_u32_e32 v85, 16, v85
	v_add_u32_e32 v83, 16, v83
	v_add_u32_e32 v88, -16, v88
	v_add_u32_e32 v86, -16, v86
	v_add_u32_e32 v84, -16, v84
	v_add_u32_e32 v230, s55, v88
	v_cndmask_b32_e64 v230, v230, v87, s[44:45]
	v_ashrrev_i32_e32 v231, 31, v230
	v_lshl_add_u64 v[230:231], v[230:231], 0, s[88:89]
	v_lshlrev_b64 v[230:231], 9, v[230:231]
	v_lshl_add_u64 v[224:225], v[152:153], 0, v[230:231]
	v_add_u32_e32 v230, s55, v86
	v_cndmask_b32_e64 v230, v230, v85, s[44:45]
	v_ashrrev_i32_e32 v231, 31, v230
	v_lshl_add_u64 v[230:231], v[230:231], 0, s[88:89]
	v_lshlrev_b64 v[230:231], 9, v[230:231]
	v_lshl_add_u64 v[226:227], v[154:155], 0, v[230:231]
	v_add_u32_e32 v230, s55, v84
	v_cndmask_b32_e64 v230, v230, v83, s[44:45]
	v_ashrrev_i32_e32 v231, 31, v230
	v_lshl_add_u64 v[230:231], v[230:231], 0, s[88:89]
	v_lshlrev_b64 v[230:231], 9, v[230:231]
	v_lshl_add_u64 v[228:229], v[156:157], 0, v[230:231]
	v_mov_b32_e32 v232, v80
	v_mov_b32_e32 v233, v81
	v_lshlrev_b32_e32 v244, 2, v72
	v_lshlrev_b32_e32 v245, 2, v109
	v_add_u32_e32 v245, 0x800, v245
	v_cndmask_b32_e64 v234, v245, v244, s[50:51]
	v_add_u32_e32 v238, v74, v75
	v_add_u32_e32 v239, v76, v77
	v_add_u32_e32 v240, v78, v79
	v_or_b32_e32 v235, 0x5400, v80
	v_add_u32_e32 v236, 0x5400, v81
	v_lshlrev_b32_e32 v244, 2, v72
	v_add_u32_e32 v244, 0x400, v244
	v_lshlrev_b32_e32 v245, 2, v109
	v_add_u32_e32 v245, 0x800, v245
	v_cndmask_b32_e64 v237, v245, v244, s[50:51]
	v_add_u32_e32 v241, v74, v75
	v_add_u32_e32 v241, 0x5400, v241
	v_add_u32_e32 v242, v76, v77
	v_add_u32_e32 v242, 0x5400, v242
	v_add_u32_e32 v243, v78, v79
	v_add_u32_e32 v243, 0x5400, v243
	v_lshlrev_b32_e32 v244, 2, v73
	v_add_u32_e32 v208, v89, v244
	v_add_u32_e32 v209, 0x400, v208
	v_add_u32_e32 v244, s55, v82
	v_cndmask_b32_e64 v244, v244, v71, s[44:45]
	v_ashrrev_i32_e32 v245, 31, v244
	v_lshl_add_u64 v[244:245], v[244:245], 0, s[88:89]
	v_lshlrev_b64 v[244:245], 11, v[244:245]
	v_lshl_add_u64 v[210:211], v[48:49], 0, v[244:245]

; __device__ __forceinline__ void rwkv_scan_unit(const Params& p, int unit, char* smem) {
;     ...
;         const char* lb = smem + st + ks * 16;
;         const char* vb = smem + st + 1280 + rl * 4;
;         float* yl = (float*)(smem + YOFF + (ci & 1) * 1024) + rl;
;         f32x4 e4 = *(const f32x4*)(lb), kd4 = *(const f32x4*)(lb + 256), ka4 = *(const f32x4*)(lb + 512), r4 = *(const f32x4*)(lb + 768), kk4 = *(const f32x4*)(lb + 1024);
;         float vv = *(const float*)vb;
;         f32x2 sA = {s0, s1}, sB = {s2, s3};
;         float c;
;         { const f32x2 cv = sA * (f32x2){kk4[0], kk4[1]} + sB * (f32x2){kk4[2], kk4[3]}; c = red16(cv[0] + cv[1]); }
; #pragma unroll
;         for (int u = 0; u < SCH; ++u) {
;             f32x4 ne = e4, nkd = kd4, nka = ka4, nr = r4, nkk = kk4; float nv = vv;
;             if (u + 1 < SCH) { const char* q = lb + (u + 1) * STEPB;
;                 ne = *(const f32x4*)(q); nkd = *(const f32x4*)(q + 256); nka = *(const f32x4*)(q + 512); nr = *(const f32x4*)(q + 768); nkk = *(const f32x4*)(q + 1024);
;                 nv = *(const float*)(vb + (u + 1) * STEPB); }
;             const f32x2 v2 = {vv, vv}, c2 = {c, c};
;             const f32x2 tA = __builtin_elementwise_fma(v2, (f32x2){kd4[0], kd4[1]}, __builtin_elementwise_fma(-sA, (f32x2){e4[0], e4[1]}, sA));
;             const f32x2 tB = __builtin_elementwise_fma(v2, (f32x2){kd4[2], kd4[3]}, __builtin_elementwise_fma(-sB, (f32x2){e4[2], e4[3]}, sB));
;             sA = __builtin_elementwise_fma(-c2, (f32x2){ka4[0], ka4[1]}, tA);
;             sB = __builtin_elementwise_fma(-c2, (f32x2){ka4[2], ka4[3]}, tB);
;             const f32x2 yv = __builtin_elementwise_fma(sB, (f32x2){r4[2], r4[3]}, sA * (f32x2){r4[0], r4[1]});
;             float y = yv[0] + yv[1];
;             if (u + 1 < SCH) {
;                 const f32x2 cv = __builtin_elementwise_fma(sB, (f32x2){nkk[2], nkk[3]}, sA * (f32x2){nkk[0], nkk[1]});
;                 float cn = cv[0] + cv[1];
;                 cn = DPP_ADD(cn, 0xB1);  y = DPP_ADD(y, 0xB1);
;                 cn = DPP_ADD(cn, 0x4E);  y = DPP_ADD(y, 0x4E);
;                 cn = DPP_ADD(cn, 0x141); y = DPP_ADD(y, 0x141);
;                 cn = DPP_ADD(cn, 0x140); y = DPP_ADD(y, 0x140);
;                 c = cn;
;             } else y = red16(y);
;             if (ks == 0) yl[u * 16] = y;
.Lsc_p0_body:
	s_add_i32 s30, s64, -1
	s_and_b32 s30, s30, 1
	ds_read_b128 v[32:35], v232 offset:1024
	ds_read_b128 v[12:15], v232 offset:0
	ds_read_b128 v[16:19], v232 offset:256
	ds_read_b32 v36, v233 offset:1280
	ds_read_b128 v[24:27], v232 offset:512
	ds_read_b128 v[28:31], v232 offset:768
	ds_read_b128 v[40:43], v232 offset:1344
	ds_read_b128 v[60:63], v232 offset:1856
	ds_read_b128 v[44:47], v232 offset:1600
	ds_read_b128 v[94:97], v232 offset:2368
	ds_read_b32 v38, v233 offset:2624
	ds_read_b128 v[64:67], v232 offset:2112
	s_lshl_b32 s52, s30, 10
	s_waitcnt lgkmcnt(11)
	v_pk_mul_f32 v[32:33], v[20:21], v[32:33]
	s_waitcnt lgkmcnt(10)
	v_pk_fma_f32 v[12:13], v[20:21], v[12:13], v[20:21] neg_lo:[1,0,0] neg_hi:[1,0,0]
	v_pk_fma_f32 v[32:33], v[22:23], v[34:35], v[32:33]
	v_pk_fma_f32 v[14:15], v[22:23], v[14:15], v[22:23] neg_lo:[1,0,0] neg_hi:[1,0,0]
	v_add_f32_e32 v34, v32, v33
	s_waitcnt lgkmcnt(8)
	v_pk_fma_f32 v[12:13], v[36:37], v[16:17], v[12:13] op_sel_hi:[0,1,1]
	v_pk_fma_f32 v[14:15], v[36:37], v[18:19], v[14:15] op_sel_hi:[0,1,1]
	v_add_f32_dpp v35, v34, v34 quad_perm:[1,0,3,2] row_mask:0xf bank_mask:0xf bound_ctrl:1
	s_nop 1
	v_add_f32_dpp v34, v35, v35 quad_perm:[2,3,0,1] row_mask:0xf bank_mask:0xf bound_ctrl:1
	s_nop 1
	v_add_f32_dpp v35, v34, v34 row_half_mirror row_mask:0xf bank_mask:0xf bound_ctrl:1
	s_nop 1
	v_add_f32_dpp v90, v35, v35 row_mirror row_mask:0xf bank_mask:0xf bound_ctrl:1
	ds_read_b128 v[16:19], v232 offset:2944
	ds_read_b128 v[32:35], v232 offset:3712
	ds_read_b32 v36, v233 offset:3968
	s_waitcnt lgkmcnt(10)
	v_pk_fma_f32 v[20:21], v[90:91], v[24:25], v[12:13] op_sel_hi:[0,1,1] neg_lo:[1,0,0] neg_hi:[1,0,0]
	v_pk_fma_f32 v[22:23], v[90:91], v[26:27], v[14:15] op_sel_hi:[0,1,1] neg_lo:[1,0,0] neg_hi:[1,0,0]
	ds_read_b128 v[12:15], v232 offset:2688
	ds_read_b128 v[24:27], v232 offset:3200
	s_waitcnt lgkmcnt(7)
	v_pk_mul_f32 v[94:95], v[20:21], v[94:95]
	v_pk_mul_f32 v[28:29], v[20:21], v[28:29]
	v_pk_fma_f32 v[94:95], v[22:23], v[96:97], v[94:95]
	v_pk_fma_f32 v[28:29], v[22:23], v[30:31], v[28:29]
	v_add_f32_e32 v96, v94, v95
	v_add_f32_e32 v30, v28, v29
	v_pk_fma_f32 v[40:41], v[20:21], v[40:41], v[20:21] neg_lo:[1,0,0] neg_hi:[1,0,0]
	v_add_f32_dpp v97, v96, v96 quad_perm:[1,0,3,2] row_mask:0xf bank_mask:0xf bound_ctrl:1
	v_add_f32_dpp v31, v30, v30 quad_perm:[1,0,3,2] row_mask:0xf bank_mask:0xf bound_ctrl:1
	v_pk_fma_f32 v[42:43], v[22:23], v[42:43], v[22:23] neg_lo:[1,0,0] neg_hi:[1,0,0]
	v_add_f32_dpp v96, v97, v97 quad_perm:[2,3,0,1] row_mask:0xf bank_mask:0xf bound_ctrl:1
	v_add_f32_dpp v30, v31, v31 quad_perm:[2,3,0,1] row_mask:0xf bank_mask:0xf bound_ctrl:1
	s_waitcnt lgkmcnt(6)
	v_pk_fma_f32 v[40:41], v[38:39], v[44:45], v[40:41] op_sel_hi:[0,1,1]
	v_add_f32_dpp v97, v96, v96 row_half_mirror row_mask:0xf bank_mask:0xf bound_ctrl:1
	v_add_f32_dpp v31, v30, v30 row_half_mirror row_mask:0xf bank_mask:0xf bound_ctrl:1
	v_pk_fma_f32 v[42:43], v[38:39], v[46:47], v[42:43] op_sel_hi:[0,1,1]
	v_add_f32_dpp v90, v97, v97 row_mirror row_mask:0xf bank_mask:0xf bound_ctrl:1
	v_add_f32_dpp v30, v31, v31 row_mirror row_mask:0xf bank_mask:0xf bound_ctrl:1
	ds_write_b32 v234, v30 offset:43008
	ds_read_b128 v[28:31], v232 offset:3456
	v_pk_fma_f32 v[20:21], v[90:91], v[60:61], v[40:41] op_sel_hi:[0,1,1] neg_lo:[1,0,0] neg_hi:[1,0,0]
	v_pk_fma_f32 v[22:23], v[90:91], v[62:63], v[42:43] op_sel_hi:[0,1,1] neg_lo:[1,0,0] neg_hi:[1,0,0]
	ds_read_b128 v[40:43], v232 offset:4032
	ds_read_b128 v[60:63], v232 offset:4544
	ds_read_b128 v[44:47], v232 offset:4288
	ds_read_b128 v[94:97], v232 offset:5056
	ds_read_b32 v38, v233 offset:5312
	s_waitcnt lgkmcnt(8)
	v_pk_mul_f32 v[32:33], v[20:21], v[32:33]
	v_pk_mul_f32 v[64:65], v[20:21], v[64:65]
	v_pk_fma_f32 v[32:33], v[22:23], v[34:35], v[32:33]
	v_pk_fma_f32 v[64:65], v[22:23], v[66:67], v[64:65]
	v_add_f32_e32 v34, v32, v33
	v_add_f32_e32 v66, v64, v65
	v_pk_fma_f32 v[12:13], v[20:21], v[12:13], v[20:21] neg_lo:[1,0,0] neg_hi:[1,0,0]
	v_add_f32_dpp v35, v34, v34 quad_perm:[1,0,3,2] row_mask:0xf bank_mask:0xf bound_ctrl:1
	v_add_f32_dpp v67, v66, v66 quad_perm:[1,0,3,2] row_mask:0xf bank_mask:0xf bound_ctrl:1
	v_pk_fma_f32 v[14:15], v[22:23], v[14:15], v[22:23] neg_lo:[1,0,0] neg_hi:[1,0,0]
	v_add_f32_dpp v34, v35, v35 quad_perm:[2,3,0,1] row_mask:0xf bank_mask:0xf bound_ctrl:1
	v_add_f32_dpp v66, v67, v67 quad_perm:[2,3,0,1] row_mask:0xf bank_mask:0xf bound_ctrl:1
	v_pk_fma_f32 v[12:13], v[36:37], v[16:17], v[12:13] op_sel_hi:[0,1,1]
	v_add_f32_dpp v35, v34, v34 row_half_mirror row_mask:0xf bank_mask:0xf bound_ctrl:1
	v_add_f32_dpp v67, v66, v66 row_half_mirror row_mask:0xf bank_mask:0xf bound_ctrl:1
	v_pk_fma_f32 v[14:15], v[36:37], v[18:19], v[14:15] op_sel_hi:[0,1,1]
	v_add_f32_dpp v90, v35, v35 row_mirror row_mask:0xf bank_mask:0xf bound_ctrl:1
	v_add_f32_dpp v66, v67, v67 row_mirror row_mask:0xf bank_mask:0xf bound_ctrl:1
	ds_write_b32 v234, v66 offset:43072
	ds_read_b128 v[64:67], v232 offset:4800
	s_waitcnt lgkmcnt(9)
	v_pk_fma_f32 v[20:21], v[90:91], v[24:25], v[12:13] op_sel_hi:[0,1,1] neg_lo:[1,0,0] neg_hi:[1,0,0]
	v_pk_fma_f32 v[22:23], v[90:91], v[26:27], v[14:15] op_sel_hi:[0,1,1] neg_lo:[1,0,0] neg_hi:[1,0,0]
	ds_read_b128 v[12:15], v232 offset:5376
	ds_read_b128 v[24:27], v232 offset:5888
	ds_read_b128 v[16:19], v232 offset:5632
	ds_read_b128 v[32:35], v232 offset:6400
	ds_read_b32 v36, v233 offset:6656
	s_waitcnt lgkmcnt(7)
; #define DPP_ADD(v, ctrl) ((v) + __builtin_bit_cast(float, __builtin_amdgcn_update_dpp(0, __builtin_bit_cast(int, (v)), (ctrl), 0xf, 0xf, true)))
; __device__ __forceinline__ void rwkv_scan_unit(const Params& p, int unit, char* smem) {
;     ...
;         for (int u = 0; u < SCH; ++u) {
;             f32x4 ne = e4, nkd = kd4, nka = ka4, nr = r4, nkk = kk4; float nv = vv;
;             if (u + 1 < SCH) { const char* q = lb + (u + 1) * STEPB;
;                 ne = *(const f32x4*)(q); nkd = *(const f32x4*)(q + 256); nka = *(const f32x4*)(q + 512); nr = *(const f32x4*)(q + 768); nkk = *(const f32x4*)(q + 1024);
;                 nv = *(const float*)(vb + (u + 1) * STEPB); }
;             const f32x2 v2 = {vv, vv}, c2 = {c, c};
;             const f32x2 tA = __builtin_elementwise_fma(v2, (f32x2){kd4[0], kd4[1]}, __builtin_elementwise_fma(-sA, (f32x2){e4[0], e4[1]}, sA));
;             const f32x2 tB = __builtin_elementwise_fma(v2, (f32x2){kd4[2], kd4[3]}, __builtin_elementwise_fma(-sB, (f32x2){e4[2], e4[3]}, sB));
;             sA = __builtin_elementwise_fma(-c2, (f32x2){ka4[0], ka4[1]}, tA);
;             sB = __builtin_elementwise_fma(-c2, (f32x2){ka4[2], ka4[3]}, tB);
;             const f32x2 yv = __builtin_elementwise_fma(sB, (f32x2){r4[2], r4[3]}, sA * (f32x2){r4[0], r4[1]});
;             float y = yv[0] + yv[1];
;             if (u + 1 < SCH) {
;                 const f32x2 cv = __builtin_elementwise_fma(sB, (f32x2){nkk[2], nkk[3]}, sA * (f32x2){nkk[0], nkk[1]});
;                 float cn = cv[0] + cv[1];
;                 cn = DPP_ADD(cn, 0xB1);  y = DPP_ADD(y, 0xB1);
;                 cn = DPP_ADD(cn, 0x4E);  y = DPP_ADD(y, 0x4E);
;                 cn = DPP_ADD(cn, 0x141); y = DPP_ADD(y, 0x141);
;                 cn = DPP_ADD(cn, 0x140); y = DPP_ADD(y, 0x140);
;                 c = cn;
;             } else y = red16(y);
;             if (ks == 0) yl[u * 16] = y;
;             e4 = ne; kd4 = nkd; ka4 = nka; r4 = nr; kk4 = nkk; vv = nv;
	v_pk_mul_f32 v[94:95], v[20:21], v[94:95]
	v_pk_mul_f32 v[28:29], v[20:21], v[28:29]
	v_pk_fma_f32 v[94:95], v[22:23], v[96:97], v[94:95]
	v_pk_fma_f32 v[28:29], v[22:23], v[30:31], v[28:29]
	v_add_f32_e32 v96, v94, v95
	v_add_f32_e32 v30, v28, v29
	v_pk_fma_f32 v[40:41], v[20:21], v[40:41], v[20:21] neg_lo:[1,0,0] neg_hi:[1,0,0]
	v_add_f32_dpp v97, v96, v96 quad_perm:[1,0,3,2] row_mask:0xf bank_mask:0xf bound_ctrl:1
	v_add_f32_dpp v31, v30, v30 quad_perm:[1,0,3,2] row_mask:0xf bank_mask:0xf bound_ctrl:1
	v_pk_fma_f32 v[42:43], v[22:23], v[42:43], v[22:23] neg_lo:[1,0,0] neg_hi:[1,0,0]
	v_add_f32_dpp v96, v97, v97 quad_perm:[2,3,0,1] row_mask:0xf bank_mask:0xf bound_ctrl:1
	v_add_f32_dpp v30, v31, v31 quad_perm:[2,3,0,1] row_mask:0xf bank_mask:0xf bound_ctrl:1
	v_pk_fma_f32 v[40:41], v[38:39], v[44:45], v[40:41] op_sel_hi:[0,1,1]
	v_add_f32_dpp v97, v96, v96 row_half_mirror row_mask:0xf bank_mask:0xf bound_ctrl:1
	v_add_f32_dpp v31, v30, v30 row_half_mirror row_mask:0xf bank_mask:0xf bound_ctrl:1
	v_pk_fma_f32 v[42:43], v[38:39], v[46:47], v[42:43] op_sel_hi:[0,1,1]
	v_add_f32_dpp v90, v97, v97 row_mirror row_mask:0xf bank_mask:0xf bound_ctrl:1
	v_add_f32_dpp v30, v31, v31 row_mirror row_mask:0xf bank_mask:0xf bound_ctrl:1
	ds_write_b32 v234, v30 offset:43136
	ds_read_b128 v[28:31], v232 offset:6144
	v_pk_fma_f32 v[20:21], v[90:91], v[60:61], v[40:41] op_sel_hi:[0,1,1] neg_lo:[1,0,0] neg_hi:[1,0,0]
	v_pk_fma_f32 v[22:23], v[90:91], v[62:63], v[42:43] op_sel_hi:[0,1,1] neg_lo:[1,0,0] neg_hi:[1,0,0]
	ds_read_b128 v[40:43], v232 offset:6720
	ds_read_b128 v[60:63], v232 offset:7232
	ds_read_b128 v[44:47], v232 offset:6976
	ds_read_b128 v[94:97], v232 offset:7744
	ds_read_b32 v38, v233 offset:8000
	s_waitcnt lgkmcnt(7)
	v_pk_mul_f32 v[32:33], v[20:21], v[32:33]
	v_pk_mul_f32 v[64:65], v[20:21], v[64:65]
	v_pk_fma_f32 v[32:33], v[22:23], v[34:35], v[32:33]
	v_pk_fma_f32 v[64:65], v[22:23], v[66:67], v[64:65]
	v_add_f32_e32 v34, v32, v33
	v_add_f32_e32 v66, v64, v65
	v_pk_fma_f32 v[12:13], v[20:21], v[12:13], v[20:21] neg_lo:[1,0,0] neg_hi:[1,0,0]
	v_add_f32_dpp v35, v34, v34 quad_perm:[1,0,3,2] row_mask:0xf bank_mask:0xf bound_ctrl:1
	v_add_f32_dpp v67, v66, v66 quad_perm:[1,0,3,2] row_mask:0xf bank_mask:0xf bound_ctrl:1
	v_pk_fma_f32 v[14:15], v[22:23], v[14:15], v[22:23] neg_lo:[1,0,0] neg_hi:[1,0,0]
	v_add_f32_dpp v34, v35, v35 quad_perm:[2,3,0,1] row_mask:0xf bank_mask:0xf bound_ctrl:1
	v_add_f32_dpp v66, v67, v67 quad_perm:[2,3,0,1] row_mask:0xf bank_mask:0xf bound_ctrl:1
	v_pk_fma_f32 v[12:13], v[36:37], v[16:17], v[12:13] op_sel_hi:[0,1,1]
	v_add_f32_dpp v35, v34, v34 row_half_mirror row_mask:0xf bank_mask:0xf bound_ctrl:1
	v_add_f32_dpp v67, v66, v66 row_half_mirror row_mask:0xf bank_mask:0xf bound_ctrl:1
	v_pk_fma_f32 v[14:15], v[36:37], v[18:19], v[14:15] op_sel_hi:[0,1,1]
	v_add_f32_dpp v90, v35, v35 row_mirror row_mask:0xf bank_mask:0xf bound_ctrl:1
	v_add_f32_dpp v66, v67, v67 row_mirror row_mask:0xf bank_mask:0xf bound_ctrl:1
	ds_write_b32 v234, v66 offset:43200
	ds_read_b128 v[64:67], v232 offset:7488
	v_pk_fma_f32 v[20:21], v[90:91], v[24:25], v[12:13] op_sel_hi:[0,1,1] neg_lo:[1,0,0] neg_hi:[1,0,0]
	v_pk_fma_f32 v[22:23], v[90:91], v[26:27], v[14:15] op_sel_hi:[0,1,1] neg_lo:[1,0,0] neg_hi:[1,0,0]
	ds_read_b128 v[12:15], v232 offset:8064
	ds_read_b128 v[24:27], v232 offset:8576
	ds_read_b128 v[16:19], v232 offset:8320
	ds_read_b128 v[32:35], v232 offset:9088
	ds_read_b32 v36, v233 offset:9344
	s_waitcnt lgkmcnt(7)
	v_pk_mul_f32 v[94:95], v[20:21], v[94:95]
	v_pk_mul_f32 v[28:29], v[20:21], v[28:29]
	v_pk_fma_f32 v[94:95], v[22:23], v[96:97], v[94:95]
	v_pk_fma_f32 v[28:29], v[22:23], v[30:31], v[28:29]
	v_add_f32_e32 v96, v94, v95
	v_add_f32_e32 v30, v28, v29
	v_pk_fma_f32 v[40:41], v[20:21], v[40:41], v[20:21] neg_lo:[1,0,0] neg_hi:[1,0,0]
	v_add_f32_dpp v97, v96, v96 quad_perm:[1,0,3,2] row_mask:0xf bank_mask:0xf bound_ctrl:1
	v_add_f32_dpp v31, v30, v30 quad_perm:[1,0,3,2] row_mask:0xf bank_mask:0xf bound_ctrl:1
	v_pk_fma_f32 v[42:43], v[22:23], v[42:43], v[22:23] neg_lo:[1,0,0] neg_hi:[1,0,0]
	v_add_f32_dpp v96, v97, v97 quad_perm:[2,3,0,1] row_mask:0xf bank_mask:0xf bound_ctrl:1
	v_add_f32_dpp v30, v31, v31 quad_perm:[2,3,0,1] row_mask:0xf bank_mask:0xf bound_ctrl:1
	v_pk_fma_f32 v[40:41], v[38:39], v[44:45], v[40:41] op_sel_hi:[0,1,1]
	v_add_f32_dpp v97, v96, v96 row_half_mirror row_mask:0xf bank_mask:0xf bound_ctrl:1
	v_add_f32_dpp v31, v30, v30 row_half_mirror row_mask:0xf bank_mask:0xf bound_ctrl:1
	v_pk_fma_f32 v[42:43], v[38:39], v[46:47], v[42:43] op_sel_hi:[0,1,1]
	v_add_f32_dpp v90, v97, v97 row_mirror row_mask:0xf bank_mask:0xf bound_ctrl:1
	v_add_f32_dpp v30, v31, v31 row_mirror row_mask:0xf bank_mask:0xf bound_ctrl:1
	ds_write_b32 v234, v30 offset:43264
	ds_read_b128 v[28:31], v232 offset:8832
	v_pk_fma_f32 v[20:21], v[90:91], v[60:61], v[40:41] op_sel_hi:[0,1,1] neg_lo:[1,0,0] neg_hi:[1,0,0]
	v_pk_fma_f32 v[22:23], v[90:91], v[62:63], v[42:43] op_sel_hi:[0,1,1] neg_lo:[1,0,0] neg_hi:[1,0,0]
	ds_read_b128 v[40:43], v232 offset:9408
	ds_read_b128 v[60:63], v232 offset:9920
	ds_read_b128 v[44:47], v232 offset:9664
	ds_read_b128 v[94:97], v232 offset:10432
	ds_read_b32 v38, v233 offset:10688
	s_waitcnt lgkmcnt(7)
; #define DPP_ADD(v, ctrl) ((v) + __builtin_bit_cast(float, __builtin_amdgcn_update_dpp(0, __builtin_bit_cast(int, (v)), (ctrl), 0xf, 0xf, true)))
; __device__ __forceinline__ void rwkv_scan_unit(const Params& p, int unit, char* smem) {
;     ...
;         for (int u = 0; u < SCH; ++u) {
;             f32x4 ne = e4, nkd = kd4, nka = ka4, nr = r4, nkk = kk4; float nv = vv;
;             if (u + 1 < SCH) { const char* q = lb + (u + 1) * STEPB;
;                 ne = *(const f32x4*)(q); nkd = *(const f32x4*)(q + 256); nka = *(const f32x4*)(q + 512); nr = *(const f32x4*)(q + 768); nkk = *(const f32x4*)(q + 1024);
;                 nv = *(const float*)(vb + (u + 1) * STEPB); }
;             const f32x2 v2 = {vv, vv}, c2 = {c, c};
;             const f32x2 tA = __builtin_elementwise_fma(v2, (f32x2){kd4[0], kd4[1]}, __builtin_elementwise_fma(-sA, (f32x2){e4[0], e4[1]}, sA));
;             const f32x2 tB = __builtin_elementwise_fma(v2, (f32x2){kd4[2], kd4[3]}, __builtin_elementwise_fma(-sB, (f32x2){e4[2], e4[3]}, sB));
;             sA = __builtin_elementwise_fma(-c2, (f32x2){ka4[0], ka4[1]}, tA);
;             sB = __builtin_elementwise_fma(-c2, (f32x2){ka4[2], ka4[3]}, tB);
;             const f32x2 yv = __builtin_elementwise_fma(sB, (f32x2){r4[2], r4[3]}, sA * (f32x2){r4[0], r4[1]});
;             float y = yv[0] + yv[1];
;             if (u + 1 < SCH) {
;                 const f32x2 cv = __builtin_elementwise_fma(sB, (f32x2){nkk[2], nkk[3]}, sA * (f32x2){nkk[0], nkk[1]});
;                 float cn = cv[0] + cv[1];
;                 cn = DPP_ADD(cn, 0xB1);  y = DPP_ADD(y, 0xB1);
;                 cn = DPP_ADD(cn, 0x4E);  y = DPP_ADD(y, 0x4E);
;                 cn = DPP_ADD(cn, 0x141); y = DPP_ADD(y, 0x141);
;                 cn = DPP_ADD(cn, 0x140); y = DPP_ADD(y, 0x140);
;                 c = cn;
;             } else y = red16(y);
;             if (ks == 0) yl[u * 16] = y;
;             e4 = ne; kd4 = nkd; ka4 = nka; r4 = nr; kk4 = nkk; vv = nv;
	v_pk_mul_f32 v[32:33], v[20:21], v[32:33]
	v_pk_mul_f32 v[64:65], v[20:21], v[64:65]
	v_pk_fma_f32 v[32:33], v[22:23], v[34:35], v[32:33]
	v_pk_fma_f32 v[64:65], v[22:23], v[66:67], v[64:65]
	v_add_f32_e32 v34, v32, v33
	v_add_f32_e32 v66, v64, v65
	v_pk_fma_f32 v[12:13], v[20:21], v[12:13], v[20:21] neg_lo:[1,0,0] neg_hi:[1,0,0]
	v_add_f32_dpp v35, v34, v34 quad_perm:[1,0,3,2] row_mask:0xf bank_mask:0xf bound_ctrl:1
	v_add_f32_dpp v67, v66, v66 quad_perm:[1,0,3,2] row_mask:0xf bank_mask:0xf bound_ctrl:1
	v_pk_fma_f32 v[14:15], v[22:23], v[14:15], v[22:23] neg_lo:[1,0,0] neg_hi:[1,0,0]
	v_add_f32_dpp v34, v35, v35 quad_perm:[2,3,0,1] row_mask:0xf bank_mask:0xf bound_ctrl:1
	v_add_f32_dpp v66, v67, v67 quad_perm:[2,3,0,1] row_mask:0xf bank_mask:0xf bound_ctrl:1
	v_pk_fma_f32 v[12:13], v[36:37], v[16:17], v[12:13] op_sel_hi:[0,1,1]
	v_add_f32_dpp v35, v34, v34 row_half_mirror row_mask:0xf bank_mask:0xf bound_ctrl:1
	v_add_f32_dpp v67, v66, v66 row_half_mirror row_mask:0xf bank_mask:0xf bound_ctrl:1
	v_pk_fma_f32 v[14:15], v[36:37], v[18:19], v[14:15] op_sel_hi:[0,1,1]
	v_add_f32_dpp v90, v35, v35 row_mirror row_mask:0xf bank_mask:0xf bound_ctrl:1
	v_add_f32_dpp v66, v67, v67 row_mirror row_mask:0xf bank_mask:0xf bound_ctrl:1
	ds_write_b32 v234, v66 offset:43328
	ds_read_b128 v[64:67], v232 offset:10176
	v_pk_fma_f32 v[20:21], v[90:91], v[24:25], v[12:13] op_sel_hi:[0,1,1] neg_lo:[1,0,0] neg_hi:[1,0,0]
	v_pk_fma_f32 v[22:23], v[90:91], v[26:27], v[14:15] op_sel_hi:[0,1,1] neg_lo:[1,0,0] neg_hi:[1,0,0]
	ds_read_b128 v[12:15], v232 offset:10752
	ds_read_b128 v[24:27], v232 offset:11264
	ds_read_b128 v[16:19], v232 offset:11008
	ds_read_b128 v[32:35], v232 offset:11776
	ds_read_b32 v36, v233 offset:12032
	s_waitcnt lgkmcnt(7)
	v_pk_mul_f32 v[94:95], v[20:21], v[94:95]
	v_pk_mul_f32 v[28:29], v[20:21], v[28:29]
	v_pk_fma_f32 v[94:95], v[22:23], v[96:97], v[94:95]
	v_pk_fma_f32 v[28:29], v[22:23], v[30:31], v[28:29]
	v_add_f32_e32 v96, v94, v95
	v_add_f32_e32 v30, v28, v29
	v_pk_fma_f32 v[40:41], v[20:21], v[40:41], v[20:21] neg_lo:[1,0,0] neg_hi:[1,0,0]
	v_add_f32_dpp v97, v96, v96 quad_perm:[1,0,3,2] row_mask:0xf bank_mask:0xf bound_ctrl:1
	v_add_f32_dpp v31, v30, v30 quad_perm:[1,0,3,2] row_mask:0xf bank_mask:0xf bound_ctrl:1
	v_pk_fma_f32 v[42:43], v[22:23], v[42:43], v[22:23] neg_lo:[1,0,0] neg_hi:[1,0,0]
	v_add_f32_dpp v96, v97, v97 quad_perm:[2,3,0,1] row_mask:0xf bank_mask:0xf bound_ctrl:1
	v_add_f32_dpp v30, v31, v31 quad_perm:[2,3,0,1] row_mask:0xf bank_mask:0xf bound_ctrl:1
	v_pk_fma_f32 v[40:41], v[38:39], v[44:45], v[40:41] op_sel_hi:[0,1,1]
	v_add_f32_dpp v97, v96, v96 row_half_mirror row_mask:0xf bank_mask:0xf bound_ctrl:1
	v_add_f32_dpp v31, v30, v30 row_half_mirror row_mask:0xf bank_mask:0xf bound_ctrl:1
	v_pk_fma_f32 v[42:43], v[38:39], v[46:47], v[42:43] op_sel_hi:[0,1,1]
	v_add_f32_dpp v90, v97, v97 row_mirror row_mask:0xf bank_mask:0xf bound_ctrl:1
	v_add_f32_dpp v30, v31, v31 row_mirror row_mask:0xf bank_mask:0xf bound_ctrl:1
	ds_write_b32 v234, v30 offset:43392
	ds_read_b128 v[28:31], v232 offset:11520
	v_pk_fma_f32 v[20:21], v[90:91], v[60:61], v[40:41] op_sel_hi:[0,1,1] neg_lo:[1,0,0] neg_hi:[1,0,0]
	v_pk_fma_f32 v[22:23], v[90:91], v[62:63], v[42:43] op_sel_hi:[0,1,1] neg_lo:[1,0,0] neg_hi:[1,0,0]
	ds_read_b128 v[40:43], v232 offset:12096
	ds_read_b128 v[60:63], v232 offset:12608
	ds_read_b128 v[44:47], v232 offset:12352
	ds_read_b128 v[94:97], v232 offset:13120
	ds_read_b32 v38, v233 offset:13376
	s_waitcnt lgkmcnt(7)
	v_pk_mul_f32 v[32:33], v[20:21], v[32:33]
	v_pk_mul_f32 v[64:65], v[20:21], v[64:65]
	v_pk_fma_f32 v[32:33], v[22:23], v[34:35], v[32:33]
	v_pk_fma_f32 v[64:65], v[22:23], v[66:67], v[64:65]
	v_add_f32_e32 v34, v32, v33
	v_add_f32_e32 v66, v64, v65
	v_pk_fma_f32 v[12:13], v[20:21], v[12:13], v[20:21] neg_lo:[1,0,0] neg_hi:[1,0,0]
	v_add_f32_dpp v35, v34, v34 quad_perm:[1,0,3,2] row_mask:0xf bank_mask:0xf bound_ctrl:1
	v_add_f32_dpp v67, v66, v66 quad_perm:[1,0,3,2] row_mask:0xf bank_mask:0xf bound_ctrl:1
	v_pk_fma_f32 v[14:15], v[22:23], v[14:15], v[22:23] neg_lo:[1,0,0] neg_hi:[1,0,0]
	v_add_f32_dpp v34, v35, v35 quad_perm:[2,3,0,1] row_mask:0xf bank_mask:0xf bound_ctrl:1
	v_add_f32_dpp v66, v67, v67 quad_perm:[2,3,0,1] row_mask:0xf bank_mask:0xf bound_ctrl:1
	v_pk_fma_f32 v[12:13], v[36:37], v[16:17], v[12:13] op_sel_hi:[0,1,1]
	v_add_f32_dpp v35, v34, v34 row_half_mirror row_mask:0xf bank_mask:0xf bound_ctrl:1
	v_add_f32_dpp v67, v66, v66 row_half_mirror row_mask:0xf bank_mask:0xf bound_ctrl:1
	v_pk_fma_f32 v[14:15], v[36:37], v[18:19], v[14:15] op_sel_hi:[0,1,1]
	v_add_f32_dpp v90, v35, v35 row_mirror row_mask:0xf bank_mask:0xf bound_ctrl:1
	v_add_f32_dpp v66, v67, v67 row_mirror row_mask:0xf bank_mask:0xf bound_ctrl:1
	ds_write_b32 v234, v66 offset:43456
	ds_read_b128 v[64:67], v232 offset:12864
	v_pk_fma_f32 v[20:21], v[90:91], v[24:25], v[12:13] op_sel_hi:[0,1,1] neg_lo:[1,0,0] neg_hi:[1,0,0]
	v_pk_fma_f32 v[22:23], v[90:91], v[26:27], v[14:15] op_sel_hi:[0,1,1] neg_lo:[1,0,0] neg_hi:[1,0,0]
	ds_read_b128 v[12:15], v232 offset:13440
	ds_read_b128 v[24:27], v232 offset:13952
	ds_read_b128 v[16:19], v232 offset:13696
	ds_read_b128 v[32:35], v232 offset:14464
	ds_read_b32 v36, v233 offset:14720
	s_waitcnt lgkmcnt(7)
; #define DPP_ADD(v, ctrl) ((v) + __builtin_bit_cast(float, __builtin_amdgcn_update_dpp(0, __builtin_bit_cast(int, (v)), (ctrl), 0xf, 0xf, true)))
; __device__ __forceinline__ void rwkv_scan_unit(const Params& p, int unit, char* smem) {
;     ...
;         for (int u = 0; u < SCH; ++u) {
;             f32x4 ne = e4, nkd = kd4, nka = ka4, nr = r4, nkk = kk4; float nv = vv;
;             if (u + 1 < SCH) { const char* q = lb + (u + 1) * STEPB;
;                 ne = *(const f32x4*)(q); nkd = *(const f32x4*)(q + 256); nka = *(const f32x4*)(q + 512); nr = *(const f32x4*)(q + 768); nkk = *(const f32x4*)(q + 1024);
;                 nv = *(const float*)(vb + (u + 1) * STEPB); }
;             const f32x2 v2 = {vv, vv}, c2 = {c, c};
;             const f32x2 tA = __builtin_elementwise_fma(v2, (f32x2){kd4[0], kd4[1]}, __builtin_elementwise_fma(-sA, (f32x2){e4[0], e4[1]}, sA));
;             const f32x2 tB = __builtin_elementwise_fma(v2, (f32x2){kd4[2], kd4[3]}, __builtin_elementwise_fma(-sB, (f32x2){e4[2], e4[3]}, sB));
;             sA = __builtin_elementwise_fma(-c2, (f32x2){ka4[0], ka4[1]}, tA);
;             sB = __builtin_elementwise_fma(-c2, (f32x2){ka4[2], ka4[3]}, tB);
;             const f32x2 yv = __builtin_elementwise_fma(sB, (f32x2){r4[2], r4[3]}, sA * (f32x2){r4[0], r4[1]});
;             float y = yv[0] + yv[1];
;             if (u + 1 < SCH) {
;                 const f32x2 cv = __builtin_elementwise_fma(sB, (f32x2){nkk[2], nkk[3]}, sA * (f32x2){nkk[0], nkk[1]});
;                 float cn = cv[0] + cv[1];
;                 cn = DPP_ADD(cn, 0xB1);  y = DPP_ADD(y, 0xB1);
;                 cn = DPP_ADD(cn, 0x4E);  y = DPP_ADD(y, 0x4E);
;                 cn = DPP_ADD(cn, 0x141); y = DPP_ADD(y, 0x141);
;                 cn = DPP_ADD(cn, 0x140); y = DPP_ADD(y, 0x140);
;                 c = cn;
;             } else y = red16(y);
;             if (ks == 0) yl[u * 16] = y;
;             e4 = ne; kd4 = nkd; ka4 = nka; r4 = nr; kk4 = nkk; vv = nv;
	v_pk_mul_f32 v[94:95], v[20:21], v[94:95]
	v_pk_mul_f32 v[28:29], v[20:21], v[28:29]
	v_pk_fma_f32 v[94:95], v[22:23], v[96:97], v[94:95]
	v_pk_fma_f32 v[28:29], v[22:23], v[30:31], v[28:29]
	v_add_f32_e32 v96, v94, v95
	v_add_f32_e32 v30, v28, v29
	v_pk_fma_f32 v[40:41], v[20:21], v[40:41], v[20:21] neg_lo:[1,0,0] neg_hi:[1,0,0]
	v_add_f32_dpp v97, v96, v96 quad_perm:[1,0,3,2] row_mask:0xf bank_mask:0xf bound_ctrl:1
	v_add_f32_dpp v31, v30, v30 quad_perm:[1,0,3,2] row_mask:0xf bank_mask:0xf bound_ctrl:1
	v_pk_fma_f32 v[42:43], v[22:23], v[42:43], v[22:23] neg_lo:[1,0,0] neg_hi:[1,0,0]
	v_add_f32_dpp v96, v97, v97 quad_perm:[2,3,0,1] row_mask:0xf bank_mask:0xf bound_ctrl:1
	v_add_f32_dpp v30, v31, v31 quad_perm:[2,3,0,1] row_mask:0xf bank_mask:0xf bound_ctrl:1
	v_pk_fma_f32 v[40:41], v[38:39], v[44:45], v[40:41] op_sel_hi:[0,1,1]
	v_add_f32_dpp v97, v96, v96 row_half_mirror row_mask:0xf bank_mask:0xf bound_ctrl:1
	v_add_f32_dpp v31, v30, v30 row_half_mirror row_mask:0xf bank_mask:0xf bound_ctrl:1
	v_pk_fma_f32 v[42:43], v[38:39], v[46:47], v[42:43] op_sel_hi:[0,1,1]
	v_add_f32_dpp v90, v97, v97 row_mirror row_mask:0xf bank_mask:0xf bound_ctrl:1
	v_add_f32_dpp v30, v31, v31 row_mirror row_mask:0xf bank_mask:0xf bound_ctrl:1
	ds_write_b32 v234, v30 offset:43520
	ds_read_b128 v[28:31], v232 offset:14208
	v_pk_fma_f32 v[20:21], v[90:91], v[60:61], v[40:41] op_sel_hi:[0,1,1] neg_lo:[1,0,0] neg_hi:[1,0,0]
	v_pk_fma_f32 v[22:23], v[90:91], v[62:63], v[42:43] op_sel_hi:[0,1,1] neg_lo:[1,0,0] neg_hi:[1,0,0]
	ds_read_b128 v[40:43], v232 offset:14784
	ds_read_b128 v[60:63], v232 offset:15296
	ds_read_b128 v[44:47], v232 offset:15040
	ds_read_b128 v[94:97], v232 offset:15808
	ds_read_b32 v38, v233 offset:16064
	s_waitcnt lgkmcnt(7)
	v_pk_mul_f32 v[32:33], v[20:21], v[32:33]
	v_pk_mul_f32 v[64:65], v[20:21], v[64:65]
	v_pk_fma_f32 v[32:33], v[22:23], v[34:35], v[32:33]
	v_pk_fma_f32 v[64:65], v[22:23], v[66:67], v[64:65]
	v_add_f32_e32 v34, v32, v33
	v_add_f32_e32 v66, v64, v65
	v_pk_fma_f32 v[12:13], v[20:21], v[12:13], v[20:21] neg_lo:[1,0,0] neg_hi:[1,0,0]
	v_add_f32_dpp v35, v34, v34 quad_perm:[1,0,3,2] row_mask:0xf bank_mask:0xf bound_ctrl:1
	v_add_f32_dpp v67, v66, v66 quad_perm:[1,0,3,2] row_mask:0xf bank_mask:0xf bound_ctrl:1
	v_pk_fma_f32 v[14:15], v[22:23], v[14:15], v[22:23] neg_lo:[1,0,0] neg_hi:[1,0,0]
	v_add_f32_dpp v34, v35, v35 quad_perm:[2,3,0,1] row_mask:0xf bank_mask:0xf bound_ctrl:1
	v_add_f32_dpp v66, v67, v67 quad_perm:[2,3,0,1] row_mask:0xf bank_mask:0xf bound_ctrl:1
	v_pk_fma_f32 v[12:13], v[36:37], v[16:17], v[12:13] op_sel_hi:[0,1,1]
	v_add_f32_dpp v35, v34, v34 row_half_mirror row_mask:0xf bank_mask:0xf bound_ctrl:1
	v_add_f32_dpp v67, v66, v66 row_half_mirror row_mask:0xf bank_mask:0xf bound_ctrl:1
	v_pk_fma_f32 v[14:15], v[36:37], v[18:19], v[14:15] op_sel_hi:[0,1,1]
	v_add_f32_dpp v90, v35, v35 row_mirror row_mask:0xf bank_mask:0xf bound_ctrl:1
	v_add_f32_dpp v66, v67, v67 row_mirror row_mask:0xf bank_mask:0xf bound_ctrl:1
	ds_write_b32 v234, v66 offset:43584
	ds_read_b128 v[64:67], v232 offset:15552
	v_pk_fma_f32 v[20:21], v[90:91], v[24:25], v[12:13] op_sel_hi:[0,1,1] neg_lo:[1,0,0] neg_hi:[1,0,0]
	v_pk_fma_f32 v[22:23], v[90:91], v[26:27], v[14:15] op_sel_hi:[0,1,1] neg_lo:[1,0,0] neg_hi:[1,0,0]
	ds_read_b128 v[12:15], v232 offset:16128
	ds_read_b128 v[24:27], v232 offset:16640
	ds_read_b128 v[16:19], v232 offset:16384
	ds_read_b128 v[32:35], v232 offset:17152
	ds_read_b32 v36, v233 offset:17408
	s_waitcnt lgkmcnt(7)
	v_pk_mul_f32 v[94:95], v[20:21], v[94:95]
	v_pk_mul_f32 v[28:29], v[20:21], v[28:29]
	v_pk_fma_f32 v[94:95], v[22:23], v[96:97], v[94:95]
	v_pk_fma_f32 v[28:29], v[22:23], v[30:31], v[28:29]
	v_add_f32_e32 v96, v94, v95
	v_add_f32_e32 v30, v28, v29
	v_pk_fma_f32 v[40:41], v[20:21], v[40:41], v[20:21] neg_lo:[1,0,0] neg_hi:[1,0,0]
	v_add_f32_dpp v97, v96, v96 quad_perm:[1,0,3,2] row_mask:0xf bank_mask:0xf bound_ctrl:1
	v_add_f32_dpp v31, v30, v30 quad_perm:[1,0,3,2] row_mask:0xf bank_mask:0xf bound_ctrl:1
	v_pk_fma_f32 v[42:43], v[22:23], v[42:43], v[22:23] neg_lo:[1,0,0] neg_hi:[1,0,0]
	v_add_f32_dpp v96, v97, v97 quad_perm:[2,3,0,1] row_mask:0xf bank_mask:0xf bound_ctrl:1
	v_add_f32_dpp v30, v31, v31 quad_perm:[2,3,0,1] row_mask:0xf bank_mask:0xf bound_ctrl:1
	v_pk_fma_f32 v[40:41], v[38:39], v[44:45], v[40:41] op_sel_hi:[0,1,1]
	v_add_f32_dpp v97, v96, v96 row_half_mirror row_mask:0xf bank_mask:0xf bound_ctrl:1
	v_add_f32_dpp v31, v30, v30 row_half_mirror row_mask:0xf bank_mask:0xf bound_ctrl:1
	v_pk_fma_f32 v[42:43], v[38:39], v[46:47], v[42:43] op_sel_hi:[0,1,1]
	v_add_f32_dpp v90, v97, v97 row_mirror row_mask:0xf bank_mask:0xf bound_ctrl:1
	v_add_f32_dpp v30, v31, v31 row_mirror row_mask:0xf bank_mask:0xf bound_ctrl:1
	ds_write_b32 v234, v30 offset:43648
	ds_read_b128 v[28:31], v232 offset:16896
	v_pk_fma_f32 v[20:21], v[90:91], v[60:61], v[40:41] op_sel_hi:[0,1,1] neg_lo:[1,0,0] neg_hi:[1,0,0]
	v_pk_fma_f32 v[22:23], v[90:91], v[62:63], v[42:43] op_sel_hi:[0,1,1] neg_lo:[1,0,0] neg_hi:[1,0,0]
	ds_read_b128 v[40:43], v232 offset:17472
	ds_read_b128 v[60:63], v232 offset:17984
	ds_read_b128 v[44:47], v232 offset:17728
	ds_read_b128 v[94:97], v232 offset:18496
	ds_read_b32 v38, v233 offset:18752
	s_waitcnt lgkmcnt(7)
; #define DPP_ADD(v, ctrl) ((v) + __builtin_bit_cast(float, __builtin_amdgcn_update_dpp(0, __builtin_bit_cast(int, (v)), (ctrl), 0xf, 0xf, true)))
; __device__ __forceinline__ void rwkv_scan_unit(const Params& p, int unit, char* smem) {
;     ...
;         for (int u = 0; u < SCH; ++u) {
;             f32x4 ne = e4, nkd = kd4, nka = ka4, nr = r4, nkk = kk4; float nv = vv;
;             if (u + 1 < SCH) { const char* q = lb + (u + 1) * STEPB;
;                 ne = *(const f32x4*)(q); nkd = *(const f32x4*)(q + 256); nka = *(const f32x4*)(q + 512); nr = *(const f32x4*)(q + 768); nkk = *(const f32x4*)(q + 1024);
;                 nv = *(const float*)(vb + (u + 1) * STEPB); }
;             const f32x2 v2 = {vv, vv}, c2 = {c, c};
;             const f32x2 tA = __builtin_elementwise_fma(v2, (f32x2){kd4[0], kd4[1]}, __builtin_elementwise_fma(-sA, (f32x2){e4[0], e4[1]}, sA));
;             const f32x2 tB = __builtin_elementwise_fma(v2, (f32x2){kd4[2], kd4[3]}, __builtin_elementwise_fma(-sB, (f32x2){e4[2], e4[3]}, sB));
;             sA = __builtin_elementwise_fma(-c2, (f32x2){ka4[0], ka4[1]}, tA);
;             sB = __builtin_elementwise_fma(-c2, (f32x2){ka4[2], ka4[3]}, tB);
;             const f32x2 yv = __builtin_elementwise_fma(sB, (f32x2){r4[2], r4[3]}, sA * (f32x2){r4[0], r4[1]});
;             float y = yv[0] + yv[1];
;             if (u + 1 < SCH) {
;                 const f32x2 cv = __builtin_elementwise_fma(sB, (f32x2){nkk[2], nkk[3]}, sA * (f32x2){nkk[0], nkk[1]});
;                 float cn = cv[0] + cv[1];
;                 cn = DPP_ADD(cn, 0xB1);  y = DPP_ADD(y, 0xB1);
;                 cn = DPP_ADD(cn, 0x4E);  y = DPP_ADD(y, 0x4E);
;                 cn = DPP_ADD(cn, 0x141); y = DPP_ADD(y, 0x141);
;                 cn = DPP_ADD(cn, 0x140); y = DPP_ADD(y, 0x140);
;                 c = cn;
;             } else y = red16(y);
;             if (ks == 0) yl[u * 16] = y;
;             e4 = ne; kd4 = nkd; ka4 = nka; r4 = nr; kk4 = nkk; vv = nv;
	v_pk_mul_f32 v[32:33], v[20:21], v[32:33]
	v_pk_mul_f32 v[64:65], v[20:21], v[64:65]
	v_pk_fma_f32 v[32:33], v[22:23], v[34:35], v[32:33]
	v_pk_fma_f32 v[64:65], v[22:23], v[66:67], v[64:65]
	v_add_f32_e32 v34, v32, v33
	v_add_f32_e32 v66, v64, v65
	v_pk_fma_f32 v[12:13], v[20:21], v[12:13], v[20:21] neg_lo:[1,0,0] neg_hi:[1,0,0]
	v_add_f32_dpp v35, v34, v34 quad_perm:[1,0,3,2] row_mask:0xf bank_mask:0xf bound_ctrl:1
	v_add_f32_dpp v67, v66, v66 quad_perm:[1,0,3,2] row_mask:0xf bank_mask:0xf bound_ctrl:1
	v_pk_fma_f32 v[14:15], v[22:23], v[14:15], v[22:23] neg_lo:[1,0,0] neg_hi:[1,0,0]
	v_add_f32_dpp v34, v35, v35 quad_perm:[2,3,0,1] row_mask:0xf bank_mask:0xf bound_ctrl:1
	v_add_f32_dpp v66, v67, v67 quad_perm:[2,3,0,1] row_mask:0xf bank_mask:0xf bound_ctrl:1
	v_pk_fma_f32 v[12:13], v[36:37], v[16:17], v[12:13] op_sel_hi:[0,1,1]
	v_add_f32_dpp v35, v34, v34 row_half_mirror row_mask:0xf bank_mask:0xf bound_ctrl:1
	v_add_f32_dpp v67, v66, v66 row_half_mirror row_mask:0xf bank_mask:0xf bound_ctrl:1
	v_pk_fma_f32 v[14:15], v[36:37], v[18:19], v[14:15] op_sel_hi:[0,1,1]
	v_add_f32_dpp v90, v35, v35 row_mirror row_mask:0xf bank_mask:0xf bound_ctrl:1
	v_add_f32_dpp v66, v67, v67 row_mirror row_mask:0xf bank_mask:0xf bound_ctrl:1
	ds_write_b32 v234, v66 offset:43712
	ds_read_b128 v[64:67], v232 offset:18240
	v_pk_fma_f32 v[20:21], v[90:91], v[24:25], v[12:13] op_sel_hi:[0,1,1] neg_lo:[1,0,0] neg_hi:[1,0,0]
	v_pk_fma_f32 v[22:23], v[90:91], v[26:27], v[14:15] op_sel_hi:[0,1,1] neg_lo:[1,0,0] neg_hi:[1,0,0]
	ds_read_b128 v[12:15], v232 offset:18816
	ds_read_b128 v[24:27], v232 offset:19328
	ds_read_b128 v[16:19], v232 offset:19072
	ds_read_b128 v[32:35], v232 offset:19840
	ds_read_b32 v36, v233 offset:20096
	s_waitcnt lgkmcnt(7)
	v_pk_mul_f32 v[94:95], v[20:21], v[94:95]
	v_pk_mul_f32 v[28:29], v[20:21], v[28:29]
	v_pk_fma_f32 v[94:95], v[22:23], v[96:97], v[94:95]
	v_pk_fma_f32 v[28:29], v[22:23], v[30:31], v[28:29]
	v_add_f32_e32 v96, v94, v95
	v_add_f32_e32 v30, v28, v29
	v_pk_fma_f32 v[40:41], v[20:21], v[40:41], v[20:21] neg_lo:[1,0,0] neg_hi:[1,0,0]
	v_add_f32_dpp v97, v96, v96 quad_perm:[1,0,3,2] row_mask:0xf bank_mask:0xf bound_ctrl:1
	v_add_f32_dpp v31, v30, v30 quad_perm:[1,0,3,2] row_mask:0xf bank_mask:0xf bound_ctrl:1
	v_pk_fma_f32 v[42:43], v[22:23], v[42:43], v[22:23] neg_lo:[1,0,0] neg_hi:[1,0,0]
	v_add_f32_dpp v96, v97, v97 quad_perm:[2,3,0,1] row_mask:0xf bank_mask:0xf bound_ctrl:1
	v_add_f32_dpp v30, v31, v31 quad_perm:[2,3,0,1] row_mask:0xf bank_mask:0xf bound_ctrl:1
	v_pk_fma_f32 v[40:41], v[38:39], v[44:45], v[40:41] op_sel_hi:[0,1,1]
	v_add_f32_dpp v97, v96, v96 row_half_mirror row_mask:0xf bank_mask:0xf bound_ctrl:1
	v_add_f32_dpp v31, v30, v30 row_half_mirror row_mask:0xf bank_mask:0xf bound_ctrl:1
	v_pk_fma_f32 v[42:43], v[38:39], v[46:47], v[42:43] op_sel_hi:[0,1,1]
	v_add_f32_dpp v90, v97, v97 row_mirror row_mask:0xf bank_mask:0xf bound_ctrl:1
	v_add_f32_dpp v30, v31, v31 row_mirror row_mask:0xf bank_mask:0xf bound_ctrl:1
	ds_write_b32 v234, v30 offset:43776
	ds_read_b128 v[28:31], v232 offset:19584
	v_pk_fma_f32 v[20:21], v[90:91], v[60:61], v[40:41] op_sel_hi:[0,1,1] neg_lo:[1,0,0] neg_hi:[1,0,0]
	v_pk_fma_f32 v[22:23], v[90:91], v[62:63], v[42:43] op_sel_hi:[0,1,1] neg_lo:[1,0,0] neg_hi:[1,0,0]
	ds_read_b128 v[40:43], v232 offset:20160
	ds_read_b128 v[60:63], v232 offset:20672
	ds_read_b128 v[44:47], v232 offset:20416
	ds_read_b128 v[94:97], v232 offset:21184
	ds_read_b32 v38, v233 offset:21440
	s_waitcnt lgkmcnt(7)
	v_pk_mul_f32 v[32:33], v[20:21], v[32:33]
	v_pk_mul_f32 v[64:65], v[20:21], v[64:65]
	v_pk_fma_f32 v[32:33], v[22:23], v[34:35], v[32:33]
	v_pk_fma_f32 v[64:65], v[22:23], v[66:67], v[64:65]
	v_add_f32_e32 v34, v32, v33
	v_add_f32_e32 v66, v64, v65
	v_pk_fma_f32 v[12:13], v[20:21], v[12:13], v[20:21] neg_lo:[1,0,0] neg_hi:[1,0,0]
	v_add_f32_dpp v35, v34, v34 quad_perm:[1,0,3,2] row_mask:0xf bank_mask:0xf bound_ctrl:1
	v_add_f32_dpp v67, v66, v66 quad_perm:[1,0,3,2] row_mask:0xf bank_mask:0xf bound_ctrl:1
	v_pk_fma_f32 v[14:15], v[22:23], v[14:15], v[22:23] neg_lo:[1,0,0] neg_hi:[1,0,0]
	v_add_f32_dpp v34, v35, v35 quad_perm:[2,3,0,1] row_mask:0xf bank_mask:0xf bound_ctrl:1
	v_add_f32_dpp v66, v67, v67 quad_perm:[2,3,0,1] row_mask:0xf bank_mask:0xf bound_ctrl:1
	v_pk_fma_f32 v[12:13], v[36:37], v[16:17], v[12:13] op_sel_hi:[0,1,1]
	v_add_f32_dpp v35, v34, v34 row_half_mirror row_mask:0xf bank_mask:0xf bound_ctrl:1
	v_add_f32_dpp v67, v66, v66 row_half_mirror row_mask:0xf bank_mask:0xf bound_ctrl:1
	v_pk_fma_f32 v[14:15], v[36:37], v[18:19], v[14:15] op_sel_hi:[0,1,1]
	v_add_f32_dpp v90, v35, v35 row_mirror row_mask:0xf bank_mask:0xf bound_ctrl:1
	v_add_f32_dpp v66, v67, v67 row_mirror row_mask:0xf bank_mask:0xf bound_ctrl:1
	ds_write_b32 v234, v66 offset:43840
	ds_read_b128 v[64:67], v232 offset:20928
	v_pk_fma_f32 v[20:21], v[90:91], v[24:25], v[12:13] op_sel_hi:[0,1,1] neg_lo:[1,0,0] neg_hi:[1,0,0]
	v_pk_fma_f32 v[22:23], v[90:91], v[26:27], v[14:15] op_sel_hi:[0,1,1] neg_lo:[1,0,0] neg_hi:[1,0,0]
	s_waitcnt lgkmcnt(2)
; #define DPP_ADD(v, ctrl) ((v) + __builtin_bit_cast(float, __builtin_amdgcn_update_dpp(0, __builtin_bit_cast(int, (v)), (ctrl), 0xf, 0xf, true)))
; __device__ __forceinline__ void rwkv_scan_unit(const Params& p, int unit, char* smem) {
;     ...
;         for (int u = 0; u < SCH; ++u) {
;             f32x4 ne = e4, nkd = kd4, nka = ka4, nr = r4, nkk = kk4; float nv = vv;
;             if (u + 1 < SCH) { const char* q = lb + (u + 1) * STEPB;
;                 ne = *(const f32x4*)(q); nkd = *(const f32x4*)(q + 256); nka = *(const f32x4*)(q + 512); nr = *(const f32x4*)(q + 768); nkk = *(const f32x4*)(q + 1024);
;                 nv = *(const float*)(vb + (u + 1) * STEPB); }
;             const f32x2 v2 = {vv, vv}, c2 = {c, c};
;             const f32x2 tA = __builtin_elementwise_fma(v2, (f32x2){kd4[0], kd4[1]}, __builtin_elementwise_fma(-sA, (f32x2){e4[0], e4[1]}, sA));
;             const f32x2 tB = __builtin_elementwise_fma(v2, (f32x2){kd4[2], kd4[3]}, __builtin_elementwise_fma(-sB, (f32x2){e4[2], e4[3]}, sB));
;             sA = __builtin_elementwise_fma(-c2, (f32x2){ka4[0], ka4[1]}, tA);
;             sB = __builtin_elementwise_fma(-c2, (f32x2){ka4[2], ka4[3]}, tB);
;             const f32x2 yv = __builtin_elementwise_fma(sB, (f32x2){r4[2], r4[3]}, sA * (f32x2){r4[0], r4[1]});
;             float y = yv[0] + yv[1];
;             if (u + 1 < SCH) {
;                 const f32x2 cv = __builtin_elementwise_fma(sB, (f32x2){nkk[2], nkk[3]}, sA * (f32x2){nkk[0], nkk[1]});
;                 float cn = cv[0] + cv[1];
;                 cn = DPP_ADD(cn, 0xB1);  y = DPP_ADD(y, 0xB1);
;                 cn = DPP_ADD(cn, 0x4E);  y = DPP_ADD(y, 0x4E);
;                 cn = DPP_ADD(cn, 0x141); y = DPP_ADD(y, 0x141);
;                 cn = DPP_ADD(cn, 0x140); y = DPP_ADD(y, 0x140);
;                 c = cn;
;             } else y = red16(y);
;             if (ks == 0) yl[u * 16] = y;
;             e4 = ne; kd4 = nkd; ka4 = nka; r4 = nr; kk4 = nkk; vv = nv;
;         }
;         s0 = sA[0]; s1 = sA[1]; s2 = sB[0]; s3 = sB[1];
;         __builtin_amdgcn_sched_barrier(0);
;         if (ci + 1 < NCH) { SC_LSTORE(((ci + 1) & 1) * STG) }
;         __syncthreads();
;         {
;             const int u = tid >> 4, r = tid & 15;
;             Yb[((size_t)b * TT + step_tok(ci * SCH + u, d)) * 1024 + r] = f2bf(*((const float*)(smem + YOFF + (ci & 1) * 1024) + u * 16 + r));
;         }
	v_pk_mul_f32 v[94:95], v[20:21], v[94:95]
	v_pk_mul_f32 v[28:29], v[20:21], v[28:29]
	v_pk_fma_f32 v[94:95], v[22:23], v[96:97], v[94:95]
	v_pk_fma_f32 v[28:29], v[22:23], v[30:31], v[28:29]
	v_add_f32_e32 v96, v94, v95
	v_add_f32_e32 v30, v28, v29
	v_pk_fma_f32 v[40:41], v[20:21], v[40:41], v[20:21] neg_lo:[1,0,0] neg_hi:[1,0,0]
	v_add_f32_dpp v97, v96, v96 quad_perm:[1,0,3,2] row_mask:0xf bank_mask:0xf bound_ctrl:1
	v_add_f32_dpp v31, v30, v30 quad_perm:[1,0,3,2] row_mask:0xf bank_mask:0xf bound_ctrl:1
	v_pk_fma_f32 v[42:43], v[22:23], v[42:43], v[22:23] neg_lo:[1,0,0] neg_hi:[1,0,0]
	v_add_f32_dpp v96, v97, v97 quad_perm:[2,3,0,1] row_mask:0xf bank_mask:0xf bound_ctrl:1
	v_add_f32_dpp v30, v31, v31 quad_perm:[2,3,0,1] row_mask:0xf bank_mask:0xf bound_ctrl:1
	v_pk_fma_f32 v[40:41], v[38:39], v[44:45], v[40:41] op_sel_hi:[0,1,1]
	v_add_f32_dpp v97, v96, v96 row_half_mirror row_mask:0xf bank_mask:0xf bound_ctrl:1
	v_add_f32_dpp v31, v30, v30 row_half_mirror row_mask:0xf bank_mask:0xf bound_ctrl:1
	v_pk_fma_f32 v[42:43], v[38:39], v[46:47], v[42:43] op_sel_hi:[0,1,1]
	v_add_f32_dpp v90, v97, v97 row_mirror row_mask:0xf bank_mask:0xf bound_ctrl:1
	v_add_f32_dpp v30, v31, v31 row_mirror row_mask:0xf bank_mask:0xf bound_ctrl:1
	ds_write_b32 v234, v30 offset:43904
	v_pk_fma_f32 v[20:21], v[90:91], v[60:61], v[40:41] op_sel_hi:[0,1,1] neg_lo:[1,0,0] neg_hi:[1,0,0]
	v_pk_fma_f32 v[22:23], v[90:91], v[62:63], v[42:43] op_sel_hi:[0,1,1] neg_lo:[1,0,0] neg_hi:[1,0,0]
	s_waitcnt lgkmcnt(1)
	v_pk_mul_f32 v[64:65], v[20:21], v[64:65]
	v_pk_fma_f32 v[64:65], v[22:23], v[66:67], v[64:65]
	s_nop 0
	v_add_f32_e32 v66, v64, v65
	s_nop 1
	v_add_f32_dpp v67, v66, v66 quad_perm:[1,0,3,2] row_mask:0xf bank_mask:0xf bound_ctrl:1
	s_nop 1
	v_add_f32_dpp v66, v67, v67 quad_perm:[2,3,0,1] row_mask:0xf bank_mask:0xf bound_ctrl:1
	s_nop 1
	v_add_f32_dpp v67, v66, v66 row_half_mirror row_mask:0xf bank_mask:0xf bound_ctrl:1
	s_nop 1
	v_add_f32_dpp v66, v67, v67 row_mirror row_mask:0xf bank_mask:0xf bound_ctrl:1
	ds_write_b32 v234, v66 offset:43968
	s_waitcnt vmcnt(12)
	v_cvt_f32_f16_sdwa v13, v0 dst_sel:DWORD dst_unused:UNUSED_PAD src0_sel:WORD_1
	v_cvt_f32_f16_e32 v12, v0
	v_cvt_f32_f16_sdwa v15, v1 dst_sel:DWORD dst_unused:UNUSED_PAD src0_sel:WORD_1
	v_cvt_f32_f16_e32 v14, v1
	ds_write_b128 v241, v[12:15]
	v_cvt_f32_f16_sdwa v13, v2 dst_sel:DWORD dst_unused:UNUSED_PAD src0_sel:WORD_1
	v_cvt_f32_f16_e32 v12, v2
	v_cvt_f32_f16_sdwa v15, v3 dst_sel:DWORD dst_unused:UNUSED_PAD src0_sel:WORD_1
	v_cvt_f32_f16_e32 v14, v3
	ds_write_b128 v241, v[12:15] offset:16
	v_cvt_f32_f16_sdwa v13, v4 dst_sel:DWORD dst_unused:UNUSED_PAD src0_sel:WORD_1
	v_cvt_f32_f16_e32 v12, v4
	v_cvt_f32_f16_sdwa v15, v5 dst_sel:DWORD dst_unused:UNUSED_PAD src0_sel:WORD_1
	v_cvt_f32_f16_e32 v14, v5
	ds_write_b128 v242, v[12:15]
	v_cvt_f32_f16_sdwa v13, v6 dst_sel:DWORD dst_unused:UNUSED_PAD src0_sel:WORD_1
	v_cvt_f32_f16_e32 v12, v6
	v_cvt_f32_f16_sdwa v15, v7 dst_sel:DWORD dst_unused:UNUSED_PAD src0_sel:WORD_1
	v_cvt_f32_f16_e32 v14, v7
	ds_write_b128 v242, v[12:15] offset:16
	v_cvt_f32_f16_sdwa v13, v8 dst_sel:DWORD dst_unused:UNUSED_PAD src0_sel:WORD_1
	v_cvt_f32_f16_e32 v12, v8
	v_cvt_f32_f16_sdwa v15, v9 dst_sel:DWORD dst_unused:UNUSED_PAD src0_sel:WORD_1
	v_cvt_f32_f16_e32 v14, v9
	ds_write_b128 v243, v[12:15]
	v_cvt_f32_f16_sdwa v13, v10 dst_sel:DWORD dst_unused:UNUSED_PAD src0_sel:WORD_1
	v_cvt_f32_f16_e32 v12, v10
	v_cvt_f32_f16_sdwa v15, v11 dst_sel:DWORD dst_unused:UNUSED_PAD src0_sel:WORD_1
	v_cvt_f32_f16_e32 v14, v11
	ds_write_b128 v243, v[12:15] offset:16
.Lsc_p0_flush:
	s_waitcnt lgkmcnt(0)
	s_barrier
	ds_read_b32 v12, v208 offset:43008
	s_cmpk_ge_u32 s55, 0x100
	s_movk_i32 s98, 0xff
	s_movk_i32 s99, 0x11ff
	s_cselect_b32 s98, s99, s98
	s_sub_u32 s98, s98, s55
	s_cmp_lg_u64 s[44:45], 0
	s_cselect_b32 s98, s55, s98
	s_lshl_b32 s98, s98, 11
	s_mov_b32 s99, 0
	s_movk_i32 s0, 0x7fff
	s_add_i32 s55, s55, 16
	s_waitcnt lgkmcnt(0)
	v_bfe_u32 v14, v12, 16, 1
	v_add3_u32 v14, v12, v14, s0
	v_lshl_add_u64 v[12:13], v[210:211], 0, s[98:99]
	s_add_i32 s64, s64, 1
	s_cmpk_lg_i32 s55, 0x1100
	global_store_short_d16_hi v[12:13], v14, off

; __device__ __forceinline__ void rwkv_scan_unit(const Params& p, int unit, char* smem) {
;     ...
;         const char* lb = smem + st + ks * 16;
;         const char* vb = smem + st + 1280 + rl * 4;
;         float* yl = (float*)(smem + YOFF + (ci & 1) * 1024) + rl;
;         f32x4 e4 = *(const f32x4*)(lb), kd4 = *(const f32x4*)(lb + 256), ka4 = *(const f32x4*)(lb + 512), r4 = *(const f32x4*)(lb + 768), kk4 = *(const f32x4*)(lb + 1024);
;         float vv = *(const float*)vb;
;         f32x2 sA = {s0, s1}, sB = {s2, s3};
;         float c;
;         { const f32x2 cv = sA * (f32x2){kk4[0], kk4[1]} + sB * (f32x2){kk4[2], kk4[3]}; c = red16(cv[0] + cv[1]); }
; #pragma unroll
;         for (int u = 0; u < SCH; ++u) {
;             f32x4 ne = e4, nkd = kd4, nka = ka4, nr = r4, nkk = kk4; float nv = vv;
;             if (u + 1 < SCH) { const char* q = lb + (u + 1) * STEPB;
;                 ne = *(const f32x4*)(q); nkd = *(const f32x4*)(q + 256); nka = *(const f32x4*)(q + 512); nr = *(const f32x4*)(q + 768); nkk = *(const f32x4*)(q + 1024);
;                 nv = *(const float*)(vb + (u + 1) * STEPB); }
;             const f32x2 v2 = {vv, vv}, c2 = {c, c};
;             const f32x2 tA = __builtin_elementwise_fma(v2, (f32x2){kd4[0], kd4[1]}, __builtin_elementwise_fma(-sA, (f32x2){e4[0], e4[1]}, sA));
;             const f32x2 tB = __builtin_elementwise_fma(v2, (f32x2){kd4[2], kd4[3]}, __builtin_elementwise_fma(-sB, (f32x2){e4[2], e4[3]}, sB));
;             sA = __builtin_elementwise_fma(-c2, (f32x2){ka4[0], ka4[1]}, tA);
;             sB = __builtin_elementwise_fma(-c2, (f32x2){ka4[2], ka4[3]}, tB);
;             const f32x2 yv = __builtin_elementwise_fma(sB, (f32x2){r4[2], r4[3]}, sA * (f32x2){r4[0], r4[1]});
;             float y = yv[0] + yv[1];
;             if (u + 1 < SCH) {
;                 const f32x2 cv = __builtin_elementwise_fma(sB, (f32x2){nkk[2], nkk[3]}, sA * (f32x2){nkk[0], nkk[1]});
;                 float cn = cv[0] + cv[1];
;                 cn = DPP_ADD(cn, 0xB1);  y = DPP_ADD(y, 0xB1);
;                 cn = DPP_ADD(cn, 0x4E);  y = DPP_ADD(y, 0x4E);
;                 cn = DPP_ADD(cn, 0x141); y = DPP_ADD(y, 0x141);
;                 cn = DPP_ADD(cn, 0x140); y = DPP_ADD(y, 0x140);
;                 c = cn;
;             } else y = red16(y);
;             if (ks == 0) yl[u * 16] = y;
.Lsc_p1_body:
	s_add_i32 s30, s64, -1
	s_and_b32 s30, s30, 1
	ds_read_b128 v[32:35], v235 offset:1024
	ds_read_b128 v[12:15], v235 offset:0
	ds_read_b128 v[16:19], v235 offset:256
	ds_read_b32 v36, v236 offset:1280
	ds_read_b128 v[24:27], v235 offset:512
	ds_read_b128 v[28:31], v235 offset:768
	ds_read_b128 v[40:43], v235 offset:1344
	ds_read_b128 v[60:63], v235 offset:1856
	ds_read_b128 v[44:47], v235 offset:1600
	ds_read_b128 v[94:97], v235 offset:2368
	ds_read_b32 v38, v236 offset:2624
	ds_read_b128 v[64:67], v235 offset:2112
	s_lshl_b32 s52, s30, 10
	s_waitcnt lgkmcnt(11)
	v_pk_mul_f32 v[32:33], v[20:21], v[32:33]
	s_waitcnt lgkmcnt(10)
	v_pk_fma_f32 v[12:13], v[20:21], v[12:13], v[20:21] neg_lo:[1,0,0] neg_hi:[1,0,0]
	v_pk_fma_f32 v[32:33], v[22:23], v[34:35], v[32:33]
	v_pk_fma_f32 v[14:15], v[22:23], v[14:15], v[22:23] neg_lo:[1,0,0] neg_hi:[1,0,0]
	v_add_f32_e32 v34, v32, v33
	s_waitcnt lgkmcnt(8)
	v_pk_fma_f32 v[12:13], v[36:37], v[16:17], v[12:13] op_sel_hi:[0,1,1]
	v_pk_fma_f32 v[14:15], v[36:37], v[18:19], v[14:15] op_sel_hi:[0,1,1]
	v_add_f32_dpp v35, v34, v34 quad_perm:[1,0,3,2] row_mask:0xf bank_mask:0xf bound_ctrl:1
	s_nop 1
	v_add_f32_dpp v34, v35, v35 quad_perm:[2,3,0,1] row_mask:0xf bank_mask:0xf bound_ctrl:1
	s_nop 1
	v_add_f32_dpp v35, v34, v34 row_half_mirror row_mask:0xf bank_mask:0xf bound_ctrl:1
	s_nop 1
	v_add_f32_dpp v90, v35, v35 row_mirror row_mask:0xf bank_mask:0xf bound_ctrl:1
	ds_read_b128 v[16:19], v235 offset:2944
	ds_read_b128 v[32:35], v235 offset:3712
	ds_read_b32 v36, v236 offset:3968
	s_waitcnt lgkmcnt(10)
	v_pk_fma_f32 v[20:21], v[90:91], v[24:25], v[12:13] op_sel_hi:[0,1,1] neg_lo:[1,0,0] neg_hi:[1,0,0]
	v_pk_fma_f32 v[22:23], v[90:91], v[26:27], v[14:15] op_sel_hi:[0,1,1] neg_lo:[1,0,0] neg_hi:[1,0,0]
	ds_read_b128 v[12:15], v235 offset:2688
	ds_read_b128 v[24:27], v235 offset:3200
	s_waitcnt lgkmcnt(7)
	v_pk_mul_f32 v[94:95], v[20:21], v[94:95]
	v_pk_mul_f32 v[28:29], v[20:21], v[28:29]
	v_pk_fma_f32 v[94:95], v[22:23], v[96:97], v[94:95]
	v_pk_fma_f32 v[28:29], v[22:23], v[30:31], v[28:29]
	v_add_f32_e32 v96, v94, v95
	v_add_f32_e32 v30, v28, v29
	v_pk_fma_f32 v[40:41], v[20:21], v[40:41], v[20:21] neg_lo:[1,0,0] neg_hi:[1,0,0]
	v_add_f32_dpp v97, v96, v96 quad_perm:[1,0,3,2] row_mask:0xf bank_mask:0xf bound_ctrl:1
	v_add_f32_dpp v31, v30, v30 quad_perm:[1,0,3,2] row_mask:0xf bank_mask:0xf bound_ctrl:1
	v_pk_fma_f32 v[42:43], v[22:23], v[42:43], v[22:23] neg_lo:[1,0,0] neg_hi:[1,0,0]
	v_add_f32_dpp v96, v97, v97 quad_perm:[2,3,0,1] row_mask:0xf bank_mask:0xf bound_ctrl:1
	v_add_f32_dpp v30, v31, v31 quad_perm:[2,3,0,1] row_mask:0xf bank_mask:0xf bound_ctrl:1
	s_waitcnt lgkmcnt(6)
	v_pk_fma_f32 v[40:41], v[38:39], v[44:45], v[40:41] op_sel_hi:[0,1,1]
	v_add_f32_dpp v97, v96, v96 row_half_mirror row_mask:0xf bank_mask:0xf bound_ctrl:1
	v_add_f32_dpp v31, v30, v30 row_half_mirror row_mask:0xf bank_mask:0xf bound_ctrl:1
	v_pk_fma_f32 v[42:43], v[38:39], v[46:47], v[42:43] op_sel_hi:[0,1,1]
	v_add_f32_dpp v90, v97, v97 row_mirror row_mask:0xf bank_mask:0xf bound_ctrl:1
	v_add_f32_dpp v30, v31, v31 row_mirror row_mask:0xf bank_mask:0xf bound_ctrl:1
	ds_write_b32 v237, v30 offset:43008
	ds_read_b128 v[28:31], v235 offset:3456
	v_pk_fma_f32 v[20:21], v[90:91], v[60:61], v[40:41] op_sel_hi:[0,1,1] neg_lo:[1,0,0] neg_hi:[1,0,0]
	v_pk_fma_f32 v[22:23], v[90:91], v[62:63], v[42:43] op_sel_hi:[0,1,1] neg_lo:[1,0,0] neg_hi:[1,0,0]
	ds_read_b128 v[40:43], v235 offset:4032
	ds_read_b128 v[60:63], v235 offset:4544
	ds_read_b128 v[44:47], v235 offset:4288
	ds_read_b128 v[94:97], v235 offset:5056
	ds_read_b32 v38, v236 offset:5312
	s_waitcnt lgkmcnt(8)
	v_pk_mul_f32 v[32:33], v[20:21], v[32:33]
	v_pk_mul_f32 v[64:65], v[20:21], v[64:65]
	v_pk_fma_f32 v[32:33], v[22:23], v[34:35], v[32:33]
	v_pk_fma_f32 v[64:65], v[22:23], v[66:67], v[64:65]
	v_add_f32_e32 v34, v32, v33
	v_add_f32_e32 v66, v64, v65
	v_pk_fma_f32 v[12:13], v[20:21], v[12:13], v[20:21] neg_lo:[1,0,0] neg_hi:[1,0,0]
	v_add_f32_dpp v35, v34, v34 quad_perm:[1,0,3,2] row_mask:0xf bank_mask:0xf bound_ctrl:1
	v_add_f32_dpp v67, v66, v66 quad_perm:[1,0,3,2] row_mask:0xf bank_mask:0xf bound_ctrl:1
	v_pk_fma_f32 v[14:15], v[22:23], v[14:15], v[22:23] neg_lo:[1,0,0] neg_hi:[1,0,0]
	v_add_f32_dpp v34, v35, v35 quad_perm:[2,3,0,1] row_mask:0xf bank_mask:0xf bound_ctrl:1
	v_add_f32_dpp v66, v67, v67 quad_perm:[2,3,0,1] row_mask:0xf bank_mask:0xf bound_ctrl:1
	v_pk_fma_f32 v[12:13], v[36:37], v[16:17], v[12:13] op_sel_hi:[0,1,1]
	v_add_f32_dpp v35, v34, v34 row_half_mirror row_mask:0xf bank_mask:0xf bound_ctrl:1
	v_add_f32_dpp v67, v66, v66 row_half_mirror row_mask:0xf bank_mask:0xf bound_ctrl:1
	v_pk_fma_f32 v[14:15], v[36:37], v[18:19], v[14:15] op_sel_hi:[0,1,1]
	v_add_f32_dpp v90, v35, v35 row_mirror row_mask:0xf bank_mask:0xf bound_ctrl:1
	v_add_f32_dpp v66, v67, v67 row_mirror row_mask:0xf bank_mask:0xf bound_ctrl:1
	ds_write_b32 v237, v66 offset:43072
	ds_read_b128 v[64:67], v235 offset:4800
	s_waitcnt lgkmcnt(9)
	v_pk_fma_f32 v[20:21], v[90:91], v[24:25], v[12:13] op_sel_hi:[0,1,1] neg_lo:[1,0,0] neg_hi:[1,0,0]
	v_pk_fma_f32 v[22:23], v[90:91], v[26:27], v[14:15] op_sel_hi:[0,1,1] neg_lo:[1,0,0] neg_hi:[1,0,0]
	ds_read_b128 v[12:15], v235 offset:5376
	ds_read_b128 v[24:27], v235 offset:5888
	ds_read_b128 v[16:19], v235 offset:5632
	ds_read_b128 v[32:35], v235 offset:6400
	ds_read_b32 v36, v236 offset:6656
	s_waitcnt lgkmcnt(7)
; #define DPP_ADD(v, ctrl) ((v) + __builtin_bit_cast(float, __builtin_amdgcn_update_dpp(0, __builtin_bit_cast(int, (v)), (ctrl), 0xf, 0xf, true)))
; __device__ __forceinline__ void rwkv_scan_unit(const Params& p, int unit, char* smem) {
;     ...
;         for (int u = 0; u < SCH; ++u) {
;             f32x4 ne = e4, nkd = kd4, nka = ka4, nr = r4, nkk = kk4; float nv = vv;
;             if (u + 1 < SCH) { const char* q = lb + (u + 1) * STEPB;
;                 ne = *(const f32x4*)(q); nkd = *(const f32x4*)(q + 256); nka = *(const f32x4*)(q + 512); nr = *(const f32x4*)(q + 768); nkk = *(const f32x4*)(q + 1024);
;                 nv = *(const float*)(vb + (u + 1) * STEPB); }
;             const f32x2 v2 = {vv, vv}, c2 = {c, c};
;             const f32x2 tA = __builtin_elementwise_fma(v2, (f32x2){kd4[0], kd4[1]}, __builtin_elementwise_fma(-sA, (f32x2){e4[0], e4[1]}, sA));
;             const f32x2 tB = __builtin_elementwise_fma(v2, (f32x2){kd4[2], kd4[3]}, __builtin_elementwise_fma(-sB, (f32x2){e4[2], e4[3]}, sB));
;             sA = __builtin_elementwise_fma(-c2, (f32x2){ka4[0], ka4[1]}, tA);
;             sB = __builtin_elementwise_fma(-c2, (f32x2){ka4[2], ka4[3]}, tB);
;             const f32x2 yv = __builtin_elementwise_fma(sB, (f32x2){r4[2], r4[3]}, sA * (f32x2){r4[0], r4[1]});
;             float y = yv[0] + yv[1];
;             if (u + 1 < SCH) {
;                 const f32x2 cv = __builtin_elementwise_fma(sB, (f32x2){nkk[2], nkk[3]}, sA * (f32x2){nkk[0], nkk[1]});
;                 float cn = cv[0] + cv[1];
;                 cn = DPP_ADD(cn, 0xB1);  y = DPP_ADD(y, 0xB1);
;                 cn = DPP_ADD(cn, 0x4E);  y = DPP_ADD(y, 0x4E);
;                 cn = DPP_ADD(cn, 0x141); y = DPP_ADD(y, 0x141);
;                 cn = DPP_ADD(cn, 0x140); y = DPP_ADD(y, 0x140);
;                 c = cn;
;             } else y = red16(y);
;             if (ks == 0) yl[u * 16] = y;
;             e4 = ne; kd4 = nkd; ka4 = nka; r4 = nr; kk4 = nkk; vv = nv;
;         }
	v_pk_mul_f32 v[94:95], v[20:21], v[94:95]
	v_pk_mul_f32 v[28:29], v[20:21], v[28:29]
	v_pk_fma_f32 v[94:95], v[22:23], v[96:97], v[94:95]
	v_pk_fma_f32 v[28:29], v[22:23], v[30:31], v[28:29]
	v_add_f32_e32 v96, v94, v95
	v_add_f32_e32 v30, v28, v29
	v_pk_fma_f32 v[40:41], v[20:21], v[40:41], v[20:21] neg_lo:[1,0,0] neg_hi:[1,0,0]
	v_add_f32_dpp v97, v96, v96 quad_perm:[1,0,3,2] row_mask:0xf bank_mask:0xf bound_ctrl:1
	v_add_f32_dpp v31, v30, v30 quad_perm:[1,0,3,2] row_mask:0xf bank_mask:0xf bound_ctrl:1
	v_pk_fma_f32 v[42:43], v[22:23], v[42:43], v[22:23] neg_lo:[1,0,0] neg_hi:[1,0,0]
	v_add_f32_dpp v96, v97, v97 quad_perm:[2,3,0,1] row_mask:0xf bank_mask:0xf bound_ctrl:1
	v_add_f32_dpp v30, v31, v31 quad_perm:[2,3,0,1] row_mask:0xf bank_mask:0xf bound_ctrl:1
	v_pk_fma_f32 v[40:41], v[38:39], v[44:45], v[40:41] op_sel_hi:[0,1,1]
	v_add_f32_dpp v97, v96, v96 row_half_mirror row_mask:0xf bank_mask:0xf bound_ctrl:1
	v_add_f32_dpp v31, v30, v30 row_half_mirror row_mask:0xf bank_mask:0xf bound_ctrl:1
	v_pk_fma_f32 v[42:43], v[38:39], v[46:47], v[42:43] op_sel_hi:[0,1,1]
	v_add_f32_dpp v90, v97, v97 row_mirror row_mask:0xf bank_mask:0xf bound_ctrl:1
	v_add_f32_dpp v30, v31, v31 row_mirror row_mask:0xf bank_mask:0xf bound_ctrl:1
	ds_write_b32 v237, v30 offset:43136
	ds_read_b128 v[28:31], v235 offset:6144
	v_pk_fma_f32 v[20:21], v[90:91], v[60:61], v[40:41] op_sel_hi:[0,1,1] neg_lo:[1,0,0] neg_hi:[1,0,0]
	v_pk_fma_f32 v[22:23], v[90:91], v[62:63], v[42:43] op_sel_hi:[0,1,1] neg_lo:[1,0,0] neg_hi:[1,0,0]
	ds_read_b128 v[40:43], v235 offset:6720
	ds_read_b128 v[60:63], v235 offset:7232
	ds_read_b128 v[44:47], v235 offset:6976
	ds_read_b128 v[94:97], v235 offset:7744
	ds_read_b32 v38, v236 offset:8000
	s_waitcnt lgkmcnt(7)
	v_pk_mul_f32 v[32:33], v[20:21], v[32:33]
	v_pk_mul_f32 v[64:65], v[20:21], v[64:65]
	v_pk_fma_f32 v[32:33], v[22:23], v[34:35], v[32:33]
	v_pk_fma_f32 v[64:65], v[22:23], v[66:67], v[64:65]
	v_add_f32_e32 v34, v32, v33
	v_add_f32_e32 v66, v64, v65
	v_pk_fma_f32 v[12:13], v[20:21], v[12:13], v[20:21] neg_lo:[1,0,0] neg_hi:[1,0,0]
	v_add_f32_dpp v35, v34, v34 quad_perm:[1,0,3,2] row_mask:0xf bank_mask:0xf bound_ctrl:1
	v_add_f32_dpp v67, v66, v66 quad_perm:[1,0,3,2] row_mask:0xf bank_mask:0xf bound_ctrl:1
	v_pk_fma_f32 v[14:15], v[22:23], v[14:15], v[22:23] neg_lo:[1,0,0] neg_hi:[1,0,0]
	v_add_f32_dpp v34, v35, v35 quad_perm:[2,3,0,1] row_mask:0xf bank_mask:0xf bound_ctrl:1
	v_add_f32_dpp v66, v67, v67 quad_perm:[2,3,0,1] row_mask:0xf bank_mask:0xf bound_ctrl:1
	v_pk_fma_f32 v[12:13], v[36:37], v[16:17], v[12:13] op_sel_hi:[0,1,1]
	v_add_f32_dpp v35, v34, v34 row_half_mirror row_mask:0xf bank_mask:0xf bound_ctrl:1
	v_add_f32_dpp v67, v66, v66 row_half_mirror row_mask:0xf bank_mask:0xf bound_ctrl:1
	v_pk_fma_f32 v[14:15], v[36:37], v[18:19], v[14:15] op_sel_hi:[0,1,1]
	v_add_f32_dpp v90, v35, v35 row_mirror row_mask:0xf bank_mask:0xf bound_ctrl:1
	v_add_f32_dpp v66, v67, v67 row_mirror row_mask:0xf bank_mask:0xf bound_ctrl:1
	ds_write_b32 v237, v66 offset:43200
	ds_read_b128 v[64:67], v235 offset:7488
	v_pk_fma_f32 v[20:21], v[90:91], v[24:25], v[12:13] op_sel_hi:[0,1,1] neg_lo:[1,0,0] neg_hi:[1,0,0]
	v_pk_fma_f32 v[22:23], v[90:91], v[26:27], v[14:15] op_sel_hi:[0,1,1] neg_lo:[1,0,0] neg_hi:[1,0,0]
	ds_read_b128 v[12:15], v235 offset:8064
	ds_read_b128 v[24:27], v235 offset:8576
	ds_read_b128 v[16:19], v235 offset:8320
	ds_read_b128 v[32:35], v235 offset:9088
	ds_read_b32 v36, v236 offset:9344
	s_waitcnt lgkmcnt(7)
	v_pk_mul_f32 v[94:95], v[20:21], v[94:95]
	v_pk_mul_f32 v[28:29], v[20:21], v[28:29]
	v_pk_fma_f32 v[94:95], v[22:23], v[96:97], v[94:95]
	v_pk_fma_f32 v[28:29], v[22:23], v[30:31], v[28:29]
	v_add_f32_e32 v96, v94, v95
	v_add_f32_e32 v30, v28, v29
	v_pk_fma_f32 v[40:41], v[20:21], v[40:41], v[20:21] neg_lo:[1,0,0] neg_hi:[1,0,0]
	v_add_f32_dpp v97, v96, v96 quad_perm:[1,0,3,2] row_mask:0xf bank_mask:0xf bound_ctrl:1
	v_add_f32_dpp v31, v30, v30 quad_perm:[1,0,3,2] row_mask:0xf bank_mask:0xf bound_ctrl:1
	v_pk_fma_f32 v[42:43], v[22:23], v[42:43], v[22:23] neg_lo:[1,0,0] neg_hi:[1,0,0]
	v_add_f32_dpp v96, v97, v97 quad_perm:[2,3,0,1] row_mask:0xf bank_mask:0xf bound_ctrl:1
	v_add_f32_dpp v30, v31, v31 quad_perm:[2,3,0,1] row_mask:0xf bank_mask:0xf bound_ctrl:1
	v_pk_fma_f32 v[40:41], v[38:39], v[44:45], v[40:41] op_sel_hi:[0,1,1]
	v_add_f32_dpp v97, v96, v96 row_half_mirror row_mask:0xf bank_mask:0xf bound_ctrl:1
	v_add_f32_dpp v31, v30, v30 row_half_mirror row_mask:0xf bank_mask:0xf bound_ctrl:1
	v_pk_fma_f32 v[42:43], v[38:39], v[46:47], v[42:43] op_sel_hi:[0,1,1]
	v_add_f32_dpp v90, v97, v97 row_mirror row_mask:0xf bank_mask:0xf bound_ctrl:1
	v_add_f32_dpp v30, v31, v31 row_mirror row_mask:0xf bank_mask:0xf bound_ctrl:1
	ds_write_b32 v237, v30 offset:43264
	ds_read_b128 v[28:31], v235 offset:8832
	v_pk_fma_f32 v[20:21], v[90:91], v[60:61], v[40:41] op_sel_hi:[0,1,1] neg_lo:[1,0,0] neg_hi:[1,0,0]
	v_pk_fma_f32 v[22:23], v[90:91], v[62:63], v[42:43] op_sel_hi:[0,1,1] neg_lo:[1,0,0] neg_hi:[1,0,0]
	ds_read_b128 v[40:43], v235 offset:9408
	ds_read_b128 v[60:63], v235 offset:9920
	ds_read_b128 v[44:47], v235 offset:9664
	ds_read_b128 v[94:97], v235 offset:10432
	ds_read_b32 v38, v236 offset:10688
	s_waitcnt lgkmcnt(7)
; #define DPP_ADD(v, ctrl) ((v) + __builtin_bit_cast(float, __builtin_amdgcn_update_dpp(0, __builtin_bit_cast(int, (v)), (ctrl), 0xf, 0xf, true)))
; __device__ __forceinline__ void rwkv_scan_unit(const Params& p, int unit, char* smem) {
;     ...
;         for (int u = 0; u < SCH; ++u) {
;             f32x4 ne = e4, nkd = kd4, nka = ka4, nr = r4, nkk = kk4; float nv = vv;
;             if (u + 1 < SCH) { const char* q = lb + (u + 1) * STEPB;
;                 ne = *(const f32x4*)(q); nkd = *(const f32x4*)(q + 256); nka = *(const f32x4*)(q + 512); nr = *(const f32x4*)(q + 768); nkk = *(const f32x4*)(q + 1024);
;                 nv = *(const float*)(vb + (u + 1) * STEPB); }
;             const f32x2 v2 = {vv, vv}, c2 = {c, c};
;             const f32x2 tA = __builtin_elementwise_fma(v2, (f32x2){kd4[0], kd4[1]}, __builtin_elementwise_fma(-sA, (f32x2){e4[0], e4[1]}, sA));
;             const f32x2 tB = __builtin_elementwise_fma(v2, (f32x2){kd4[2], kd4[3]}, __builtin_elementwise_fma(-sB, (f32x2){e4[2], e4[3]}, sB));
;             sA = __builtin_elementwise_fma(-c2, (f32x2){ka4[0], ka4[1]}, tA);
;             sB = __builtin_elementwise_fma(-c2, (f32x2){ka4[2], ka4[3]}, tB);
;             const f32x2 yv = __builtin_elementwise_fma(sB, (f32x2){r4[2], r4[3]}, sA * (f32x2){r4[0], r4[1]});
;             float y = yv[0] + yv[1];
;             if (u + 1 < SCH) {
;                 const f32x2 cv = __builtin_elementwise_fma(sB, (f32x2){nkk[2], nkk[3]}, sA * (f32x2){nkk[0], nkk[1]});
;                 float cn = cv[0] + cv[1];
;                 cn = DPP_ADD(cn, 0xB1);  y = DPP_ADD(y, 0xB1);
;                 cn = DPP_ADD(cn, 0x4E);  y = DPP_ADD(y, 0x4E);
;                 cn = DPP_ADD(cn, 0x141); y = DPP_ADD(y, 0x141);
;                 cn = DPP_ADD(cn, 0x140); y = DPP_ADD(y, 0x140);
;                 c = cn;
;             } else y = red16(y);
;             if (ks == 0) yl[u * 16] = y;
;             e4 = ne; kd4 = nkd; ka4 = nka; r4 = nr; kk4 = nkk; vv = nv;
;         }
	v_pk_mul_f32 v[32:33], v[20:21], v[32:33]
	v_pk_mul_f32 v[64:65], v[20:21], v[64:65]
	v_pk_fma_f32 v[32:33], v[22:23], v[34:35], v[32:33]
	v_pk_fma_f32 v[64:65], v[22:23], v[66:67], v[64:65]
	v_add_f32_e32 v34, v32, v33
	v_add_f32_e32 v66, v64, v65
	v_pk_fma_f32 v[12:13], v[20:21], v[12:13], v[20:21] neg_lo:[1,0,0] neg_hi:[1,0,0]
	v_add_f32_dpp v35, v34, v34 quad_perm:[1,0,3,2] row_mask:0xf bank_mask:0xf bound_ctrl:1
	v_add_f32_dpp v67, v66, v66 quad_perm:[1,0,3,2] row_mask:0xf bank_mask:0xf bound_ctrl:1
	v_pk_fma_f32 v[14:15], v[22:23], v[14:15], v[22:23] neg_lo:[1,0,0] neg_hi:[1,0,0]
	v_add_f32_dpp v34, v35, v35 quad_perm:[2,3,0,1] row_mask:0xf bank_mask:0xf bound_ctrl:1
	v_add_f32_dpp v66, v67, v67 quad_perm:[2,3,0,1] row_mask:0xf bank_mask:0xf bound_ctrl:1
	v_pk_fma_f32 v[12:13], v[36:37], v[16:17], v[12:13] op_sel_hi:[0,1,1]
	v_add_f32_dpp v35, v34, v34 row_half_mirror row_mask:0xf bank_mask:0xf bound_ctrl:1
	v_add_f32_dpp v67, v66, v66 row_half_mirror row_mask:0xf bank_mask:0xf bound_ctrl:1
	v_pk_fma_f32 v[14:15], v[36:37], v[18:19], v[14:15] op_sel_hi:[0,1,1]
	v_add_f32_dpp v90, v35, v35 row_mirror row_mask:0xf bank_mask:0xf bound_ctrl:1
	v_add_f32_dpp v66, v67, v67 row_mirror row_mask:0xf bank_mask:0xf bound_ctrl:1
	ds_write_b32 v237, v66 offset:43328
	ds_read_b128 v[64:67], v235 offset:10176
	v_pk_fma_f32 v[20:21], v[90:91], v[24:25], v[12:13] op_sel_hi:[0,1,1] neg_lo:[1,0,0] neg_hi:[1,0,0]
	v_pk_fma_f32 v[22:23], v[90:91], v[26:27], v[14:15] op_sel_hi:[0,1,1] neg_lo:[1,0,0] neg_hi:[1,0,0]
	ds_read_b128 v[12:15], v235 offset:10752
	ds_read_b128 v[24:27], v235 offset:11264
	ds_read_b128 v[16:19], v235 offset:11008
	ds_read_b128 v[32:35], v235 offset:11776
	ds_read_b32 v36, v236 offset:12032
	s_waitcnt lgkmcnt(7)
	v_pk_mul_f32 v[94:95], v[20:21], v[94:95]
	v_pk_mul_f32 v[28:29], v[20:21], v[28:29]
	v_pk_fma_f32 v[94:95], v[22:23], v[96:97], v[94:95]
	v_pk_fma_f32 v[28:29], v[22:23], v[30:31], v[28:29]
	v_add_f32_e32 v96, v94, v95
	v_add_f32_e32 v30, v28, v29
	v_pk_fma_f32 v[40:41], v[20:21], v[40:41], v[20:21] neg_lo:[1,0,0] neg_hi:[1,0,0]
	v_add_f32_dpp v97, v96, v96 quad_perm:[1,0,3,2] row_mask:0xf bank_mask:0xf bound_ctrl:1
	v_add_f32_dpp v31, v30, v30 quad_perm:[1,0,3,2] row_mask:0xf bank_mask:0xf bound_ctrl:1
	v_pk_fma_f32 v[42:43], v[22:23], v[42:43], v[22:23] neg_lo:[1,0,0] neg_hi:[1,0,0]
	v_add_f32_dpp v96, v97, v97 quad_perm:[2,3,0,1] row_mask:0xf bank_mask:0xf bound_ctrl:1
	v_add_f32_dpp v30, v31, v31 quad_perm:[2,3,0,1] row_mask:0xf bank_mask:0xf bound_ctrl:1
	v_pk_fma_f32 v[40:41], v[38:39], v[44:45], v[40:41] op_sel_hi:[0,1,1]
	v_add_f32_dpp v97, v96, v96 row_half_mirror row_mask:0xf bank_mask:0xf bound_ctrl:1
	v_add_f32_dpp v31, v30, v30 row_half_mirror row_mask:0xf bank_mask:0xf bound_ctrl:1
	v_pk_fma_f32 v[42:43], v[38:39], v[46:47], v[42:43] op_sel_hi:[0,1,1]
	v_add_f32_dpp v90, v97, v97 row_mirror row_mask:0xf bank_mask:0xf bound_ctrl:1
	v_add_f32_dpp v30, v31, v31 row_mirror row_mask:0xf bank_mask:0xf bound_ctrl:1
	ds_write_b32 v237, v30 offset:43392
	ds_read_b128 v[28:31], v235 offset:11520
	v_pk_fma_f32 v[20:21], v[90:91], v[60:61], v[40:41] op_sel_hi:[0,1,1] neg_lo:[1,0,0] neg_hi:[1,0,0]
	v_pk_fma_f32 v[22:23], v[90:91], v[62:63], v[42:43] op_sel_hi:[0,1,1] neg_lo:[1,0,0] neg_hi:[1,0,0]
	ds_read_b128 v[40:43], v235 offset:12096
	ds_read_b128 v[60:63], v235 offset:12608
	ds_read_b128 v[44:47], v235 offset:12352
	ds_read_b128 v[94:97], v235 offset:13120
	ds_read_b32 v38, v236 offset:13376
	s_waitcnt lgkmcnt(7)
	v_pk_mul_f32 v[32:33], v[20:21], v[32:33]
	v_pk_mul_f32 v[64:65], v[20:21], v[64:65]
	v_pk_fma_f32 v[32:33], v[22:23], v[34:35], v[32:33]
	v_pk_fma_f32 v[64:65], v[22:23], v[66:67], v[64:65]
	v_add_f32_e32 v34, v32, v33
	v_add_f32_e32 v66, v64, v65
	v_pk_fma_f32 v[12:13], v[20:21], v[12:13], v[20:21] neg_lo:[1,0,0] neg_hi:[1,0,0]
	v_add_f32_dpp v35, v34, v34 quad_perm:[1,0,3,2] row_mask:0xf bank_mask:0xf bound_ctrl:1
	v_add_f32_dpp v67, v66, v66 quad_perm:[1,0,3,2] row_mask:0xf bank_mask:0xf bound_ctrl:1
	v_pk_fma_f32 v[14:15], v[22:23], v[14:15], v[22:23] neg_lo:[1,0,0] neg_hi:[1,0,0]
	v_add_f32_dpp v34, v35, v35 quad_perm:[2,3,0,1] row_mask:0xf bank_mask:0xf bound_ctrl:1
	v_add_f32_dpp v66, v67, v67 quad_perm:[2,3,0,1] row_mask:0xf bank_mask:0xf bound_ctrl:1
	v_pk_fma_f32 v[12:13], v[36:37], v[16:17], v[12:13] op_sel_hi:[0,1,1]
	v_add_f32_dpp v35, v34, v34 row_half_mirror row_mask:0xf bank_mask:0xf bound_ctrl:1
	v_add_f32_dpp v67, v66, v66 row_half_mirror row_mask:0xf bank_mask:0xf bound_ctrl:1
	v_pk_fma_f32 v[14:15], v[36:37], v[18:19], v[14:15] op_sel_hi:[0,1,1]
	v_add_f32_dpp v90, v35, v35 row_mirror row_mask:0xf bank_mask:0xf bound_ctrl:1
	v_add_f32_dpp v66, v67, v67 row_mirror row_mask:0xf bank_mask:0xf bound_ctrl:1
	ds_write_b32 v237, v66 offset:43456
	ds_read_b128 v[64:67], v235 offset:12864
	v_pk_fma_f32 v[20:21], v[90:91], v[24:25], v[12:13] op_sel_hi:[0,1,1] neg_lo:[1,0,0] neg_hi:[1,0,0]
	v_pk_fma_f32 v[22:23], v[90:91], v[26:27], v[14:15] op_sel_hi:[0,1,1] neg_lo:[1,0,0] neg_hi:[1,0,0]
	ds_read_b128 v[12:15], v235 offset:13440
	ds_read_b128 v[24:27], v235 offset:13952
	ds_read_b128 v[16:19], v235 offset:13696
	ds_read_b128 v[32:35], v235 offset:14464
	ds_read_b32 v36, v236 offset:14720
	s_waitcnt lgkmcnt(7)
; #define DPP_ADD(v, ctrl) ((v) + __builtin_bit_cast(float, __builtin_amdgcn_update_dpp(0, __builtin_bit_cast(int, (v)), (ctrl), 0xf, 0xf, true)))
; __device__ __forceinline__ void rwkv_scan_unit(const Params& p, int unit, char* smem) {
;     ...
;         for (int u = 0; u < SCH; ++u) {
;             f32x4 ne = e4, nkd = kd4, nka = ka4, nr = r4, nkk = kk4; float nv = vv;
;             if (u + 1 < SCH) { const char* q = lb + (u + 1) * STEPB;
;                 ne = *(const f32x4*)(q); nkd = *(const f32x4*)(q + 256); nka = *(const f32x4*)(q + 512); nr = *(const f32x4*)(q + 768); nkk = *(const f32x4*)(q + 1024);
;                 nv = *(const float*)(vb + (u + 1) * STEPB); }
;             const f32x2 v2 = {vv, vv}, c2 = {c, c};
;             const f32x2 tA = __builtin_elementwise_fma(v2, (f32x2){kd4[0], kd4[1]}, __builtin_elementwise_fma(-sA, (f32x2){e4[0], e4[1]}, sA));
;             const f32x2 tB = __builtin_elementwise_fma(v2, (f32x2){kd4[2], kd4[3]}, __builtin_elementwise_fma(-sB, (f32x2){e4[2], e4[3]}, sB));
;             sA = __builtin_elementwise_fma(-c2, (f32x2){ka4[0], ka4[1]}, tA);
;             sB = __builtin_elementwise_fma(-c2, (f32x2){ka4[2], ka4[3]}, tB);
;             const f32x2 yv = __builtin_elementwise_fma(sB, (f32x2){r4[2], r4[3]}, sA * (f32x2){r4[0], r4[1]});
;             float y = yv[0] + yv[1];
;             if (u + 1 < SCH) {
;                 const f32x2 cv = __builtin_elementwise_fma(sB, (f32x2){nkk[2], nkk[3]}, sA * (f32x2){nkk[0], nkk[1]});
;                 float cn = cv[0] + cv[1];
;                 cn = DPP_ADD(cn, 0xB1);  y = DPP_ADD(y, 0xB1);
;                 cn = DPP_ADD(cn, 0x4E);  y = DPP_ADD(y, 0x4E);
;                 cn = DPP_ADD(cn, 0x141); y = DPP_ADD(y, 0x141);
;                 cn = DPP_ADD(cn, 0x140); y = DPP_ADD(y, 0x140);
;                 c = cn;
;             } else y = red16(y);
;             if (ks == 0) yl[u * 16] = y;
;             e4 = ne; kd4 = nkd; ka4 = nka; r4 = nr; kk4 = nkk; vv = nv;
;         }
	v_pk_mul_f32 v[94:95], v[20:21], v[94:95]
	v_pk_mul_f32 v[28:29], v[20:21], v[28:29]
	v_pk_fma_f32 v[94:95], v[22:23], v[96:97], v[94:95]
	v_pk_fma_f32 v[28:29], v[22:23], v[30:31], v[28:29]
	v_add_f32_e32 v96, v94, v95
	v_add_f32_e32 v30, v28, v29
	v_pk_fma_f32 v[40:41], v[20:21], v[40:41], v[20:21] neg_lo:[1,0,0] neg_hi:[1,0,0]
	v_add_f32_dpp v97, v96, v96 quad_perm:[1,0,3,2] row_mask:0xf bank_mask:0xf bound_ctrl:1
	v_add_f32_dpp v31, v30, v30 quad_perm:[1,0,3,2] row_mask:0xf bank_mask:0xf bound_ctrl:1
	v_pk_fma_f32 v[42:43], v[22:23], v[42:43], v[22:23] neg_lo:[1,0,0] neg_hi:[1,0,0]
	v_add_f32_dpp v96, v97, v97 quad_perm:[2,3,0,1] row_mask:0xf bank_mask:0xf bound_ctrl:1
	v_add_f32_dpp v30, v31, v31 quad_perm:[2,3,0,1] row_mask:0xf bank_mask:0xf bound_ctrl:1
	v_pk_fma_f32 v[40:41], v[38:39], v[44:45], v[40:41] op_sel_hi:[0,1,1]
	v_add_f32_dpp v97, v96, v96 row_half_mirror row_mask:0xf bank_mask:0xf bound_ctrl:1
	v_add_f32_dpp v31, v30, v30 row_half_mirror row_mask:0xf bank_mask:0xf bound_ctrl:1
	v_pk_fma_f32 v[42:43], v[38:39], v[46:47], v[42:43] op_sel_hi:[0,1,1]
	v_add_f32_dpp v90, v97, v97 row_mirror row_mask:0xf bank_mask:0xf bound_ctrl:1
	v_add_f32_dpp v30, v31, v31 row_mirror row_mask:0xf bank_mask:0xf bound_ctrl:1
	ds_write_b32 v237, v30 offset:43520
	ds_read_b128 v[28:31], v235 offset:14208
	v_pk_fma_f32 v[20:21], v[90:91], v[60:61], v[40:41] op_sel_hi:[0,1,1] neg_lo:[1,0,0] neg_hi:[1,0,0]
	v_pk_fma_f32 v[22:23], v[90:91], v[62:63], v[42:43] op_sel_hi:[0,1,1] neg_lo:[1,0,0] neg_hi:[1,0,0]
	ds_read_b128 v[40:43], v235 offset:14784
	ds_read_b128 v[60:63], v235 offset:15296
	ds_read_b128 v[44:47], v235 offset:15040
	ds_read_b128 v[94:97], v235 offset:15808
	ds_read_b32 v38, v236 offset:16064
	s_waitcnt lgkmcnt(7)
	v_pk_mul_f32 v[32:33], v[20:21], v[32:33]
	v_pk_mul_f32 v[64:65], v[20:21], v[64:65]
	v_pk_fma_f32 v[32:33], v[22:23], v[34:35], v[32:33]
	v_pk_fma_f32 v[64:65], v[22:23], v[66:67], v[64:65]
	v_add_f32_e32 v34, v32, v33
	v_add_f32_e32 v66, v64, v65
	v_pk_fma_f32 v[12:13], v[20:21], v[12:13], v[20:21] neg_lo:[1,0,0] neg_hi:[1,0,0]
	v_add_f32_dpp v35, v34, v34 quad_perm:[1,0,3,2] row_mask:0xf bank_mask:0xf bound_ctrl:1
	v_add_f32_dpp v67, v66, v66 quad_perm:[1,0,3,2] row_mask:0xf bank_mask:0xf bound_ctrl:1
	v_pk_fma_f32 v[14:15], v[22:23], v[14:15], v[22:23] neg_lo:[1,0,0] neg_hi:[1,0,0]
	v_add_f32_dpp v34, v35, v35 quad_perm:[2,3,0,1] row_mask:0xf bank_mask:0xf bound_ctrl:1
	v_add_f32_dpp v66, v67, v67 quad_perm:[2,3,0,1] row_mask:0xf bank_mask:0xf bound_ctrl:1
	v_pk_fma_f32 v[12:13], v[36:37], v[16:17], v[12:13] op_sel_hi:[0,1,1]
	v_add_f32_dpp v35, v34, v34 row_half_mirror row_mask:0xf bank_mask:0xf bound_ctrl:1
	v_add_f32_dpp v67, v66, v66 row_half_mirror row_mask:0xf bank_mask:0xf bound_ctrl:1
	v_pk_fma_f32 v[14:15], v[36:37], v[18:19], v[14:15] op_sel_hi:[0,1,1]
	v_add_f32_dpp v90, v35, v35 row_mirror row_mask:0xf bank_mask:0xf bound_ctrl:1
	v_add_f32_dpp v66, v67, v67 row_mirror row_mask:0xf bank_mask:0xf bound_ctrl:1
	ds_write_b32 v237, v66 offset:43584
	ds_read_b128 v[64:67], v235 offset:15552
	v_pk_fma_f32 v[20:21], v[90:91], v[24:25], v[12:13] op_sel_hi:[0,1,1] neg_lo:[1,0,0] neg_hi:[1,0,0]
	v_pk_fma_f32 v[22:23], v[90:91], v[26:27], v[14:15] op_sel_hi:[0,1,1] neg_lo:[1,0,0] neg_hi:[1,0,0]
	ds_read_b128 v[12:15], v235 offset:16128
	ds_read_b128 v[24:27], v235 offset:16640
	ds_read_b128 v[16:19], v235 offset:16384
	ds_read_b128 v[32:35], v235 offset:17152
	ds_read_b32 v36, v236 offset:17408
	s_waitcnt lgkmcnt(7)
	v_pk_mul_f32 v[94:95], v[20:21], v[94:95]
	v_pk_mul_f32 v[28:29], v[20:21], v[28:29]
	v_pk_fma_f32 v[94:95], v[22:23], v[96:97], v[94:95]
	v_pk_fma_f32 v[28:29], v[22:23], v[30:31], v[28:29]
	v_add_f32_e32 v96, v94, v95
	v_add_f32_e32 v30, v28, v29
	v_pk_fma_f32 v[40:41], v[20:21], v[40:41], v[20:21] neg_lo:[1,0,0] neg_hi:[1,0,0]
	v_add_f32_dpp v97, v96, v96 quad_perm:[1,0,3,2] row_mask:0xf bank_mask:0xf bound_ctrl:1
	v_add_f32_dpp v31, v30, v30 quad_perm:[1,0,3,2] row_mask:0xf bank_mask:0xf bound_ctrl:1
	v_pk_fma_f32 v[42:43], v[22:23], v[42:43], v[22:23] neg_lo:[1,0,0] neg_hi:[1,0,0]
	v_add_f32_dpp v96, v97, v97 quad_perm:[2,3,0,1] row_mask:0xf bank_mask:0xf bound_ctrl:1
	v_add_f32_dpp v30, v31, v31 quad_perm:[2,3,0,1] row_mask:0xf bank_mask:0xf bound_ctrl:1
	v_pk_fma_f32 v[40:41], v[38:39], v[44:45], v[40:41] op_sel_hi:[0,1,1]
	v_add_f32_dpp v97, v96, v96 row_half_mirror row_mask:0xf bank_mask:0xf bound_ctrl:1
	v_add_f32_dpp v31, v30, v30 row_half_mirror row_mask:0xf bank_mask:0xf bound_ctrl:1
	v_pk_fma_f32 v[42:43], v[38:39], v[46:47], v[42:43] op_sel_hi:[0,1,1]
	v_add_f32_dpp v90, v97, v97 row_mirror row_mask:0xf bank_mask:0xf bound_ctrl:1
	v_add_f32_dpp v30, v31, v31 row_mirror row_mask:0xf bank_mask:0xf bound_ctrl:1
	ds_write_b32 v237, v30 offset:43648
	ds_read_b128 v[28:31], v235 offset:16896
	v_pk_fma_f32 v[20:21], v[90:91], v[60:61], v[40:41] op_sel_hi:[0,1,1] neg_lo:[1,0,0] neg_hi:[1,0,0]
	v_pk_fma_f32 v[22:23], v[90:91], v[62:63], v[42:43] op_sel_hi:[0,1,1] neg_lo:[1,0,0] neg_hi:[1,0,0]
	ds_read_b128 v[40:43], v235 offset:17472
	ds_read_b128 v[60:63], v235 offset:17984
	ds_read_b128 v[44:47], v235 offset:17728
	ds_read_b128 v[94:97], v235 offset:18496
	ds_read_b32 v38, v236 offset:18752
	s_waitcnt lgkmcnt(7)
; #define DPP_ADD(v, ctrl) ((v) + __builtin_bit_cast(float, __builtin_amdgcn_update_dpp(0, __builtin_bit_cast(int, (v)), (ctrl), 0xf, 0xf, true)))
; __device__ __forceinline__ void rwkv_scan_unit(const Params& p, int unit, char* smem) {
;     ...
;         for (int u = 0; u < SCH; ++u) {
;             f32x4 ne = e4, nkd = kd4, nka = ka4, nr = r4, nkk = kk4; float nv = vv;
;             if (u + 1 < SCH) { const char* q = lb + (u + 1) * STEPB;
;                 ne = *(const f32x4*)(q); nkd = *(const f32x4*)(q + 256); nka = *(const f32x4*)(q + 512); nr = *(const f32x4*)(q + 768); nkk = *(const f32x4*)(q + 1024);
;                 nv = *(const float*)(vb + (u + 1) * STEPB); }
;             const f32x2 v2 = {vv, vv}, c2 = {c, c};
;             const f32x2 tA = __builtin_elementwise_fma(v2, (f32x2){kd4[0], kd4[1]}, __builtin_elementwise_fma(-sA, (f32x2){e4[0], e4[1]}, sA));
;             const f32x2 tB = __builtin_elementwise_fma(v2, (f32x2){kd4[2], kd4[3]}, __builtin_elementwise_fma(-sB, (f32x2){e4[2], e4[3]}, sB));
;             sA = __builtin_elementwise_fma(-c2, (f32x2){ka4[0], ka4[1]}, tA);
;             sB = __builtin_elementwise_fma(-c2, (f32x2){ka4[2], ka4[3]}, tB);
;             const f32x2 yv = __builtin_elementwise_fma(sB, (f32x2){r4[2], r4[3]}, sA * (f32x2){r4[0], r4[1]});
;             float y = yv[0] + yv[1];
;             if (u + 1 < SCH) {
;                 const f32x2 cv = __builtin_elementwise_fma(sB, (f32x2){nkk[2], nkk[3]}, sA * (f32x2){nkk[0], nkk[1]});
;                 float cn = cv[0] + cv[1];
;                 cn = DPP_ADD(cn, 0xB1);  y = DPP_ADD(y, 0xB1);
;                 cn = DPP_ADD(cn, 0x4E);  y = DPP_ADD(y, 0x4E);
;                 cn = DPP_ADD(cn, 0x141); y = DPP_ADD(y, 0x141);
;                 cn = DPP_ADD(cn, 0x140); y = DPP_ADD(y, 0x140);
;                 c = cn;
;             } else y = red16(y);
;             if (ks == 0) yl[u * 16] = y;
;             e4 = ne; kd4 = nkd; ka4 = nka; r4 = nr; kk4 = nkk; vv = nv;
;         }
	v_pk_mul_f32 v[32:33], v[20:21], v[32:33]
	v_pk_mul_f32 v[64:65], v[20:21], v[64:65]
	v_pk_fma_f32 v[32:33], v[22:23], v[34:35], v[32:33]
	v_pk_fma_f32 v[64:65], v[22:23], v[66:67], v[64:65]
	v_add_f32_e32 v34, v32, v33
	v_add_f32_e32 v66, v64, v65
	v_pk_fma_f32 v[12:13], v[20:21], v[12:13], v[20:21] neg_lo:[1,0,0] neg_hi:[1,0,0]
	v_add_f32_dpp v35, v34, v34 quad_perm:[1,0,3,2] row_mask:0xf bank_mask:0xf bound_ctrl:1
	v_add_f32_dpp v67, v66, v66 quad_perm:[1,0,3,2] row_mask:0xf bank_mask:0xf bound_ctrl:1
	v_pk_fma_f32 v[14:15], v[22:23], v[14:15], v[22:23] neg_lo:[1,0,0] neg_hi:[1,0,0]
	v_add_f32_dpp v34, v35, v35 quad_perm:[2,3,0,1] row_mask:0xf bank_mask:0xf bound_ctrl:1
	v_add_f32_dpp v66, v67, v67 quad_perm:[2,3,0,1] row_mask:0xf bank_mask:0xf bound_ctrl:1
	v_pk_fma_f32 v[12:13], v[36:37], v[16:17], v[12:13] op_sel_hi:[0,1,1]
	v_add_f32_dpp v35, v34, v34 row_half_mirror row_mask:0xf bank_mask:0xf bound_ctrl:1
	v_add_f32_dpp v67, v66, v66 row_half_mirror row_mask:0xf bank_mask:0xf bound_ctrl:1
	v_pk_fma_f32 v[14:15], v[36:37], v[18:19], v[14:15] op_sel_hi:[0,1,1]
	v_add_f32_dpp v90, v35, v35 row_mirror row_mask:0xf bank_mask:0xf bound_ctrl:1
	v_add_f32_dpp v66, v67, v67 row_mirror row_mask:0xf bank_mask:0xf bound_ctrl:1
	ds_write_b32 v237, v66 offset:43712
	ds_read_b128 v[64:67], v235 offset:18240
	v_pk_fma_f32 v[20:21], v[90:91], v[24:25], v[12:13] op_sel_hi:[0,1,1] neg_lo:[1,0,0] neg_hi:[1,0,0]
	v_pk_fma_f32 v[22:23], v[90:91], v[26:27], v[14:15] op_sel_hi:[0,1,1] neg_lo:[1,0,0] neg_hi:[1,0,0]
	ds_read_b128 v[12:15], v235 offset:18816
	ds_read_b128 v[24:27], v235 offset:19328
	ds_read_b128 v[16:19], v235 offset:19072
	ds_read_b128 v[32:35], v235 offset:19840
	ds_read_b32 v36, v236 offset:20096
	s_waitcnt lgkmcnt(7)
	v_pk_mul_f32 v[94:95], v[20:21], v[94:95]
	v_pk_mul_f32 v[28:29], v[20:21], v[28:29]
	v_pk_fma_f32 v[94:95], v[22:23], v[96:97], v[94:95]
	v_pk_fma_f32 v[28:29], v[22:23], v[30:31], v[28:29]
	v_add_f32_e32 v96, v94, v95
	v_add_f32_e32 v30, v28, v29
	v_pk_fma_f32 v[40:41], v[20:21], v[40:41], v[20:21] neg_lo:[1,0,0] neg_hi:[1,0,0]
	v_add_f32_dpp v97, v96, v96 quad_perm:[1,0,3,2] row_mask:0xf bank_mask:0xf bound_ctrl:1
	v_add_f32_dpp v31, v30, v30 quad_perm:[1,0,3,2] row_mask:0xf bank_mask:0xf bound_ctrl:1
	v_pk_fma_f32 v[42:43], v[22:23], v[42:43], v[22:23] neg_lo:[1,0,0] neg_hi:[1,0,0]
	v_add_f32_dpp v96, v97, v97 quad_perm:[2,3,0,1] row_mask:0xf bank_mask:0xf bound_ctrl:1
	v_add_f32_dpp v30, v31, v31 quad_perm:[2,3,0,1] row_mask:0xf bank_mask:0xf bound_ctrl:1
	v_pk_fma_f32 v[40:41], v[38:39], v[44:45], v[40:41] op_sel_hi:[0,1,1]
	v_add_f32_dpp v97, v96, v96 row_half_mirror row_mask:0xf bank_mask:0xf bound_ctrl:1
	v_add_f32_dpp v31, v30, v30 row_half_mirror row_mask:0xf bank_mask:0xf bound_ctrl:1
	v_pk_fma_f32 v[42:43], v[38:39], v[46:47], v[42:43] op_sel_hi:[0,1,1]
	v_add_f32_dpp v90, v97, v97 row_mirror row_mask:0xf bank_mask:0xf bound_ctrl:1
	v_add_f32_dpp v30, v31, v31 row_mirror row_mask:0xf bank_mask:0xf bound_ctrl:1
	ds_write_b32 v237, v30 offset:43776
	ds_read_b128 v[28:31], v235 offset:19584
	v_pk_fma_f32 v[20:21], v[90:91], v[60:61], v[40:41] op_sel_hi:[0,1,1] neg_lo:[1,0,0] neg_hi:[1,0,0]
	v_pk_fma_f32 v[22:23], v[90:91], v[62:63], v[42:43] op_sel_hi:[0,1,1] neg_lo:[1,0,0] neg_hi:[1,0,0]
	ds_read_b128 v[40:43], v235 offset:20160
	ds_read_b128 v[60:63], v235 offset:20672
	ds_read_b128 v[44:47], v235 offset:20416
	ds_read_b128 v[94:97], v235 offset:21184
	ds_read_b32 v38, v236 offset:21440
	s_waitcnt lgkmcnt(7)
	v_pk_mul_f32 v[32:33], v[20:21], v[32:33]
	v_pk_mul_f32 v[64:65], v[20:21], v[64:65]
	v_pk_fma_f32 v[32:33], v[22:23], v[34:35], v[32:33]
	v_pk_fma_f32 v[64:65], v[22:23], v[66:67], v[64:65]
	v_add_f32_e32 v34, v32, v33
	v_add_f32_e32 v66, v64, v65
	v_pk_fma_f32 v[12:13], v[20:21], v[12:13], v[20:21] neg_lo:[1,0,0] neg_hi:[1,0,0]
	v_add_f32_dpp v35, v34, v34 quad_perm:[1,0,3,2] row_mask:0xf bank_mask:0xf bound_ctrl:1
	v_add_f32_dpp v67, v66, v66 quad_perm:[1,0,3,2] row_mask:0xf bank_mask:0xf bound_ctrl:1
	v_pk_fma_f32 v[14:15], v[22:23], v[14:15], v[22:23] neg_lo:[1,0,0] neg_hi:[1,0,0]
	v_add_f32_dpp v34, v35, v35 quad_perm:[2,3,0,1] row_mask:0xf bank_mask:0xf bound_ctrl:1
	v_add_f32_dpp v66, v67, v67 quad_perm:[2,3,0,1] row_mask:0xf bank_mask:0xf bound_ctrl:1
	v_pk_fma_f32 v[12:13], v[36:37], v[16:17], v[12:13] op_sel_hi:[0,1,1]
	v_add_f32_dpp v35, v34, v34 row_half_mirror row_mask:0xf bank_mask:0xf bound_ctrl:1
	v_add_f32_dpp v67, v66, v66 row_half_mirror row_mask:0xf bank_mask:0xf bound_ctrl:1
	v_pk_fma_f32 v[14:15], v[36:37], v[18:19], v[14:15] op_sel_hi:[0,1,1]
	v_add_f32_dpp v90, v35, v35 row_mirror row_mask:0xf bank_mask:0xf bound_ctrl:1
	v_add_f32_dpp v66, v67, v67 row_mirror row_mask:0xf bank_mask:0xf bound_ctrl:1
	ds_write_b32 v237, v66 offset:43840
	ds_read_b128 v[64:67], v235 offset:20928
	v_pk_fma_f32 v[20:21], v[90:91], v[24:25], v[12:13] op_sel_hi:[0,1,1] neg_lo:[1,0,0] neg_hi:[1,0,0]
	v_pk_fma_f32 v[22:23], v[90:91], v[26:27], v[14:15] op_sel_hi:[0,1,1] neg_lo:[1,0,0] neg_hi:[1,0,0]
	s_waitcnt lgkmcnt(2)
; #define DPP_ADD(v, ctrl) ((v) + __builtin_bit_cast(float, __builtin_amdgcn_update_dpp(0, __builtin_bit_cast(int, (v)), (ctrl), 0xf, 0xf, true)))
; __device__ __forceinline__ void rwkv_scan_unit(const Params& p, int unit, char* smem) {
;     ...
;         for (int u = 0; u < SCH; ++u) {
;             f32x4 ne = e4, nkd = kd4, nka = ka4, nr = r4, nkk = kk4; float nv = vv;
;             if (u + 1 < SCH) { const char* q = lb + (u + 1) * STEPB;
;                 ne = *(const f32x4*)(q); nkd = *(const f32x4*)(q + 256); nka = *(const f32x4*)(q + 512); nr = *(const f32x4*)(q + 768); nkk = *(const f32x4*)(q + 1024);
;                 nv = *(const float*)(vb + (u + 1) * STEPB); }
;             const f32x2 v2 = {vv, vv}, c2 = {c, c};
;             const f32x2 tA = __builtin_elementwise_fma(v2, (f32x2){kd4[0], kd4[1]}, __builtin_elementwise_fma(-sA, (f32x2){e4[0], e4[1]}, sA));
;             const f32x2 tB = __builtin_elementwise_fma(v2, (f32x2){kd4[2], kd4[3]}, __builtin_elementwise_fma(-sB, (f32x2){e4[2], e4[3]}, sB));
;             sA = __builtin_elementwise_fma(-c2, (f32x2){ka4[0], ka4[1]}, tA);
;             sB = __builtin_elementwise_fma(-c2, (f32x2){ka4[2], ka4[3]}, tB);
;             const f32x2 yv = __builtin_elementwise_fma(sB, (f32x2){r4[2], r4[3]}, sA * (f32x2){r4[0], r4[1]});
;             float y = yv[0] + yv[1];
;             if (u + 1 < SCH) {
;                 const f32x2 cv = __builtin_elementwise_fma(sB, (f32x2){nkk[2], nkk[3]}, sA * (f32x2){nkk[0], nkk[1]});
;                 float cn = cv[0] + cv[1];
;                 cn = DPP_ADD(cn, 0xB1);  y = DPP_ADD(y, 0xB1);
;                 cn = DPP_ADD(cn, 0x4E);  y = DPP_ADD(y, 0x4E);
;                 cn = DPP_ADD(cn, 0x141); y = DPP_ADD(y, 0x141);
;                 cn = DPP_ADD(cn, 0x140); y = DPP_ADD(y, 0x140);
;                 c = cn;
;             } else y = red16(y);
;             if (ks == 0) yl[u * 16] = y;
;             e4 = ne; kd4 = nkd; ka4 = nka; r4 = nr; kk4 = nkk; vv = nv;
;         }
;         s0 = sA[0]; s1 = sA[1]; s2 = sB[0]; s3 = sB[1];
;         __builtin_amdgcn_sched_barrier(0);
;         if (ci + 1 < NCH) { SC_LSTORE(((ci + 1) & 1) * STG) }
;         __syncthreads();
;         {
;             const int u = tid >> 4, r = tid & 15;
;             Yb[((size_t)b * TT + step_tok(ci * SCH + u, d)) * 1024 + r] = f2bf(*((const float*)(smem + YOFF + (ci & 1) * 1024) + u * 16 + r));
;         }
	v_pk_mul_f32 v[94:95], v[20:21], v[94:95]
	v_pk_mul_f32 v[28:29], v[20:21], v[28:29]
	v_pk_fma_f32 v[94:95], v[22:23], v[96:97], v[94:95]
	v_pk_fma_f32 v[28:29], v[22:23], v[30:31], v[28:29]
	v_add_f32_e32 v96, v94, v95
	v_add_f32_e32 v30, v28, v29
	v_pk_fma_f32 v[40:41], v[20:21], v[40:41], v[20:21] neg_lo:[1,0,0] neg_hi:[1,0,0]
	v_add_f32_dpp v97, v96, v96 quad_perm:[1,0,3,2] row_mask:0xf bank_mask:0xf bound_ctrl:1
	v_add_f32_dpp v31, v30, v30 quad_perm:[1,0,3,2] row_mask:0xf bank_mask:0xf bound_ctrl:1
	v_pk_fma_f32 v[42:43], v[22:23], v[42:43], v[22:23] neg_lo:[1,0,0] neg_hi:[1,0,0]
	v_add_f32_dpp v96, v97, v97 quad_perm:[2,3,0,1] row_mask:0xf bank_mask:0xf bound_ctrl:1
	v_add_f32_dpp v30, v31, v31 quad_perm:[2,3,0,1] row_mask:0xf bank_mask:0xf bound_ctrl:1
	v_pk_fma_f32 v[40:41], v[38:39], v[44:45], v[40:41] op_sel_hi:[0,1,1]
	v_add_f32_dpp v97, v96, v96 row_half_mirror row_mask:0xf bank_mask:0xf bound_ctrl:1
	v_add_f32_dpp v31, v30, v30 row_half_mirror row_mask:0xf bank_mask:0xf bound_ctrl:1
	v_pk_fma_f32 v[42:43], v[38:39], v[46:47], v[42:43] op_sel_hi:[0,1,1]
	v_add_f32_dpp v90, v97, v97 row_mirror row_mask:0xf bank_mask:0xf bound_ctrl:1
	v_add_f32_dpp v30, v31, v31 row_mirror row_mask:0xf bank_mask:0xf bound_ctrl:1
	ds_write_b32 v237, v30 offset:43904
	v_pk_fma_f32 v[20:21], v[90:91], v[60:61], v[40:41] op_sel_hi:[0,1,1] neg_lo:[1,0,0] neg_hi:[1,0,0]
	v_pk_fma_f32 v[22:23], v[90:91], v[62:63], v[42:43] op_sel_hi:[0,1,1] neg_lo:[1,0,0] neg_hi:[1,0,0]
	s_waitcnt lgkmcnt(1)
	v_pk_mul_f32 v[64:65], v[20:21], v[64:65]
	v_pk_fma_f32 v[64:65], v[22:23], v[66:67], v[64:65]
	s_nop 0
	v_add_f32_e32 v66, v64, v65
	s_nop 1
	v_add_f32_dpp v67, v66, v66 quad_perm:[1,0,3,2] row_mask:0xf bank_mask:0xf bound_ctrl:1
	s_nop 1
	v_add_f32_dpp v66, v67, v67 quad_perm:[2,3,0,1] row_mask:0xf bank_mask:0xf bound_ctrl:1
	s_nop 1
	v_add_f32_dpp v67, v66, v66 row_half_mirror row_mask:0xf bank_mask:0xf bound_ctrl:1
	s_nop 1
	v_add_f32_dpp v66, v67, v67 row_mirror row_mask:0xf bank_mask:0xf bound_ctrl:1
	ds_write_b32 v237, v66 offset:43968
	s_waitcnt vmcnt(12)
	v_cvt_f32_f16_sdwa v13, v140 dst_sel:DWORD dst_unused:UNUSED_PAD src0_sel:WORD_1
	v_cvt_f32_f16_e32 v12, v140
	v_cvt_f32_f16_sdwa v15, v141 dst_sel:DWORD dst_unused:UNUSED_PAD src0_sel:WORD_1
	v_cvt_f32_f16_e32 v14, v141
	ds_write_b128 v238, v[12:15]
	v_cvt_f32_f16_sdwa v13, v142 dst_sel:DWORD dst_unused:UNUSED_PAD src0_sel:WORD_1
	v_cvt_f32_f16_e32 v12, v142
	v_cvt_f32_f16_sdwa v15, v143 dst_sel:DWORD dst_unused:UNUSED_PAD src0_sel:WORD_1
	v_cvt_f32_f16_e32 v14, v143
	ds_write_b128 v238, v[12:15] offset:16
	v_cvt_f32_f16_sdwa v13, v144 dst_sel:DWORD dst_unused:UNUSED_PAD src0_sel:WORD_1
	v_cvt_f32_f16_e32 v12, v144
	v_cvt_f32_f16_sdwa v15, v145 dst_sel:DWORD dst_unused:UNUSED_PAD src0_sel:WORD_1
	v_cvt_f32_f16_e32 v14, v145
	ds_write_b128 v239, v[12:15]
	v_cvt_f32_f16_sdwa v13, v146 dst_sel:DWORD dst_unused:UNUSED_PAD src0_sel:WORD_1
	v_cvt_f32_f16_e32 v12, v146
	v_cvt_f32_f16_sdwa v15, v147 dst_sel:DWORD dst_unused:UNUSED_PAD src0_sel:WORD_1
	v_cvt_f32_f16_e32 v14, v147
	ds_write_b128 v239, v[12:15] offset:16
	v_cvt_f32_f16_sdwa v13, v148 dst_sel:DWORD dst_unused:UNUSED_PAD src0_sel:WORD_1
	v_cvt_f32_f16_e32 v12, v148
	v_cvt_f32_f16_sdwa v15, v149 dst_sel:DWORD dst_unused:UNUSED_PAD src0_sel:WORD_1
	v_cvt_f32_f16_e32 v14, v149
	ds_write_b128 v240, v[12:15]
	v_cvt_f32_f16_sdwa v13, v150 dst_sel:DWORD dst_unused:UNUSED_PAD src0_sel:WORD_1
	v_cvt_f32_f16_e32 v12, v150
	v_cvt_f32_f16_sdwa v15, v151 dst_sel:DWORD dst_unused:UNUSED_PAD src0_sel:WORD_1
	v_cvt_f32_f16_e32 v14, v151
	ds_write_b128 v240, v[12:15] offset:16
.Lsc_p1_flush:
	s_waitcnt lgkmcnt(0)
	s_barrier
	ds_read_b32 v12, v209 offset:43008
	s_cmpk_ge_u32 s55, 0x100
	s_movk_i32 s98, 0xff
	s_movk_i32 s99, 0x11ff
	s_cselect_b32 s98, s99, s98
	s_sub_u32 s98, s98, s55
	s_cmp_lg_u64 s[44:45], 0
	s_cselect_b32 s98, s55, s98
	s_lshl_b32 s98, s98, 11
	s_mov_b32 s99, 0
	s_movk_i32 s0, 0x7fff
	s_add_i32 s55, s55, 16
	s_waitcnt lgkmcnt(0)
	v_bfe_u32 v14, v12, 16, 1
	v_add3_u32 v14, v12, v14, s0
	v_lshl_add_u64 v[12:13], v[210:211], 0, s[98:99]
	s_add_i32 s64, s64, 1
	s_cmpk_lg_i32 s55, 0x1100
	global_store_short_d16_hi v[12:13], v14, off

; __device__ __forceinline__ void rwkv_scan_unit(const Params& p, int unit, char* smem) {
;     ...
;         const char* lb = smem + st + ks * 16;
;         const char* vb = smem + st + 1280 + rl * 4;
;         float* yl = (float*)(smem + YOFF + (ci & 1) * 1024) + rl;
;         f32x4 e4 = *(const f32x4*)(lb), kd4 = *(const f32x4*)(lb + 256), ka4 = *(const f32x4*)(lb + 512), r4 = *(const f32x4*)(lb + 768), kk4 = *(const f32x4*)(lb + 1024);
;         float vv = *(const float*)vb;
;         f32x2 sA = {s0, s1}, sB = {s2, s3};
;         float c;
;         { const f32x2 cv = sA * (f32x2){kk4[0], kk4[1]} + sB * (f32x2){kk4[2], kk4[3]}; c = red16(cv[0] + cv[1]); }
; #pragma unroll
;         for (int u = 0; u < SCH; ++u) {
;             f32x4 ne = e4, nkd = kd4, nka = ka4, nr = r4, nkk = kk4; float nv = vv;
;             if (u + 1 < SCH) { const char* q = lb + (u + 1) * STEPB;
;                 ne = *(const f32x4*)(q); nkd = *(const f32x4*)(q + 256); nka = *(const f32x4*)(q + 512); nr = *(const f32x4*)(q + 768); nkk = *(const f32x4*)(q + 1024);
;                 nv = *(const float*)(vb + (u + 1) * STEPB); }
;             const f32x2 v2 = {vv, vv}, c2 = {c, c};
;             const f32x2 tA = __builtin_elementwise_fma(v2, (f32x2){kd4[0], kd4[1]}, __builtin_elementwise_fma(-sA, (f32x2){e4[0], e4[1]}, sA));
;             const f32x2 tB = __builtin_elementwise_fma(v2, (f32x2){kd4[2], kd4[3]}, __builtin_elementwise_fma(-sB, (f32x2){e4[2], e4[3]}, sB));
;             sA = __builtin_elementwise_fma(-c2, (f32x2){ka4[0], ka4[1]}, tA);
;             sB = __builtin_elementwise_fma(-c2, (f32x2){ka4[2], ka4[3]}, tB);
;             const f32x2 yv = __builtin_elementwise_fma(sB, (f32x2){r4[2], r4[3]}, sA * (f32x2){r4[0], r4[1]});
;             float y = yv[0] + yv[1];
;             if (u + 1 < SCH) {
;                 const f32x2 cv = __builtin_elementwise_fma(sB, (f32x2){nkk[2], nkk[3]}, sA * (f32x2){nkk[0], nkk[1]});
;                 float cn = cv[0] + cv[1];
;                 cn = DPP_ADD(cn, 0xB1);  y = DPP_ADD(y, 0xB1);
;                 cn = DPP_ADD(cn, 0x4E);  y = DPP_ADD(y, 0x4E);
;                 cn = DPP_ADD(cn, 0x141); y = DPP_ADD(y, 0x141);
;                 cn = DPP_ADD(cn, 0x140); y = DPP_ADD(y, 0x140);
;                 c = cn;
;             } else y = red16(y);
;             if (ks == 0) yl[u * 16] = y;
.Lsc_p2_body:
	s_add_i32 s30, s64, -1
	s_and_b32 s30, s30, 1
	ds_read_b128 v[32:35], v232 offset:1024
	ds_read_b128 v[12:15], v232 offset:0
	ds_read_b128 v[16:19], v232 offset:256
	ds_read_b32 v36, v233 offset:1280
	ds_read_b128 v[24:27], v232 offset:512
	ds_read_b128 v[28:31], v232 offset:768
	ds_read_b128 v[40:43], v232 offset:1344
	ds_read_b128 v[60:63], v232 offset:1856
	ds_read_b128 v[44:47], v232 offset:1600
	ds_read_b128 v[94:97], v232 offset:2368
	ds_read_b32 v38, v233 offset:2624
	ds_read_b128 v[64:67], v232 offset:2112
	s_lshl_b32 s52, s30, 10
	s_waitcnt lgkmcnt(11)
	v_pk_mul_f32 v[32:33], v[20:21], v[32:33]
	s_waitcnt lgkmcnt(10)
	v_pk_fma_f32 v[12:13], v[20:21], v[12:13], v[20:21] neg_lo:[1,0,0] neg_hi:[1,0,0]
	v_pk_fma_f32 v[32:33], v[22:23], v[34:35], v[32:33]
	v_pk_fma_f32 v[14:15], v[22:23], v[14:15], v[22:23] neg_lo:[1,0,0] neg_hi:[1,0,0]
	v_add_f32_e32 v34, v32, v33
	s_waitcnt lgkmcnt(8)
	v_pk_fma_f32 v[12:13], v[36:37], v[16:17], v[12:13] op_sel_hi:[0,1,1]
	v_pk_fma_f32 v[14:15], v[36:37], v[18:19], v[14:15] op_sel_hi:[0,1,1]
	v_add_f32_dpp v35, v34, v34 quad_perm:[1,0,3,2] row_mask:0xf bank_mask:0xf bound_ctrl:1
	s_nop 1
	v_add_f32_dpp v34, v35, v35 quad_perm:[2,3,0,1] row_mask:0xf bank_mask:0xf bound_ctrl:1
	s_nop 1
	v_add_f32_dpp v35, v34, v34 row_half_mirror row_mask:0xf bank_mask:0xf bound_ctrl:1
	s_nop 1
	v_add_f32_dpp v90, v35, v35 row_mirror row_mask:0xf bank_mask:0xf bound_ctrl:1
	ds_read_b128 v[16:19], v232 offset:2944
	ds_read_b128 v[32:35], v232 offset:3712
	ds_read_b32 v36, v233 offset:3968
	s_waitcnt lgkmcnt(10)
	v_pk_fma_f32 v[20:21], v[90:91], v[24:25], v[12:13] op_sel_hi:[0,1,1] neg_lo:[1,0,0] neg_hi:[1,0,0]
	v_pk_fma_f32 v[22:23], v[90:91], v[26:27], v[14:15] op_sel_hi:[0,1,1] neg_lo:[1,0,0] neg_hi:[1,0,0]
	ds_read_b128 v[12:15], v232 offset:2688
	ds_read_b128 v[24:27], v232 offset:3200
	s_waitcnt lgkmcnt(7)
	v_pk_mul_f32 v[94:95], v[20:21], v[94:95]
	v_pk_mul_f32 v[28:29], v[20:21], v[28:29]
	v_pk_fma_f32 v[94:95], v[22:23], v[96:97], v[94:95]
	v_pk_fma_f32 v[28:29], v[22:23], v[30:31], v[28:29]
	v_add_f32_e32 v96, v94, v95
	v_add_f32_e32 v30, v28, v29
	v_pk_fma_f32 v[40:41], v[20:21], v[40:41], v[20:21] neg_lo:[1,0,0] neg_hi:[1,0,0]
	v_add_f32_dpp v97, v96, v96 quad_perm:[1,0,3,2] row_mask:0xf bank_mask:0xf bound_ctrl:1
	v_add_f32_dpp v31, v30, v30 quad_perm:[1,0,3,2] row_mask:0xf bank_mask:0xf bound_ctrl:1
	v_pk_fma_f32 v[42:43], v[22:23], v[42:43], v[22:23] neg_lo:[1,0,0] neg_hi:[1,0,0]
	v_add_f32_dpp v96, v97, v97 quad_perm:[2,3,0,1] row_mask:0xf bank_mask:0xf bound_ctrl:1
	v_add_f32_dpp v30, v31, v31 quad_perm:[2,3,0,1] row_mask:0xf bank_mask:0xf bound_ctrl:1
	s_waitcnt lgkmcnt(6)
	v_pk_fma_f32 v[40:41], v[38:39], v[44:45], v[40:41] op_sel_hi:[0,1,1]
	v_add_f32_dpp v97, v96, v96 row_half_mirror row_mask:0xf bank_mask:0xf bound_ctrl:1
	v_add_f32_dpp v31, v30, v30 row_half_mirror row_mask:0xf bank_mask:0xf bound_ctrl:1
	v_pk_fma_f32 v[42:43], v[38:39], v[46:47], v[42:43] op_sel_hi:[0,1,1]
	v_add_f32_dpp v90, v97, v97 row_mirror row_mask:0xf bank_mask:0xf bound_ctrl:1
	v_add_f32_dpp v30, v31, v31 row_mirror row_mask:0xf bank_mask:0xf bound_ctrl:1
	ds_write_b32 v234, v30 offset:43008
	ds_read_b128 v[28:31], v232 offset:3456
	v_pk_fma_f32 v[20:21], v[90:91], v[60:61], v[40:41] op_sel_hi:[0,1,1] neg_lo:[1,0,0] neg_hi:[1,0,0]
	v_pk_fma_f32 v[22:23], v[90:91], v[62:63], v[42:43] op_sel_hi:[0,1,1] neg_lo:[1,0,0] neg_hi:[1,0,0]
	ds_read_b128 v[40:43], v232 offset:4032
	ds_read_b128 v[60:63], v232 offset:4544
	ds_read_b128 v[44:47], v232 offset:4288
	ds_read_b128 v[94:97], v232 offset:5056
	ds_read_b32 v38, v233 offset:5312
	s_waitcnt lgkmcnt(8)
	v_pk_mul_f32 v[32:33], v[20:21], v[32:33]
	v_pk_mul_f32 v[64:65], v[20:21], v[64:65]
	v_pk_fma_f32 v[32:33], v[22:23], v[34:35], v[32:33]
	v_pk_fma_f32 v[64:65], v[22:23], v[66:67], v[64:65]
	v_add_f32_e32 v34, v32, v33
	v_add_f32_e32 v66, v64, v65
	v_pk_fma_f32 v[12:13], v[20:21], v[12:13], v[20:21] neg_lo:[1,0,0] neg_hi:[1,0,0]
	v_add_f32_dpp v35, v34, v34 quad_perm:[1,0,3,2] row_mask:0xf bank_mask:0xf bound_ctrl:1
	v_add_f32_dpp v67, v66, v66 quad_perm:[1,0,3,2] row_mask:0xf bank_mask:0xf bound_ctrl:1
	v_pk_fma_f32 v[14:15], v[22:23], v[14:15], v[22:23] neg_lo:[1,0,0] neg_hi:[1,0,0]
	v_add_f32_dpp v34, v35, v35 quad_perm:[2,3,0,1] row_mask:0xf bank_mask:0xf bound_ctrl:1
	v_add_f32_dpp v66, v67, v67 quad_perm:[2,3,0,1] row_mask:0xf bank_mask:0xf bound_ctrl:1
	v_pk_fma_f32 v[12:13], v[36:37], v[16:17], v[12:13] op_sel_hi:[0,1,1]
	v_add_f32_dpp v35, v34, v34 row_half_mirror row_mask:0xf bank_mask:0xf bound_ctrl:1
	v_add_f32_dpp v67, v66, v66 row_half_mirror row_mask:0xf bank_mask:0xf bound_ctrl:1
	v_pk_fma_f32 v[14:15], v[36:37], v[18:19], v[14:15] op_sel_hi:[0,1,1]
	v_add_f32_dpp v90, v35, v35 row_mirror row_mask:0xf bank_mask:0xf bound_ctrl:1
	v_add_f32_dpp v66, v67, v67 row_mirror row_mask:0xf bank_mask:0xf bound_ctrl:1
	ds_write_b32 v234, v66 offset:43072
	ds_read_b128 v[64:67], v232 offset:4800
	s_waitcnt lgkmcnt(9)
	v_pk_fma_f32 v[20:21], v[90:91], v[24:25], v[12:13] op_sel_hi:[0,1,1] neg_lo:[1,0,0] neg_hi:[1,0,0]
	v_pk_fma_f32 v[22:23], v[90:91], v[26:27], v[14:15] op_sel_hi:[0,1,1] neg_lo:[1,0,0] neg_hi:[1,0,0]
	ds_read_b128 v[12:15], v232 offset:5376
	ds_read_b128 v[24:27], v232 offset:5888
	ds_read_b128 v[16:19], v232 offset:5632
	ds_read_b128 v[32:35], v232 offset:6400
	ds_read_b32 v36, v233 offset:6656
	s_waitcnt lgkmcnt(7)
; #define DPP_ADD(v, ctrl) ((v) + __builtin_bit_cast(float, __builtin_amdgcn_update_dpp(0, __builtin_bit_cast(int, (v)), (ctrl), 0xf, 0xf, true)))
; __device__ __forceinline__ void rwkv_scan_unit(const Params& p, int unit, char* smem) {
;     ...
;         for (int u = 0; u < SCH; ++u) {
;             f32x4 ne = e4, nkd = kd4, nka = ka4, nr = r4, nkk = kk4; float nv = vv;
;             if (u + 1 < SCH) { const char* q = lb + (u + 1) * STEPB;
;                 ne = *(const f32x4*)(q); nkd = *(const f32x4*)(q + 256); nka = *(const f32x4*)(q + 512); nr = *(const f32x4*)(q + 768); nkk = *(const f32x4*)(q + 1024);
;                 nv = *(const float*)(vb + (u + 1) * STEPB); }
;             const f32x2 v2 = {vv, vv}, c2 = {c, c};
;             const f32x2 tA = __builtin_elementwise_fma(v2, (f32x2){kd4[0], kd4[1]}, __builtin_elementwise_fma(-sA, (f32x2){e4[0], e4[1]}, sA));
;             const f32x2 tB = __builtin_elementwise_fma(v2, (f32x2){kd4[2], kd4[3]}, __builtin_elementwise_fma(-sB, (f32x2){e4[2], e4[3]}, sB));
;             sA = __builtin_elementwise_fma(-c2, (f32x2){ka4[0], ka4[1]}, tA);
;             sB = __builtin_elementwise_fma(-c2, (f32x2){ka4[2], ka4[3]}, tB);
;             const f32x2 yv = __builtin_elementwise_fma(sB, (f32x2){r4[2], r4[3]}, sA * (f32x2){r4[0], r4[1]});
;             float y = yv[0] + yv[1];
;             if (u + 1 < SCH) {
;                 const f32x2 cv = __builtin_elementwise_fma(sB, (f32x2){nkk[2], nkk[3]}, sA * (f32x2){nkk[0], nkk[1]});
;                 float cn = cv[0] + cv[1];
;                 cn = DPP_ADD(cn, 0xB1);  y = DPP_ADD(y, 0xB1);
;                 cn = DPP_ADD(cn, 0x4E);  y = DPP_ADD(y, 0x4E);
;                 cn = DPP_ADD(cn, 0x141); y = DPP_ADD(y, 0x141);
;                 cn = DPP_ADD(cn, 0x140); y = DPP_ADD(y, 0x140);
;                 c = cn;
;             } else y = red16(y);
;             if (ks == 0) yl[u * 16] = y;
;             e4 = ne; kd4 = nkd; ka4 = nka; r4 = nr; kk4 = nkk; vv = nv;
;         }
	v_pk_mul_f32 v[94:95], v[20:21], v[94:95]
	v_pk_mul_f32 v[28:29], v[20:21], v[28:29]
	v_pk_fma_f32 v[94:95], v[22:23], v[96:97], v[94:95]
	v_pk_fma_f32 v[28:29], v[22:23], v[30:31], v[28:29]
	v_add_f32_e32 v96, v94, v95
	v_add_f32_e32 v30, v28, v29
	v_pk_fma_f32 v[40:41], v[20:21], v[40:41], v[20:21] neg_lo:[1,0,0] neg_hi:[1,0,0]
	v_add_f32_dpp v97, v96, v96 quad_perm:[1,0,3,2] row_mask:0xf bank_mask:0xf bound_ctrl:1
	v_add_f32_dpp v31, v30, v30 quad_perm:[1,0,3,2] row_mask:0xf bank_mask:0xf bound_ctrl:1
	v_pk_fma_f32 v[42:43], v[22:23], v[42:43], v[22:23] neg_lo:[1,0,0] neg_hi:[1,0,0]
	v_add_f32_dpp v96, v97, v97 quad_perm:[2,3,0,1] row_mask:0xf bank_mask:0xf bound_ctrl:1
	v_add_f32_dpp v30, v31, v31 quad_perm:[2,3,0,1] row_mask:0xf bank_mask:0xf bound_ctrl:1
	v_pk_fma_f32 v[40:41], v[38:39], v[44:45], v[40:41] op_sel_hi:[0,1,1]
	v_add_f32_dpp v97, v96, v96 row_half_mirror row_mask:0xf bank_mask:0xf bound_ctrl:1
	v_add_f32_dpp v31, v30, v30 row_half_mirror row_mask:0xf bank_mask:0xf bound_ctrl:1
	v_pk_fma_f32 v[42:43], v[38:39], v[46:47], v[42:43] op_sel_hi:[0,1,1]
	v_add_f32_dpp v90, v97, v97 row_mirror row_mask:0xf bank_mask:0xf bound_ctrl:1
	v_add_f32_dpp v30, v31, v31 row_mirror row_mask:0xf bank_mask:0xf bound_ctrl:1
	ds_write_b32 v234, v30 offset:43136
	ds_read_b128 v[28:31], v232 offset:6144
	v_pk_fma_f32 v[20:21], v[90:91], v[60:61], v[40:41] op_sel_hi:[0,1,1] neg_lo:[1,0,0] neg_hi:[1,0,0]
	v_pk_fma_f32 v[22:23], v[90:91], v[62:63], v[42:43] op_sel_hi:[0,1,1] neg_lo:[1,0,0] neg_hi:[1,0,0]
	ds_read_b128 v[40:43], v232 offset:6720
	ds_read_b128 v[60:63], v232 offset:7232
	ds_read_b128 v[44:47], v232 offset:6976
	ds_read_b128 v[94:97], v232 offset:7744
	ds_read_b32 v38, v233 offset:8000
	s_waitcnt lgkmcnt(7)
	v_pk_mul_f32 v[32:33], v[20:21], v[32:33]
	v_pk_mul_f32 v[64:65], v[20:21], v[64:65]
	v_pk_fma_f32 v[32:33], v[22:23], v[34:35], v[32:33]
	v_pk_fma_f32 v[64:65], v[22:23], v[66:67], v[64:65]
	v_add_f32_e32 v34, v32, v33
	v_add_f32_e32 v66, v64, v65
	v_pk_fma_f32 v[12:13], v[20:21], v[12:13], v[20:21] neg_lo:[1,0,0] neg_hi:[1,0,0]
	v_add_f32_dpp v35, v34, v34 quad_perm:[1,0,3,2] row_mask:0xf bank_mask:0xf bound_ctrl:1
	v_add_f32_dpp v67, v66, v66 quad_perm:[1,0,3,2] row_mask:0xf bank_mask:0xf bound_ctrl:1
	v_pk_fma_f32 v[14:15], v[22:23], v[14:15], v[22:23] neg_lo:[1,0,0] neg_hi:[1,0,0]
	v_add_f32_dpp v34, v35, v35 quad_perm:[2,3,0,1] row_mask:0xf bank_mask:0xf bound_ctrl:1
	v_add_f32_dpp v66, v67, v67 quad_perm:[2,3,0,1] row_mask:0xf bank_mask:0xf bound_ctrl:1
	v_pk_fma_f32 v[12:13], v[36:37], v[16:17], v[12:13] op_sel_hi:[0,1,1]
	v_add_f32_dpp v35, v34, v34 row_half_mirror row_mask:0xf bank_mask:0xf bound_ctrl:1
	v_add_f32_dpp v67, v66, v66 row_half_mirror row_mask:0xf bank_mask:0xf bound_ctrl:1
	v_pk_fma_f32 v[14:15], v[36:37], v[18:19], v[14:15] op_sel_hi:[0,1,1]
	v_add_f32_dpp v90, v35, v35 row_mirror row_mask:0xf bank_mask:0xf bound_ctrl:1
	v_add_f32_dpp v66, v67, v67 row_mirror row_mask:0xf bank_mask:0xf bound_ctrl:1
	ds_write_b32 v234, v66 offset:43200
	ds_read_b128 v[64:67], v232 offset:7488
	v_pk_fma_f32 v[20:21], v[90:91], v[24:25], v[12:13] op_sel_hi:[0,1,1] neg_lo:[1,0,0] neg_hi:[1,0,0]
	v_pk_fma_f32 v[22:23], v[90:91], v[26:27], v[14:15] op_sel_hi:[0,1,1] neg_lo:[1,0,0] neg_hi:[1,0,0]
	ds_read_b128 v[12:15], v232 offset:8064
	ds_read_b128 v[24:27], v232 offset:8576
	ds_read_b128 v[16:19], v232 offset:8320
	ds_read_b128 v[32:35], v232 offset:9088
	ds_read_b32 v36, v233 offset:9344
	s_waitcnt lgkmcnt(7)
	v_pk_mul_f32 v[94:95], v[20:21], v[94:95]
	v_pk_mul_f32 v[28:29], v[20:21], v[28:29]
	v_pk_fma_f32 v[94:95], v[22:23], v[96:97], v[94:95]
	v_pk_fma_f32 v[28:29], v[22:23], v[30:31], v[28:29]
	v_add_f32_e32 v96, v94, v95
	v_add_f32_e32 v30, v28, v29
	v_pk_fma_f32 v[40:41], v[20:21], v[40:41], v[20:21] neg_lo:[1,0,0] neg_hi:[1,0,0]
	v_add_f32_dpp v97, v96, v96 quad_perm:[1,0,3,2] row_mask:0xf bank_mask:0xf bound_ctrl:1
	v_add_f32_dpp v31, v30, v30 quad_perm:[1,0,3,2] row_mask:0xf bank_mask:0xf bound_ctrl:1
	v_pk_fma_f32 v[42:43], v[22:23], v[42:43], v[22:23] neg_lo:[1,0,0] neg_hi:[1,0,0]
	v_add_f32_dpp v96, v97, v97 quad_perm:[2,3,0,1] row_mask:0xf bank_mask:0xf bound_ctrl:1
	v_add_f32_dpp v30, v31, v31 quad_perm:[2,3,0,1] row_mask:0xf bank_mask:0xf bound_ctrl:1
	v_pk_fma_f32 v[40:41], v[38:39], v[44:45], v[40:41] op_sel_hi:[0,1,1]
	v_add_f32_dpp v97, v96, v96 row_half_mirror row_mask:0xf bank_mask:0xf bound_ctrl:1
	v_add_f32_dpp v31, v30, v30 row_half_mirror row_mask:0xf bank_mask:0xf bound_ctrl:1
	v_pk_fma_f32 v[42:43], v[38:39], v[46:47], v[42:43] op_sel_hi:[0,1,1]
	v_add_f32_dpp v90, v97, v97 row_mirror row_mask:0xf bank_mask:0xf bound_ctrl:1
	v_add_f32_dpp v30, v31, v31 row_mirror row_mask:0xf bank_mask:0xf bound_ctrl:1
	ds_write_b32 v234, v30 offset:43264
	ds_read_b128 v[28:31], v232 offset:8832
	v_pk_fma_f32 v[20:21], v[90:91], v[60:61], v[40:41] op_sel_hi:[0,1,1] neg_lo:[1,0,0] neg_hi:[1,0,0]
	v_pk_fma_f32 v[22:23], v[90:91], v[62:63], v[42:43] op_sel_hi:[0,1,1] neg_lo:[1,0,0] neg_hi:[1,0,0]
	ds_read_b128 v[40:43], v232 offset:9408
	ds_read_b128 v[60:63], v232 offset:9920
	ds_read_b128 v[44:47], v232 offset:9664
	ds_read_b128 v[94:97], v232 offset:10432
	ds_read_b32 v38, v233 offset:10688
	s_waitcnt lgkmcnt(7)
; #define DPP_ADD(v, ctrl) ((v) + __builtin_bit_cast(float, __builtin_amdgcn_update_dpp(0, __builtin_bit_cast(int, (v)), (ctrl), 0xf, 0xf, true)))
; __device__ __forceinline__ void rwkv_scan_unit(const Params& p, int unit, char* smem) {
;     ...
;         for (int u = 0; u < SCH; ++u) {
;             f32x4 ne = e4, nkd = kd4, nka = ka4, nr = r4, nkk = kk4; float nv = vv;
;             if (u + 1 < SCH) { const char* q = lb + (u + 1) * STEPB;
;                 ne = *(const f32x4*)(q); nkd = *(const f32x4*)(q + 256); nka = *(const f32x4*)(q + 512); nr = *(const f32x4*)(q + 768); nkk = *(const f32x4*)(q + 1024);
;                 nv = *(const float*)(vb + (u + 1) * STEPB); }
;             const f32x2 v2 = {vv, vv}, c2 = {c, c};
;             const f32x2 tA = __builtin_elementwise_fma(v2, (f32x2){kd4[0], kd4[1]}, __builtin_elementwise_fma(-sA, (f32x2){e4[0], e4[1]}, sA));
;             const f32x2 tB = __builtin_elementwise_fma(v2, (f32x2){kd4[2], kd4[3]}, __builtin_elementwise_fma(-sB, (f32x2){e4[2], e4[3]}, sB));
;             sA = __builtin_elementwise_fma(-c2, (f32x2){ka4[0], ka4[1]}, tA);
;             sB = __builtin_elementwise_fma(-c2, (f32x2){ka4[2], ka4[3]}, tB);
;             const f32x2 yv = __builtin_elementwise_fma(sB, (f32x2){r4[2], r4[3]}, sA * (f32x2){r4[0], r4[1]});
;             float y = yv[0] + yv[1];
;             if (u + 1 < SCH) {
;                 const f32x2 cv = __builtin_elementwise_fma(sB, (f32x2){nkk[2], nkk[3]}, sA * (f32x2){nkk[0], nkk[1]});
;                 float cn = cv[0] + cv[1];
;                 cn = DPP_ADD(cn, 0xB1);  y = DPP_ADD(y, 0xB1);
;                 cn = DPP_ADD(cn, 0x4E);  y = DPP_ADD(y, 0x4E);
;                 cn = DPP_ADD(cn, 0x141); y = DPP_ADD(y, 0x141);
;                 cn = DPP_ADD(cn, 0x140); y = DPP_ADD(y, 0x140);
;                 c = cn;
;             } else y = red16(y);
;             if (ks == 0) yl[u * 16] = y;
;             e4 = ne; kd4 = nkd; ka4 = nka; r4 = nr; kk4 = nkk; vv = nv;
;         }
	v_pk_mul_f32 v[32:33], v[20:21], v[32:33]
	v_pk_mul_f32 v[64:65], v[20:21], v[64:65]
	v_pk_fma_f32 v[32:33], v[22:23], v[34:35], v[32:33]
	v_pk_fma_f32 v[64:65], v[22:23], v[66:67], v[64:65]
	v_add_f32_e32 v34, v32, v33
	v_add_f32_e32 v66, v64, v65
	v_pk_fma_f32 v[12:13], v[20:21], v[12:13], v[20:21] neg_lo:[1,0,0] neg_hi:[1,0,0]
	v_add_f32_dpp v35, v34, v34 quad_perm:[1,0,3,2] row_mask:0xf bank_mask:0xf bound_ctrl:1
	v_add_f32_dpp v67, v66, v66 quad_perm:[1,0,3,2] row_mask:0xf bank_mask:0xf bound_ctrl:1
	v_pk_fma_f32 v[14:15], v[22:23], v[14:15], v[22:23] neg_lo:[1,0,0] neg_hi:[1,0,0]
	v_add_f32_dpp v34, v35, v35 quad_perm:[2,3,0,1] row_mask:0xf bank_mask:0xf bound_ctrl:1
	v_add_f32_dpp v66, v67, v67 quad_perm:[2,3,0,1] row_mask:0xf bank_mask:0xf bound_ctrl:1
	v_pk_fma_f32 v[12:13], v[36:37], v[16:17], v[12:13] op_sel_hi:[0,1,1]
	v_add_f32_dpp v35, v34, v34 row_half_mirror row_mask:0xf bank_mask:0xf bound_ctrl:1
	v_add_f32_dpp v67, v66, v66 row_half_mirror row_mask:0xf bank_mask:0xf bound_ctrl:1
	v_pk_fma_f32 v[14:15], v[36:37], v[18:19], v[14:15] op_sel_hi:[0,1,1]
	v_add_f32_dpp v90, v35, v35 row_mirror row_mask:0xf bank_mask:0xf bound_ctrl:1
	v_add_f32_dpp v66, v67, v67 row_mirror row_mask:0xf bank_mask:0xf bound_ctrl:1
	ds_write_b32 v234, v66 offset:43328
	ds_read_b128 v[64:67], v232 offset:10176
	v_pk_fma_f32 v[20:21], v[90:91], v[24:25], v[12:13] op_sel_hi:[0,1,1] neg_lo:[1,0,0] neg_hi:[1,0,0]
	v_pk_fma_f32 v[22:23], v[90:91], v[26:27], v[14:15] op_sel_hi:[0,1,1] neg_lo:[1,0,0] neg_hi:[1,0,0]
	ds_read_b128 v[12:15], v232 offset:10752
	ds_read_b128 v[24:27], v232 offset:11264
	ds_read_b128 v[16:19], v232 offset:11008
	ds_read_b128 v[32:35], v232 offset:11776
	ds_read_b32 v36, v233 offset:12032
	s_waitcnt lgkmcnt(7)
	v_pk_mul_f32 v[94:95], v[20:21], v[94:95]
	v_pk_mul_f32 v[28:29], v[20:21], v[28:29]
	v_pk_fma_f32 v[94:95], v[22:23], v[96:97], v[94:95]
	v_pk_fma_f32 v[28:29], v[22:23], v[30:31], v[28:29]
	v_add_f32_e32 v96, v94, v95
	v_add_f32_e32 v30, v28, v29
	v_pk_fma_f32 v[40:41], v[20:21], v[40:41], v[20:21] neg_lo:[1,0,0] neg_hi:[1,0,0]
	v_add_f32_dpp v97, v96, v96 quad_perm:[1,0,3,2] row_mask:0xf bank_mask:0xf bound_ctrl:1
	v_add_f32_dpp v31, v30, v30 quad_perm:[1,0,3,2] row_mask:0xf bank_mask:0xf bound_ctrl:1
	v_pk_fma_f32 v[42:43], v[22:23], v[42:43], v[22:23] neg_lo:[1,0,0] neg_hi:[1,0,0]
	v_add_f32_dpp v96, v97, v97 quad_perm:[2,3,0,1] row_mask:0xf bank_mask:0xf bound_ctrl:1
	v_add_f32_dpp v30, v31, v31 quad_perm:[2,3,0,1] row_mask:0xf bank_mask:0xf bound_ctrl:1
	v_pk_fma_f32 v[40:41], v[38:39], v[44:45], v[40:41] op_sel_hi:[0,1,1]
	v_add_f32_dpp v97, v96, v96 row_half_mirror row_mask:0xf bank_mask:0xf bound_ctrl:1
	v_add_f32_dpp v31, v30, v30 row_half_mirror row_mask:0xf bank_mask:0xf bound_ctrl:1
	v_pk_fma_f32 v[42:43], v[38:39], v[46:47], v[42:43] op_sel_hi:[0,1,1]
	v_add_f32_dpp v90, v97, v97 row_mirror row_mask:0xf bank_mask:0xf bound_ctrl:1
	v_add_f32_dpp v30, v31, v31 row_mirror row_mask:0xf bank_mask:0xf bound_ctrl:1
	ds_write_b32 v234, v30 offset:43392
	ds_read_b128 v[28:31], v232 offset:11520
	v_pk_fma_f32 v[20:21], v[90:91], v[60:61], v[40:41] op_sel_hi:[0,1,1] neg_lo:[1,0,0] neg_hi:[1,0,0]
	v_pk_fma_f32 v[22:23], v[90:91], v[62:63], v[42:43] op_sel_hi:[0,1,1] neg_lo:[1,0,0] neg_hi:[1,0,0]
	ds_read_b128 v[40:43], v232 offset:12096
	ds_read_b128 v[60:63], v232 offset:12608
	ds_read_b128 v[44:47], v232 offset:12352
	ds_read_b128 v[94:97], v232 offset:13120
	ds_read_b32 v38, v233 offset:13376
	s_waitcnt lgkmcnt(7)
	v_pk_mul_f32 v[32:33], v[20:21], v[32:33]
	v_pk_mul_f32 v[64:65], v[20:21], v[64:65]
	v_pk_fma_f32 v[32:33], v[22:23], v[34:35], v[32:33]
	v_pk_fma_f32 v[64:65], v[22:23], v[66:67], v[64:65]
	v_add_f32_e32 v34, v32, v33
	v_add_f32_e32 v66, v64, v65
	v_pk_fma_f32 v[12:13], v[20:21], v[12:13], v[20:21] neg_lo:[1,0,0] neg_hi:[1,0,0]
	v_add_f32_dpp v35, v34, v34 quad_perm:[1,0,3,2] row_mask:0xf bank_mask:0xf bound_ctrl:1
	v_add_f32_dpp v67, v66, v66 quad_perm:[1,0,3,2] row_mask:0xf bank_mask:0xf bound_ctrl:1
	v_pk_fma_f32 v[14:15], v[22:23], v[14:15], v[22:23] neg_lo:[1,0,0] neg_hi:[1,0,0]
	v_add_f32_dpp v34, v35, v35 quad_perm:[2,3,0,1] row_mask:0xf bank_mask:0xf bound_ctrl:1
	v_add_f32_dpp v66, v67, v67 quad_perm:[2,3,0,1] row_mask:0xf bank_mask:0xf bound_ctrl:1
	v_pk_fma_f32 v[12:13], v[36:37], v[16:17], v[12:13] op_sel_hi:[0,1,1]
	v_add_f32_dpp v35, v34, v34 row_half_mirror row_mask:0xf bank_mask:0xf bound_ctrl:1
	v_add_f32_dpp v67, v66, v66 row_half_mirror row_mask:0xf bank_mask:0xf bound_ctrl:1
	v_pk_fma_f32 v[14:15], v[36:37], v[18:19], v[14:15] op_sel_hi:[0,1,1]
	v_add_f32_dpp v90, v35, v35 row_mirror row_mask:0xf bank_mask:0xf bound_ctrl:1
	v_add_f32_dpp v66, v67, v67 row_mirror row_mask:0xf bank_mask:0xf bound_ctrl:1
	ds_write_b32 v234, v66 offset:43456
	ds_read_b128 v[64:67], v232 offset:12864
	v_pk_fma_f32 v[20:21], v[90:91], v[24:25], v[12:13] op_sel_hi:[0,1,1] neg_lo:[1,0,0] neg_hi:[1,0,0]
	v_pk_fma_f32 v[22:23], v[90:91], v[26:27], v[14:15] op_sel_hi:[0,1,1] neg_lo:[1,0,0] neg_hi:[1,0,0]
	ds_read_b128 v[12:15], v232 offset:13440
	ds_read_b128 v[24:27], v232 offset:13952
	ds_read_b128 v[16:19], v232 offset:13696
	ds_read_b128 v[32:35], v232 offset:14464
	ds_read_b32 v36, v233 offset:14720
	s_waitcnt lgkmcnt(7)
; #define DPP_ADD(v, ctrl) ((v) + __builtin_bit_cast(float, __builtin_amdgcn_update_dpp(0, __builtin_bit_cast(int, (v)), (ctrl), 0xf, 0xf, true)))
; __device__ __forceinline__ void rwkv_scan_unit(const Params& p, int unit, char* smem) {
;     ...
;         for (int u = 0; u < SCH; ++u) {
;             f32x4 ne = e4, nkd = kd4, nka = ka4, nr = r4, nkk = kk4; float nv = vv;
;             if (u + 1 < SCH) { const char* q = lb + (u + 1) * STEPB;
;                 ne = *(const f32x4*)(q); nkd = *(const f32x4*)(q + 256); nka = *(const f32x4*)(q + 512); nr = *(const f32x4*)(q + 768); nkk = *(const f32x4*)(q + 1024);
;                 nv = *(const float*)(vb + (u + 1) * STEPB); }
;             const f32x2 v2 = {vv, vv}, c2 = {c, c};
;             const f32x2 tA = __builtin_elementwise_fma(v2, (f32x2){kd4[0], kd4[1]}, __builtin_elementwise_fma(-sA, (f32x2){e4[0], e4[1]}, sA));
;             const f32x2 tB = __builtin_elementwise_fma(v2, (f32x2){kd4[2], kd4[3]}, __builtin_elementwise_fma(-sB, (f32x2){e4[2], e4[3]}, sB));
;             sA = __builtin_elementwise_fma(-c2, (f32x2){ka4[0], ka4[1]}, tA);
;             sB = __builtin_elementwise_fma(-c2, (f32x2){ka4[2], ka4[3]}, tB);
;             const f32x2 yv = __builtin_elementwise_fma(sB, (f32x2){r4[2], r4[3]}, sA * (f32x2){r4[0], r4[1]});
;             float y = yv[0] + yv[1];
;             if (u + 1 < SCH) {
;                 const f32x2 cv = __builtin_elementwise_fma(sB, (f32x2){nkk[2], nkk[3]}, sA * (f32x2){nkk[0], nkk[1]});
;                 float cn = cv[0] + cv[1];
;                 cn = DPP_ADD(cn, 0xB1);  y = DPP_ADD(y, 0xB1);
;                 cn = DPP_ADD(cn, 0x4E);  y = DPP_ADD(y, 0x4E);
;                 cn = DPP_ADD(cn, 0x141); y = DPP_ADD(y, 0x141);
;                 cn = DPP_ADD(cn, 0x140); y = DPP_ADD(y, 0x140);
;                 c = cn;
;             } else y = red16(y);
;             if (ks == 0) yl[u * 16] = y;
;             e4 = ne; kd4 = nkd; ka4 = nka; r4 = nr; kk4 = nkk; vv = nv;
;         }
	v_pk_mul_f32 v[94:95], v[20:21], v[94:95]
	v_pk_mul_f32 v[28:29], v[20:21], v[28:29]
	v_pk_fma_f32 v[94:95], v[22:23], v[96:97], v[94:95]
	v_pk_fma_f32 v[28:29], v[22:23], v[30:31], v[28:29]
	v_add_f32_e32 v96, v94, v95
	v_add_f32_e32 v30, v28, v29
	v_pk_fma_f32 v[40:41], v[20:21], v[40:41], v[20:21] neg_lo:[1,0,0] neg_hi:[1,0,0]
	v_add_f32_dpp v97, v96, v96 quad_perm:[1,0,3,2] row_mask:0xf bank_mask:0xf bound_ctrl:1
	v_add_f32_dpp v31, v30, v30 quad_perm:[1,0,3,2] row_mask:0xf bank_mask:0xf bound_ctrl:1
	v_pk_fma_f32 v[42:43], v[22:23], v[42:43], v[22:23] neg_lo:[1,0,0] neg_hi:[1,0,0]
	v_add_f32_dpp v96, v97, v97 quad_perm:[2,3,0,1] row_mask:0xf bank_mask:0xf bound_ctrl:1
	v_add_f32_dpp v30, v31, v31 quad_perm:[2,3,0,1] row_mask:0xf bank_mask:0xf bound_ctrl:1
	v_pk_fma_f32 v[40:41], v[38:39], v[44:45], v[40:41] op_sel_hi:[0,1,1]
	v_add_f32_dpp v97, v96, v96 row_half_mirror row_mask:0xf bank_mask:0xf bound_ctrl:1
	v_add_f32_dpp v31, v30, v30 row_half_mirror row_mask:0xf bank_mask:0xf bound_ctrl:1
	v_pk_fma_f32 v[42:43], v[38:39], v[46:47], v[42:43] op_sel_hi:[0,1,1]
	v_add_f32_dpp v90, v97, v97 row_mirror row_mask:0xf bank_mask:0xf bound_ctrl:1
	v_add_f32_dpp v30, v31, v31 row_mirror row_mask:0xf bank_mask:0xf bound_ctrl:1
	ds_write_b32 v234, v30 offset:43520
	ds_read_b128 v[28:31], v232 offset:14208
	v_pk_fma_f32 v[20:21], v[90:91], v[60:61], v[40:41] op_sel_hi:[0,1,1] neg_lo:[1,0,0] neg_hi:[1,0,0]
	v_pk_fma_f32 v[22:23], v[90:91], v[62:63], v[42:43] op_sel_hi:[0,1,1] neg_lo:[1,0,0] neg_hi:[1,0,0]
	ds_read_b128 v[40:43], v232 offset:14784
	ds_read_b128 v[60:63], v232 offset:15296
	ds_read_b128 v[44:47], v232 offset:15040
	ds_read_b128 v[94:97], v232 offset:15808
	ds_read_b32 v38, v233 offset:16064
	s_waitcnt lgkmcnt(7)
	v_pk_mul_f32 v[32:33], v[20:21], v[32:33]
	v_pk_mul_f32 v[64:65], v[20:21], v[64:65]
	v_pk_fma_f32 v[32:33], v[22:23], v[34:35], v[32:33]
	v_pk_fma_f32 v[64:65], v[22:23], v[66:67], v[64:65]
	v_add_f32_e32 v34, v32, v33
	v_add_f32_e32 v66, v64, v65
	v_pk_fma_f32 v[12:13], v[20:21], v[12:13], v[20:21] neg_lo:[1,0,0] neg_hi:[1,0,0]
	v_add_f32_dpp v35, v34, v34 quad_perm:[1,0,3,2] row_mask:0xf bank_mask:0xf bound_ctrl:1
	v_add_f32_dpp v67, v66, v66 quad_perm:[1,0,3,2] row_mask:0xf bank_mask:0xf bound_ctrl:1
	v_pk_fma_f32 v[14:15], v[22:23], v[14:15], v[22:23] neg_lo:[1,0,0] neg_hi:[1,0,0]
	v_add_f32_dpp v34, v35, v35 quad_perm:[2,3,0,1] row_mask:0xf bank_mask:0xf bound_ctrl:1
	v_add_f32_dpp v66, v67, v67 quad_perm:[2,3,0,1] row_mask:0xf bank_mask:0xf bound_ctrl:1
	v_pk_fma_f32 v[12:13], v[36:37], v[16:17], v[12:13] op_sel_hi:[0,1,1]
	v_add_f32_dpp v35, v34, v34 row_half_mirror row_mask:0xf bank_mask:0xf bound_ctrl:1
	v_add_f32_dpp v67, v66, v66 row_half_mirror row_mask:0xf bank_mask:0xf bound_ctrl:1
	v_pk_fma_f32 v[14:15], v[36:37], v[18:19], v[14:15] op_sel_hi:[0,1,1]
	v_add_f32_dpp v90, v35, v35 row_mirror row_mask:0xf bank_mask:0xf bound_ctrl:1
	v_add_f32_dpp v66, v67, v67 row_mirror row_mask:0xf bank_mask:0xf bound_ctrl:1
	ds_write_b32 v234, v66 offset:43584
	ds_read_b128 v[64:67], v232 offset:15552
	v_pk_fma_f32 v[20:21], v[90:91], v[24:25], v[12:13] op_sel_hi:[0,1,1] neg_lo:[1,0,0] neg_hi:[1,0,0]
	v_pk_fma_f32 v[22:23], v[90:91], v[26:27], v[14:15] op_sel_hi:[0,1,1] neg_lo:[1,0,0] neg_hi:[1,0,0]
	ds_read_b128 v[12:15], v232 offset:16128
	ds_read_b128 v[24:27], v232 offset:16640
	ds_read_b128 v[16:19], v232 offset:16384
	ds_read_b128 v[32:35], v232 offset:17152
	ds_read_b32 v36, v233 offset:17408
	s_waitcnt lgkmcnt(7)
	v_pk_mul_f32 v[94:95], v[20:21], v[94:95]
	v_pk_mul_f32 v[28:29], v[20:21], v[28:29]
	v_pk_fma_f32 v[94:95], v[22:23], v[96:97], v[94:95]
	v_pk_fma_f32 v[28:29], v[22:23], v[30:31], v[28:29]
	v_add_f32_e32 v96, v94, v95
	v_add_f32_e32 v30, v28, v29
	v_pk_fma_f32 v[40:41], v[20:21], v[40:41], v[20:21] neg_lo:[1,0,0] neg_hi:[1,0,0]
	v_add_f32_dpp v97, v96, v96 quad_perm:[1,0,3,2] row_mask:0xf bank_mask:0xf bound_ctrl:1
	v_add_f32_dpp v31, v30, v30 quad_perm:[1,0,3,2] row_mask:0xf bank_mask:0xf bound_ctrl:1
	v_pk_fma_f32 v[42:43], v[22:23], v[42:43], v[22:23] neg_lo:[1,0,0] neg_hi:[1,0,0]
	v_add_f32_dpp v96, v97, v97 quad_perm:[2,3,0,1] row_mask:0xf bank_mask:0xf bound_ctrl:1
	v_add_f32_dpp v30, v31, v31 quad_perm:[2,3,0,1] row_mask:0xf bank_mask:0xf bound_ctrl:1
	v_pk_fma_f32 v[40:41], v[38:39], v[44:45], v[40:41] op_sel_hi:[0,1,1]
	v_add_f32_dpp v97, v96, v96 row_half_mirror row_mask:0xf bank_mask:0xf bound_ctrl:1
	v_add_f32_dpp v31, v30, v30 row_half_mirror row_mask:0xf bank_mask:0xf bound_ctrl:1
	v_pk_fma_f32 v[42:43], v[38:39], v[46:47], v[42:43] op_sel_hi:[0,1,1]
	v_add_f32_dpp v90, v97, v97 row_mirror row_mask:0xf bank_mask:0xf bound_ctrl:1
	v_add_f32_dpp v30, v31, v31 row_mirror row_mask:0xf bank_mask:0xf bound_ctrl:1
	ds_write_b32 v234, v30 offset:43648
	ds_read_b128 v[28:31], v232 offset:16896
	v_pk_fma_f32 v[20:21], v[90:91], v[60:61], v[40:41] op_sel_hi:[0,1,1] neg_lo:[1,0,0] neg_hi:[1,0,0]
	v_pk_fma_f32 v[22:23], v[90:91], v[62:63], v[42:43] op_sel_hi:[0,1,1] neg_lo:[1,0,0] neg_hi:[1,0,0]
	ds_read_b128 v[40:43], v232 offset:17472
	ds_read_b128 v[60:63], v232 offset:17984
	ds_read_b128 v[44:47], v232 offset:17728
	ds_read_b128 v[94:97], v232 offset:18496
	ds_read_b32 v38, v233 offset:18752
	s_waitcnt lgkmcnt(7)
; #define DPP_ADD(v, ctrl) ((v) + __builtin_bit_cast(float, __builtin_amdgcn_update_dpp(0, __builtin_bit_cast(int, (v)), (ctrl), 0xf, 0xf, true)))
; __device__ __forceinline__ void rwkv_scan_unit(const Params& p, int unit, char* smem) {
;     ...
;         for (int u = 0; u < SCH; ++u) {
;             f32x4 ne = e4, nkd = kd4, nka = ka4, nr = r4, nkk = kk4; float nv = vv;
;             if (u + 1 < SCH) { const char* q = lb + (u + 1) * STEPB;
;                 ne = *(const f32x4*)(q); nkd = *(const f32x4*)(q + 256); nka = *(const f32x4*)(q + 512); nr = *(const f32x4*)(q + 768); nkk = *(const f32x4*)(q + 1024);
;                 nv = *(const float*)(vb + (u + 1) * STEPB); }
;             const f32x2 v2 = {vv, vv}, c2 = {c, c};
;             const f32x2 tA = __builtin_elementwise_fma(v2, (f32x2){kd4[0], kd4[1]}, __builtin_elementwise_fma(-sA, (f32x2){e4[0], e4[1]}, sA));
;             const f32x2 tB = __builtin_elementwise_fma(v2, (f32x2){kd4[2], kd4[3]}, __builtin_elementwise_fma(-sB, (f32x2){e4[2], e4[3]}, sB));
;             sA = __builtin_elementwise_fma(-c2, (f32x2){ka4[0], ka4[1]}, tA);
;             sB = __builtin_elementwise_fma(-c2, (f32x2){ka4[2], ka4[3]}, tB);
;             const f32x2 yv = __builtin_elementwise_fma(sB, (f32x2){r4[2], r4[3]}, sA * (f32x2){r4[0], r4[1]});
;             float y = yv[0] + yv[1];
;             if (u + 1 < SCH) {
;                 const f32x2 cv = __builtin_elementwise_fma(sB, (f32x2){nkk[2], nkk[3]}, sA * (f32x2){nkk[0], nkk[1]});
;                 float cn = cv[0] + cv[1];
;                 cn = DPP_ADD(cn, 0xB1);  y = DPP_ADD(y, 0xB1);
;                 cn = DPP_ADD(cn, 0x4E);  y = DPP_ADD(y, 0x4E);
;                 cn = DPP_ADD(cn, 0x141); y = DPP_ADD(y, 0x141);
;                 cn = DPP_ADD(cn, 0x140); y = DPP_ADD(y, 0x140);
;                 c = cn;
;             } else y = red16(y);
;             if (ks == 0) yl[u * 16] = y;
;             e4 = ne; kd4 = nkd; ka4 = nka; r4 = nr; kk4 = nkk; vv = nv;
;         }
	v_pk_mul_f32 v[32:33], v[20:21], v[32:33]
	v_pk_mul_f32 v[64:65], v[20:21], v[64:65]
	v_pk_fma_f32 v[32:33], v[22:23], v[34:35], v[32:33]
	v_pk_fma_f32 v[64:65], v[22:23], v[66:67], v[64:65]
	v_add_f32_e32 v34, v32, v33
	v_add_f32_e32 v66, v64, v65
	v_pk_fma_f32 v[12:13], v[20:21], v[12:13], v[20:21] neg_lo:[1,0,0] neg_hi:[1,0,0]
	v_add_f32_dpp v35, v34, v34 quad_perm:[1,0,3,2] row_mask:0xf bank_mask:0xf bound_ctrl:1
	v_add_f32_dpp v67, v66, v66 quad_perm:[1,0,3,2] row_mask:0xf bank_mask:0xf bound_ctrl:1
	v_pk_fma_f32 v[14:15], v[22:23], v[14:15], v[22:23] neg_lo:[1,0,0] neg_hi:[1,0,0]
	v_add_f32_dpp v34, v35, v35 quad_perm:[2,3,0,1] row_mask:0xf bank_mask:0xf bound_ctrl:1
	v_add_f32_dpp v66, v67, v67 quad_perm:[2,3,0,1] row_mask:0xf bank_mask:0xf bound_ctrl:1
	v_pk_fma_f32 v[12:13], v[36:37], v[16:17], v[12:13] op_sel_hi:[0,1,1]
	v_add_f32_dpp v35, v34, v34 row_half_mirror row_mask:0xf bank_mask:0xf bound_ctrl:1
	v_add_f32_dpp v67, v66, v66 row_half_mirror row_mask:0xf bank_mask:0xf bound_ctrl:1
	v_pk_fma_f32 v[14:15], v[36:37], v[18:19], v[14:15] op_sel_hi:[0,1,1]
	v_add_f32_dpp v90, v35, v35 row_mirror row_mask:0xf bank_mask:0xf bound_ctrl:1
	v_add_f32_dpp v66, v67, v67 row_mirror row_mask:0xf bank_mask:0xf bound_ctrl:1
	ds_write_b32 v234, v66 offset:43712
	ds_read_b128 v[64:67], v232 offset:18240
	v_pk_fma_f32 v[20:21], v[90:91], v[24:25], v[12:13] op_sel_hi:[0,1,1] neg_lo:[1,0,0] neg_hi:[1,0,0]
	v_pk_fma_f32 v[22:23], v[90:91], v[26:27], v[14:15] op_sel_hi:[0,1,1] neg_lo:[1,0,0] neg_hi:[1,0,0]
	ds_read_b128 v[12:15], v232 offset:18816
	ds_read_b128 v[24:27], v232 offset:19328
	ds_read_b128 v[16:19], v232 offset:19072
	ds_read_b128 v[32:35], v232 offset:19840
	ds_read_b32 v36, v233 offset:20096
	s_waitcnt lgkmcnt(7)
	v_pk_mul_f32 v[94:95], v[20:21], v[94:95]
	v_pk_mul_f32 v[28:29], v[20:21], v[28:29]
	v_pk_fma_f32 v[94:95], v[22:23], v[96:97], v[94:95]
	v_pk_fma_f32 v[28:29], v[22:23], v[30:31], v[28:29]
	v_add_f32_e32 v96, v94, v95
	v_add_f32_e32 v30, v28, v29
	v_pk_fma_f32 v[40:41], v[20:21], v[40:41], v[20:21] neg_lo:[1,0,0] neg_hi:[1,0,0]
	v_add_f32_dpp v97, v96, v96 quad_perm:[1,0,3,2] row_mask:0xf bank_mask:0xf bound_ctrl:1
	v_add_f32_dpp v31, v30, v30 quad_perm:[1,0,3,2] row_mask:0xf bank_mask:0xf bound_ctrl:1
	v_pk_fma_f32 v[42:43], v[22:23], v[42:43], v[22:23] neg_lo:[1,0,0] neg_hi:[1,0,0]
	v_add_f32_dpp v96, v97, v97 quad_perm:[2,3,0,1] row_mask:0xf bank_mask:0xf bound_ctrl:1
	v_add_f32_dpp v30, v31, v31 quad_perm:[2,3,0,1] row_mask:0xf bank_mask:0xf bound_ctrl:1
	v_pk_fma_f32 v[40:41], v[38:39], v[44:45], v[40:41] op_sel_hi:[0,1,1]
	v_add_f32_dpp v97, v96, v96 row_half_mirror row_mask:0xf bank_mask:0xf bound_ctrl:1
	v_add_f32_dpp v31, v30, v30 row_half_mirror row_mask:0xf bank_mask:0xf bound_ctrl:1
	v_pk_fma_f32 v[42:43], v[38:39], v[46:47], v[42:43] op_sel_hi:[0,1,1]
	v_add_f32_dpp v90, v97, v97 row_mirror row_mask:0xf bank_mask:0xf bound_ctrl:1
	v_add_f32_dpp v30, v31, v31 row_mirror row_mask:0xf bank_mask:0xf bound_ctrl:1
	ds_write_b32 v234, v30 offset:43776
	ds_read_b128 v[28:31], v232 offset:19584
	v_pk_fma_f32 v[20:21], v[90:91], v[60:61], v[40:41] op_sel_hi:[0,1,1] neg_lo:[1,0,0] neg_hi:[1,0,0]
	v_pk_fma_f32 v[22:23], v[90:91], v[62:63], v[42:43] op_sel_hi:[0,1,1] neg_lo:[1,0,0] neg_hi:[1,0,0]
	ds_read_b128 v[40:43], v232 offset:20160
	ds_read_b128 v[60:63], v232 offset:20672
	ds_read_b128 v[44:47], v232 offset:20416
	ds_read_b128 v[94:97], v232 offset:21184
	ds_read_b32 v38, v233 offset:21440
	s_waitcnt lgkmcnt(7)
	v_pk_mul_f32 v[32:33], v[20:21], v[32:33]
	v_pk_mul_f32 v[64:65], v[20:21], v[64:65]
	v_pk_fma_f32 v[32:33], v[22:23], v[34:35], v[32:33]
	v_pk_fma_f32 v[64:65], v[22:23], v[66:67], v[64:65]
	v_add_f32_e32 v34, v32, v33
	v_add_f32_e32 v66, v64, v65
	v_pk_fma_f32 v[12:13], v[20:21], v[12:13], v[20:21] neg_lo:[1,0,0] neg_hi:[1,0,0]
	v_add_f32_dpp v35, v34, v34 quad_perm:[1,0,3,2] row_mask:0xf bank_mask:0xf bound_ctrl:1
	v_add_f32_dpp v67, v66, v66 quad_perm:[1,0,3,2] row_mask:0xf bank_mask:0xf bound_ctrl:1
	v_pk_fma_f32 v[14:15], v[22:23], v[14:15], v[22:23] neg_lo:[1,0,0] neg_hi:[1,0,0]
	v_add_f32_dpp v34, v35, v35 quad_perm:[2,3,0,1] row_mask:0xf bank_mask:0xf bound_ctrl:1
	v_add_f32_dpp v66, v67, v67 quad_perm:[2,3,0,1] row_mask:0xf bank_mask:0xf bound_ctrl:1
	v_pk_fma_f32 v[12:13], v[36:37], v[16:17], v[12:13] op_sel_hi:[0,1,1]
	v_add_f32_dpp v35, v34, v34 row_half_mirror row_mask:0xf bank_mask:0xf bound_ctrl:1
	v_add_f32_dpp v67, v66, v66 row_half_mirror row_mask:0xf bank_mask:0xf bound_ctrl:1
	v_pk_fma_f32 v[14:15], v[36:37], v[18:19], v[14:15] op_sel_hi:[0,1,1]
	v_add_f32_dpp v90, v35, v35 row_mirror row_mask:0xf bank_mask:0xf bound_ctrl:1
	v_add_f32_dpp v66, v67, v67 row_mirror row_mask:0xf bank_mask:0xf bound_ctrl:1
	ds_write_b32 v234, v66 offset:43840
	ds_read_b128 v[64:67], v232 offset:20928
	v_pk_fma_f32 v[20:21], v[90:91], v[24:25], v[12:13] op_sel_hi:[0,1,1] neg_lo:[1,0,0] neg_hi:[1,0,0]
	v_pk_fma_f32 v[22:23], v[90:91], v[26:27], v[14:15] op_sel_hi:[0,1,1] neg_lo:[1,0,0] neg_hi:[1,0,0]
	s_waitcnt lgkmcnt(2)
; #define DPP_ADD(v, ctrl) ((v) + __builtin_bit_cast(float, __builtin_amdgcn_update_dpp(0, __builtin_bit_cast(int, (v)), (ctrl), 0xf, 0xf, true)))
; #define SC_LSTORE(st_) { SC_S1(st_, 0, rg0) SC_S1(st_, 1, rg1) SC_S1(st_, 2, rg2) }
; __device__ __forceinline__ void rwkv_scan_unit(const Params& p, int unit, char* smem) {
;     ...
;         for (int u = 0; u < SCH; ++u) {
;             f32x4 ne = e4, nkd = kd4, nka = ka4, nr = r4, nkk = kk4; float nv = vv;
;             if (u + 1 < SCH) { const char* q = lb + (u + 1) * STEPB;
;                 ne = *(const f32x4*)(q); nkd = *(const f32x4*)(q + 256); nka = *(const f32x4*)(q + 512); nr = *(const f32x4*)(q + 768); nkk = *(const f32x4*)(q + 1024);
;                 nv = *(const float*)(vb + (u + 1) * STEPB); }
;             const f32x2 v2 = {vv, vv}, c2 = {c, c};
;             const f32x2 tA = __builtin_elementwise_fma(v2, (f32x2){kd4[0], kd4[1]}, __builtin_elementwise_fma(-sA, (f32x2){e4[0], e4[1]}, sA));
;             const f32x2 tB = __builtin_elementwise_fma(v2, (f32x2){kd4[2], kd4[3]}, __builtin_elementwise_fma(-sB, (f32x2){e4[2], e4[3]}, sB));
;             sA = __builtin_elementwise_fma(-c2, (f32x2){ka4[0], ka4[1]}, tA);
;             sB = __builtin_elementwise_fma(-c2, (f32x2){ka4[2], ka4[3]}, tB);
;             const f32x2 yv = __builtin_elementwise_fma(sB, (f32x2){r4[2], r4[3]}, sA * (f32x2){r4[0], r4[1]});
;             float y = yv[0] + yv[1];
;             if (u + 1 < SCH) {
;                 const f32x2 cv = __builtin_elementwise_fma(sB, (f32x2){nkk[2], nkk[3]}, sA * (f32x2){nkk[0], nkk[1]});
;                 float cn = cv[0] + cv[1];
;                 cn = DPP_ADD(cn, 0xB1);  y = DPP_ADD(y, 0xB1);
;                 cn = DPP_ADD(cn, 0x4E);  y = DPP_ADD(y, 0x4E);
;                 cn = DPP_ADD(cn, 0x141); y = DPP_ADD(y, 0x141);
;                 cn = DPP_ADD(cn, 0x140); y = DPP_ADD(y, 0x140);
;                 c = cn;
;             } else y = red16(y);
;             if (ks == 0) yl[u * 16] = y;
;             e4 = ne; kd4 = nkd; ka4 = nka; r4 = nr; kk4 = nkk; vv = nv;
;         }
;         s0 = sA[0]; s1 = sA[1]; s2 = sB[0]; s3 = sB[1];
;         __builtin_amdgcn_sched_barrier(0);
;         if (ci + 1 < NCH) { SC_LSTORE(((ci + 1) & 1) * STG) }
	v_pk_mul_f32 v[94:95], v[20:21], v[94:95]
	v_pk_mul_f32 v[28:29], v[20:21], v[28:29]
	v_pk_fma_f32 v[94:95], v[22:23], v[96:97], v[94:95]
	v_pk_fma_f32 v[28:29], v[22:23], v[30:31], v[28:29]
	v_add_f32_e32 v96, v94, v95
	v_add_f32_e32 v30, v28, v29
	v_pk_fma_f32 v[40:41], v[20:21], v[40:41], v[20:21] neg_lo:[1,0,0] neg_hi:[1,0,0]
	v_add_f32_dpp v97, v96, v96 quad_perm:[1,0,3,2] row_mask:0xf bank_mask:0xf bound_ctrl:1
	v_add_f32_dpp v31, v30, v30 quad_perm:[1,0,3,2] row_mask:0xf bank_mask:0xf bound_ctrl:1
	v_pk_fma_f32 v[42:43], v[22:23], v[42:43], v[22:23] neg_lo:[1,0,0] neg_hi:[1,0,0]
	v_add_f32_dpp v96, v97, v97 quad_perm:[2,3,0,1] row_mask:0xf bank_mask:0xf bound_ctrl:1
	v_add_f32_dpp v30, v31, v31 quad_perm:[2,3,0,1] row_mask:0xf bank_mask:0xf bound_ctrl:1
	v_pk_fma_f32 v[40:41], v[38:39], v[44:45], v[40:41] op_sel_hi:[0,1,1]
	v_add_f32_dpp v97, v96, v96 row_half_mirror row_mask:0xf bank_mask:0xf bound_ctrl:1
	v_add_f32_dpp v31, v30, v30 row_half_mirror row_mask:0xf bank_mask:0xf bound_ctrl:1
	v_pk_fma_f32 v[42:43], v[38:39], v[46:47], v[42:43] op_sel_hi:[0,1,1]
	v_add_f32_dpp v90, v97, v97 row_mirror row_mask:0xf bank_mask:0xf bound_ctrl:1
	v_add_f32_dpp v30, v31, v31 row_mirror row_mask:0xf bank_mask:0xf bound_ctrl:1
	ds_write_b32 v234, v30 offset:43904
	v_pk_fma_f32 v[20:21], v[90:91], v[60:61], v[40:41] op_sel_hi:[0,1,1] neg_lo:[1,0,0] neg_hi:[1,0,0]
	v_pk_fma_f32 v[22:23], v[90:91], v[62:63], v[42:43] op_sel_hi:[0,1,1] neg_lo:[1,0,0] neg_hi:[1,0,0]
	s_waitcnt lgkmcnt(1)
	v_pk_mul_f32 v[64:65], v[20:21], v[64:65]
	v_pk_fma_f32 v[64:65], v[22:23], v[66:67], v[64:65]
	s_nop 0
	v_add_f32_e32 v66, v64, v65
	s_nop 1
	v_add_f32_dpp v67, v66, v66 quad_perm:[1,0,3,2] row_mask:0xf bank_mask:0xf bound_ctrl:1
	s_nop 1
	v_add_f32_dpp v66, v67, v67 quad_perm:[2,3,0,1] row_mask:0xf bank_mask:0xf bound_ctrl:1
	s_nop 1
	v_add_f32_dpp v67, v66, v66 row_half_mirror row_mask:0xf bank_mask:0xf bound_ctrl:1
	s_nop 1
	v_add_f32_dpp v66, v67, v67 row_mirror row_mask:0xf bank_mask:0xf bound_ctrl:1
	ds_write_b32 v234, v66 offset:43968
	s_waitcnt vmcnt(12)
	v_cvt_f32_f16_sdwa v13, v124 dst_sel:DWORD dst_unused:UNUSED_PAD src0_sel:WORD_1
	v_cvt_f32_f16_e32 v12, v124
	v_cvt_f32_f16_sdwa v15, v125 dst_sel:DWORD dst_unused:UNUSED_PAD src0_sel:WORD_1
	v_cvt_f32_f16_e32 v14, v125
	ds_write_b128 v241, v[12:15]
	v_cvt_f32_f16_sdwa v13, v126 dst_sel:DWORD dst_unused:UNUSED_PAD src0_sel:WORD_1
	v_cvt_f32_f16_e32 v12, v126
	v_cvt_f32_f16_sdwa v15, v127 dst_sel:DWORD dst_unused:UNUSED_PAD src0_sel:WORD_1
	v_cvt_f32_f16_e32 v14, v127
	ds_write_b128 v241, v[12:15] offset:16
	v_cvt_f32_f16_sdwa v13, v128 dst_sel:DWORD dst_unused:UNUSED_PAD src0_sel:WORD_1
	v_cvt_f32_f16_e32 v12, v128
	v_cvt_f32_f16_sdwa v15, v129 dst_sel:DWORD dst_unused:UNUSED_PAD src0_sel:WORD_1
	v_cvt_f32_f16_e32 v14, v129
	ds_write_b128 v242, v[12:15]
	v_cvt_f32_f16_sdwa v13, v130 dst_sel:DWORD dst_unused:UNUSED_PAD src0_sel:WORD_1
	v_cvt_f32_f16_e32 v12, v130
	v_cvt_f32_f16_sdwa v15, v131 dst_sel:DWORD dst_unused:UNUSED_PAD src0_sel:WORD_1
	v_cvt_f32_f16_e32 v14, v131
	ds_write_b128 v242, v[12:15] offset:16
	v_cvt_f32_f16_sdwa v13, v132 dst_sel:DWORD dst_unused:UNUSED_PAD src0_sel:WORD_1
	v_cvt_f32_f16_e32 v12, v132
	v_cvt_f32_f16_sdwa v15, v133 dst_sel:DWORD dst_unused:UNUSED_PAD src0_sel:WORD_1
	v_cvt_f32_f16_e32 v14, v133
	ds_write_b128 v243, v[12:15]
	v_cvt_f32_f16_sdwa v13, v134 dst_sel:DWORD dst_unused:UNUSED_PAD src0_sel:WORD_1
	v_cvt_f32_f16_e32 v12, v134
	v_cvt_f32_f16_sdwa v15, v135 dst_sel:DWORD dst_unused:UNUSED_PAD src0_sel:WORD_1
	v_cvt_f32_f16_e32 v14, v135
	ds_write_b128 v243, v[12:15] offset:16

; __device__ __forceinline__ void rwkv_scan_unit(const Params& p, int unit, char* smem) {
;     ...
;         const char* lb = smem + st + ks * 16;
;         const char* vb = smem + st + 1280 + rl * 4;
;         float* yl = (float*)(smem + YOFF + (ci & 1) * 1024) + rl;
;         f32x4 e4 = *(const f32x4*)(lb), kd4 = *(const f32x4*)(lb + 256), ka4 = *(const f32x4*)(lb + 512), r4 = *(const f32x4*)(lb + 768), kk4 = *(const f32x4*)(lb + 1024);
;         float vv = *(const float*)vb;
;         f32x2 sA = {s0, s1}, sB = {s2, s3};
;         float c;
;         { const f32x2 cv = sA * (f32x2){kk4[0], kk4[1]} + sB * (f32x2){kk4[2], kk4[3]}; c = red16(cv[0] + cv[1]); }
; #pragma unroll
;         for (int u = 0; u < SCH; ++u) {
;             f32x4 ne = e4, nkd = kd4, nka = ka4, nr = r4, nkk = kk4; float nv = vv;
;             if (u + 1 < SCH) { const char* q = lb + (u + 1) * STEPB;
;                 ne = *(const f32x4*)(q); nkd = *(const f32x4*)(q + 256); nka = *(const f32x4*)(q + 512); nr = *(const f32x4*)(q + 768); nkk = *(const f32x4*)(q + 1024);
;                 nv = *(const float*)(vb + (u + 1) * STEPB); }
;             const f32x2 v2 = {vv, vv}, c2 = {c, c};
;             const f32x2 tA = __builtin_elementwise_fma(v2, (f32x2){kd4[0], kd4[1]}, __builtin_elementwise_fma(-sA, (f32x2){e4[0], e4[1]}, sA));
;             const f32x2 tB = __builtin_elementwise_fma(v2, (f32x2){kd4[2], kd4[3]}, __builtin_elementwise_fma(-sB, (f32x2){e4[2], e4[3]}, sB));
;             sA = __builtin_elementwise_fma(-c2, (f32x2){ka4[0], ka4[1]}, tA);
;             sB = __builtin_elementwise_fma(-c2, (f32x2){ka4[2], ka4[3]}, tB);
;             const f32x2 yv = __builtin_elementwise_fma(sB, (f32x2){r4[2], r4[3]}, sA * (f32x2){r4[0], r4[1]});
;             float y = yv[0] + yv[1];
;             if (u + 1 < SCH) {
;                 const f32x2 cv = __builtin_elementwise_fma(sB, (f32x2){nkk[2], nkk[3]}, sA * (f32x2){nkk[0], nkk[1]});
;                 float cn = cv[0] + cv[1];
;                 cn = DPP_ADD(cn, 0xB1);  y = DPP_ADD(y, 0xB1);
;                 cn = DPP_ADD(cn, 0x4E);  y = DPP_ADD(y, 0x4E);
;                 cn = DPP_ADD(cn, 0x141); y = DPP_ADD(y, 0x141);
;                 cn = DPP_ADD(cn, 0x140); y = DPP_ADD(y, 0x140);
;                 c = cn;
;             } else y = red16(y);
;             if (ks == 0) yl[u * 16] = y;
.Lsc_p3_body:
	s_add_i32 s30, s64, -1
	s_and_b32 s30, s30, 1
	ds_read_b128 v[32:35], v235 offset:1024
	ds_read_b128 v[12:15], v235 offset:0
	ds_read_b128 v[16:19], v235 offset:256
	ds_read_b32 v36, v236 offset:1280
	ds_read_b128 v[24:27], v235 offset:512
	ds_read_b128 v[28:31], v235 offset:768
	ds_read_b128 v[40:43], v235 offset:1344
	ds_read_b128 v[60:63], v235 offset:1856
	ds_read_b128 v[44:47], v235 offset:1600
	ds_read_b128 v[94:97], v235 offset:2368
	ds_read_b32 v38, v236 offset:2624
	ds_read_b128 v[64:67], v235 offset:2112
	s_lshl_b32 s52, s30, 10
	s_waitcnt lgkmcnt(11)
	v_pk_mul_f32 v[32:33], v[20:21], v[32:33]
	s_waitcnt lgkmcnt(10)
	v_pk_fma_f32 v[12:13], v[20:21], v[12:13], v[20:21] neg_lo:[1,0,0] neg_hi:[1,0,0]
	v_pk_fma_f32 v[32:33], v[22:23], v[34:35], v[32:33]
	v_pk_fma_f32 v[14:15], v[22:23], v[14:15], v[22:23] neg_lo:[1,0,0] neg_hi:[1,0,0]
	v_add_f32_e32 v34, v32, v33
	s_waitcnt lgkmcnt(8)
	v_pk_fma_f32 v[12:13], v[36:37], v[16:17], v[12:13] op_sel_hi:[0,1,1]
	v_pk_fma_f32 v[14:15], v[36:37], v[18:19], v[14:15] op_sel_hi:[0,1,1]
	v_add_f32_dpp v35, v34, v34 quad_perm:[1,0,3,2] row_mask:0xf bank_mask:0xf bound_ctrl:1
	s_nop 1
	v_add_f32_dpp v34, v35, v35 quad_perm:[2,3,0,1] row_mask:0xf bank_mask:0xf bound_ctrl:1
	s_nop 1
	v_add_f32_dpp v35, v34, v34 row_half_mirror row_mask:0xf bank_mask:0xf bound_ctrl:1
	s_nop 1
	v_add_f32_dpp v90, v35, v35 row_mirror row_mask:0xf bank_mask:0xf bound_ctrl:1
	ds_read_b128 v[16:19], v235 offset:2944
	ds_read_b128 v[32:35], v235 offset:3712
	ds_read_b32 v36, v236 offset:3968
	s_waitcnt lgkmcnt(10)
	v_pk_fma_f32 v[20:21], v[90:91], v[24:25], v[12:13] op_sel_hi:[0,1,1] neg_lo:[1,0,0] neg_hi:[1,0,0]
	v_pk_fma_f32 v[22:23], v[90:91], v[26:27], v[14:15] op_sel_hi:[0,1,1] neg_lo:[1,0,0] neg_hi:[1,0,0]
	ds_read_b128 v[12:15], v235 offset:2688
	ds_read_b128 v[24:27], v235 offset:3200
	s_waitcnt lgkmcnt(7)
	v_pk_mul_f32 v[94:95], v[20:21], v[94:95]
	v_pk_mul_f32 v[28:29], v[20:21], v[28:29]
	v_pk_fma_f32 v[94:95], v[22:23], v[96:97], v[94:95]
	v_pk_fma_f32 v[28:29], v[22:23], v[30:31], v[28:29]
	v_add_f32_e32 v96, v94, v95
	v_add_f32_e32 v30, v28, v29
	v_pk_fma_f32 v[40:41], v[20:21], v[40:41], v[20:21] neg_lo:[1,0,0] neg_hi:[1,0,0]
	v_add_f32_dpp v97, v96, v96 quad_perm:[1,0,3,2] row_mask:0xf bank_mask:0xf bound_ctrl:1
	v_add_f32_dpp v31, v30, v30 quad_perm:[1,0,3,2] row_mask:0xf bank_mask:0xf bound_ctrl:1
	v_pk_fma_f32 v[42:43], v[22:23], v[42:43], v[22:23] neg_lo:[1,0,0] neg_hi:[1,0,0]
	v_add_f32_dpp v96, v97, v97 quad_perm:[2,3,0,1] row_mask:0xf bank_mask:0xf bound_ctrl:1
	v_add_f32_dpp v30, v31, v31 quad_perm:[2,3,0,1] row_mask:0xf bank_mask:0xf bound_ctrl:1
	s_waitcnt lgkmcnt(6)
	v_pk_fma_f32 v[40:41], v[38:39], v[44:45], v[40:41] op_sel_hi:[0,1,1]
	v_add_f32_dpp v97, v96, v96 row_half_mirror row_mask:0xf bank_mask:0xf bound_ctrl:1
	v_add_f32_dpp v31, v30, v30 row_half_mirror row_mask:0xf bank_mask:0xf bound_ctrl:1
	v_pk_fma_f32 v[42:43], v[38:39], v[46:47], v[42:43] op_sel_hi:[0,1,1]
	v_add_f32_dpp v90, v97, v97 row_mirror row_mask:0xf bank_mask:0xf bound_ctrl:1
	v_add_f32_dpp v30, v31, v31 row_mirror row_mask:0xf bank_mask:0xf bound_ctrl:1
	ds_write_b32 v237, v30 offset:43008
	ds_read_b128 v[28:31], v235 offset:3456
	v_pk_fma_f32 v[20:21], v[90:91], v[60:61], v[40:41] op_sel_hi:[0,1,1] neg_lo:[1,0,0] neg_hi:[1,0,0]
	v_pk_fma_f32 v[22:23], v[90:91], v[62:63], v[42:43] op_sel_hi:[0,1,1] neg_lo:[1,0,0] neg_hi:[1,0,0]
	ds_read_b128 v[40:43], v235 offset:4032
	ds_read_b128 v[60:63], v235 offset:4544
	ds_read_b128 v[44:47], v235 offset:4288
	ds_read_b128 v[94:97], v235 offset:5056
	ds_read_b32 v38, v236 offset:5312
	s_waitcnt lgkmcnt(8)
	v_pk_mul_f32 v[32:33], v[20:21], v[32:33]
	v_pk_mul_f32 v[64:65], v[20:21], v[64:65]
	v_pk_fma_f32 v[32:33], v[22:23], v[34:35], v[32:33]
	v_pk_fma_f32 v[64:65], v[22:23], v[66:67], v[64:65]
	v_add_f32_e32 v34, v32, v33
	v_add_f32_e32 v66, v64, v65
	v_pk_fma_f32 v[12:13], v[20:21], v[12:13], v[20:21] neg_lo:[1,0,0] neg_hi:[1,0,0]
	v_add_f32_dpp v35, v34, v34 quad_perm:[1,0,3,2] row_mask:0xf bank_mask:0xf bound_ctrl:1
	v_add_f32_dpp v67, v66, v66 quad_perm:[1,0,3,2] row_mask:0xf bank_mask:0xf bound_ctrl:1
	v_pk_fma_f32 v[14:15], v[22:23], v[14:15], v[22:23] neg_lo:[1,0,0] neg_hi:[1,0,0]
	v_add_f32_dpp v34, v35, v35 quad_perm:[2,3,0,1] row_mask:0xf bank_mask:0xf bound_ctrl:1
	v_add_f32_dpp v66, v67, v67 quad_perm:[2,3,0,1] row_mask:0xf bank_mask:0xf bound_ctrl:1
	v_pk_fma_f32 v[12:13], v[36:37], v[16:17], v[12:13] op_sel_hi:[0,1,1]
	v_add_f32_dpp v35, v34, v34 row_half_mirror row_mask:0xf bank_mask:0xf bound_ctrl:1
	v_add_f32_dpp v67, v66, v66 row_half_mirror row_mask:0xf bank_mask:0xf bound_ctrl:1
	v_pk_fma_f32 v[14:15], v[36:37], v[18:19], v[14:15] op_sel_hi:[0,1,1]
	v_add_f32_dpp v90, v35, v35 row_mirror row_mask:0xf bank_mask:0xf bound_ctrl:1
	v_add_f32_dpp v66, v67, v67 row_mirror row_mask:0xf bank_mask:0xf bound_ctrl:1
	ds_write_b32 v237, v66 offset:43072
	ds_read_b128 v[64:67], v235 offset:4800
	s_waitcnt lgkmcnt(9)
	v_pk_fma_f32 v[20:21], v[90:91], v[24:25], v[12:13] op_sel_hi:[0,1,1] neg_lo:[1,0,0] neg_hi:[1,0,0]
	v_pk_fma_f32 v[22:23], v[90:91], v[26:27], v[14:15] op_sel_hi:[0,1,1] neg_lo:[1,0,0] neg_hi:[1,0,0]
	ds_read_b128 v[12:15], v235 offset:5376
	ds_read_b128 v[24:27], v235 offset:5888
	ds_read_b128 v[16:19], v235 offset:5632
	ds_read_b128 v[32:35], v235 offset:6400
	ds_read_b32 v36, v236 offset:6656
	s_waitcnt lgkmcnt(7)
; #define DPP_ADD(v, ctrl) ((v) + __builtin_bit_cast(float, __builtin_amdgcn_update_dpp(0, __builtin_bit_cast(int, (v)), (ctrl), 0xf, 0xf, true)))
; __device__ __forceinline__ void rwkv_scan_unit(const Params& p, int unit, char* smem) {
;     ...
;         for (int u = 0; u < SCH; ++u) {
;             f32x4 ne = e4, nkd = kd4, nka = ka4, nr = r4, nkk = kk4; float nv = vv;
;             if (u + 1 < SCH) { const char* q = lb + (u + 1) * STEPB;
;                 ne = *(const f32x4*)(q); nkd = *(const f32x4*)(q + 256); nka = *(const f32x4*)(q + 512); nr = *(const f32x4*)(q + 768); nkk = *(const f32x4*)(q + 1024);
;                 nv = *(const float*)(vb + (u + 1) * STEPB); }
;             const f32x2 v2 = {vv, vv}, c2 = {c, c};
;             const f32x2 tA = __builtin_elementwise_fma(v2, (f32x2){kd4[0], kd4[1]}, __builtin_elementwise_fma(-sA, (f32x2){e4[0], e4[1]}, sA));
;             const f32x2 tB = __builtin_elementwise_fma(v2, (f32x2){kd4[2], kd4[3]}, __builtin_elementwise_fma(-sB, (f32x2){e4[2], e4[3]}, sB));
;             sA = __builtin_elementwise_fma(-c2, (f32x2){ka4[0], ka4[1]}, tA);
;             sB = __builtin_elementwise_fma(-c2, (f32x2){ka4[2], ka4[3]}, tB);
;             const f32x2 yv = __builtin_elementwise_fma(sB, (f32x2){r4[2], r4[3]}, sA * (f32x2){r4[0], r4[1]});
;             float y = yv[0] + yv[1];
;             if (u + 1 < SCH) {
;                 const f32x2 cv = __builtin_elementwise_fma(sB, (f32x2){nkk[2], nkk[3]}, sA * (f32x2){nkk[0], nkk[1]});
;                 float cn = cv[0] + cv[1];
;                 cn = DPP_ADD(cn, 0xB1);  y = DPP_ADD(y, 0xB1);
;                 cn = DPP_ADD(cn, 0x4E);  y = DPP_ADD(y, 0x4E);
;                 cn = DPP_ADD(cn, 0x141); y = DPP_ADD(y, 0x141);
;                 cn = DPP_ADD(cn, 0x140); y = DPP_ADD(y, 0x140);
;                 c = cn;
;             } else y = red16(y);
;             if (ks == 0) yl[u * 16] = y;
;             e4 = ne; kd4 = nkd; ka4 = nka; r4 = nr; kk4 = nkk; vv = nv;
;         }
	v_pk_mul_f32 v[94:95], v[20:21], v[94:95]
	v_pk_mul_f32 v[28:29], v[20:21], v[28:29]
	v_pk_fma_f32 v[94:95], v[22:23], v[96:97], v[94:95]
	v_pk_fma_f32 v[28:29], v[22:23], v[30:31], v[28:29]
	v_add_f32_e32 v96, v94, v95
	v_add_f32_e32 v30, v28, v29
	v_pk_fma_f32 v[40:41], v[20:21], v[40:41], v[20:21] neg_lo:[1,0,0] neg_hi:[1,0,0]
	v_add_f32_dpp v97, v96, v96 quad_perm:[1,0,3,2] row_mask:0xf bank_mask:0xf bound_ctrl:1
	v_add_f32_dpp v31, v30, v30 quad_perm:[1,0,3,2] row_mask:0xf bank_mask:0xf bound_ctrl:1
	v_pk_fma_f32 v[42:43], v[22:23], v[42:43], v[22:23] neg_lo:[1,0,0] neg_hi:[1,0,0]
	v_add_f32_dpp v96, v97, v97 quad_perm:[2,3,0,1] row_mask:0xf bank_mask:0xf bound_ctrl:1
	v_add_f32_dpp v30, v31, v31 quad_perm:[2,3,0,1] row_mask:0xf bank_mask:0xf bound_ctrl:1
	v_pk_fma_f32 v[40:41], v[38:39], v[44:45], v[40:41] op_sel_hi:[0,1,1]
	v_add_f32_dpp v97, v96, v96 row_half_mirror row_mask:0xf bank_mask:0xf bound_ctrl:1
	v_add_f32_dpp v31, v30, v30 row_half_mirror row_mask:0xf bank_mask:0xf bound_ctrl:1
	v_pk_fma_f32 v[42:43], v[38:39], v[46:47], v[42:43] op_sel_hi:[0,1,1]
	v_add_f32_dpp v90, v97, v97 row_mirror row_mask:0xf bank_mask:0xf bound_ctrl:1
	v_add_f32_dpp v30, v31, v31 row_mirror row_mask:0xf bank_mask:0xf bound_ctrl:1
	ds_write_b32 v237, v30 offset:43136
	ds_read_b128 v[28:31], v235 offset:6144
	v_pk_fma_f32 v[20:21], v[90:91], v[60:61], v[40:41] op_sel_hi:[0,1,1] neg_lo:[1,0,0] neg_hi:[1,0,0]
	v_pk_fma_f32 v[22:23], v[90:91], v[62:63], v[42:43] op_sel_hi:[0,1,1] neg_lo:[1,0,0] neg_hi:[1,0,0]
	ds_read_b128 v[40:43], v235 offset:6720
	ds_read_b128 v[60:63], v235 offset:7232
	ds_read_b128 v[44:47], v235 offset:6976
	ds_read_b128 v[94:97], v235 offset:7744
	ds_read_b32 v38, v236 offset:8000
	s_waitcnt lgkmcnt(7)
	v_pk_mul_f32 v[32:33], v[20:21], v[32:33]
	v_pk_mul_f32 v[64:65], v[20:21], v[64:65]
	v_pk_fma_f32 v[32:33], v[22:23], v[34:35], v[32:33]
	v_pk_fma_f32 v[64:65], v[22:23], v[66:67], v[64:65]
	v_add_f32_e32 v34, v32, v33
	v_add_f32_e32 v66, v64, v65
	v_pk_fma_f32 v[12:13], v[20:21], v[12:13], v[20:21] neg_lo:[1,0,0] neg_hi:[1,0,0]
	v_add_f32_dpp v35, v34, v34 quad_perm:[1,0,3,2] row_mask:0xf bank_mask:0xf bound_ctrl:1
	v_add_f32_dpp v67, v66, v66 quad_perm:[1,0,3,2] row_mask:0xf bank_mask:0xf bound_ctrl:1
	v_pk_fma_f32 v[14:15], v[22:23], v[14:15], v[22:23] neg_lo:[1,0,0] neg_hi:[1,0,0]
	v_add_f32_dpp v34, v35, v35 quad_perm:[2,3,0,1] row_mask:0xf bank_mask:0xf bound_ctrl:1
	v_add_f32_dpp v66, v67, v67 quad_perm:[2,3,0,1] row_mask:0xf bank_mask:0xf bound_ctrl:1
	v_pk_fma_f32 v[12:13], v[36:37], v[16:17], v[12:13] op_sel_hi:[0,1,1]
	v_add_f32_dpp v35, v34, v34 row_half_mirror row_mask:0xf bank_mask:0xf bound_ctrl:1
	v_add_f32_dpp v67, v66, v66 row_half_mirror row_mask:0xf bank_mask:0xf bound_ctrl:1
	v_pk_fma_f32 v[14:15], v[36:37], v[18:19], v[14:15] op_sel_hi:[0,1,1]
	v_add_f32_dpp v90, v35, v35 row_mirror row_mask:0xf bank_mask:0xf bound_ctrl:1
	v_add_f32_dpp v66, v67, v67 row_mirror row_mask:0xf bank_mask:0xf bound_ctrl:1
	ds_write_b32 v237, v66 offset:43200
	ds_read_b128 v[64:67], v235 offset:7488
	v_pk_fma_f32 v[20:21], v[90:91], v[24:25], v[12:13] op_sel_hi:[0,1,1] neg_lo:[1,0,0] neg_hi:[1,0,0]
	v_pk_fma_f32 v[22:23], v[90:91], v[26:27], v[14:15] op_sel_hi:[0,1,1] neg_lo:[1,0,0] neg_hi:[1,0,0]
	ds_read_b128 v[12:15], v235 offset:8064
	ds_read_b128 v[24:27], v235 offset:8576
	ds_read_b128 v[16:19], v235 offset:8320
	ds_read_b128 v[32:35], v235 offset:9088
	ds_read_b32 v36, v236 offset:9344
	s_waitcnt lgkmcnt(7)
	v_pk_mul_f32 v[94:95], v[20:21], v[94:95]
	v_pk_mul_f32 v[28:29], v[20:21], v[28:29]
	v_pk_fma_f32 v[94:95], v[22:23], v[96:97], v[94:95]
	v_pk_fma_f32 v[28:29], v[22:23], v[30:31], v[28:29]
	v_add_f32_e32 v96, v94, v95
	v_add_f32_e32 v30, v28, v29
	v_pk_fma_f32 v[40:41], v[20:21], v[40:41], v[20:21] neg_lo:[1,0,0] neg_hi:[1,0,0]
	v_add_f32_dpp v97, v96, v96 quad_perm:[1,0,3,2] row_mask:0xf bank_mask:0xf bound_ctrl:1
	v_add_f32_dpp v31, v30, v30 quad_perm:[1,0,3,2] row_mask:0xf bank_mask:0xf bound_ctrl:1
	v_pk_fma_f32 v[42:43], v[22:23], v[42:43], v[22:23] neg_lo:[1,0,0] neg_hi:[1,0,0]
	v_add_f32_dpp v96, v97, v97 quad_perm:[2,3,0,1] row_mask:0xf bank_mask:0xf bound_ctrl:1
	v_add_f32_dpp v30, v31, v31 quad_perm:[2,3,0,1] row_mask:0xf bank_mask:0xf bound_ctrl:1
	v_pk_fma_f32 v[40:41], v[38:39], v[44:45], v[40:41] op_sel_hi:[0,1,1]
	v_add_f32_dpp v97, v96, v96 row_half_mirror row_mask:0xf bank_mask:0xf bound_ctrl:1
	v_add_f32_dpp v31, v30, v30 row_half_mirror row_mask:0xf bank_mask:0xf bound_ctrl:1
	v_pk_fma_f32 v[42:43], v[38:39], v[46:47], v[42:43] op_sel_hi:[0,1,1]
	v_add_f32_dpp v90, v97, v97 row_mirror row_mask:0xf bank_mask:0xf bound_ctrl:1
	v_add_f32_dpp v30, v31, v31 row_mirror row_mask:0xf bank_mask:0xf bound_ctrl:1
	ds_write_b32 v237, v30 offset:43264
	ds_read_b128 v[28:31], v235 offset:8832
	v_pk_fma_f32 v[20:21], v[90:91], v[60:61], v[40:41] op_sel_hi:[0,1,1] neg_lo:[1,0,0] neg_hi:[1,0,0]
	v_pk_fma_f32 v[22:23], v[90:91], v[62:63], v[42:43] op_sel_hi:[0,1,1] neg_lo:[1,0,0] neg_hi:[1,0,0]
	ds_read_b128 v[40:43], v235 offset:9408
	ds_read_b128 v[60:63], v235 offset:9920
	ds_read_b128 v[44:47], v235 offset:9664
	ds_read_b128 v[94:97], v235 offset:10432
	ds_read_b32 v38, v236 offset:10688
	s_waitcnt lgkmcnt(7)
; #define DPP_ADD(v, ctrl) ((v) + __builtin_bit_cast(float, __builtin_amdgcn_update_dpp(0, __builtin_bit_cast(int, (v)), (ctrl), 0xf, 0xf, true)))
; __device__ __forceinline__ void rwkv_scan_unit(const Params& p, int unit, char* smem) {
;     ...
;         for (int u = 0; u < SCH; ++u) {
;             f32x4 ne = e4, nkd = kd4, nka = ka4, nr = r4, nkk = kk4; float nv = vv;
;             if (u + 1 < SCH) { const char* q = lb + (u + 1) * STEPB;
;                 ne = *(const f32x4*)(q); nkd = *(const f32x4*)(q + 256); nka = *(const f32x4*)(q + 512); nr = *(const f32x4*)(q + 768); nkk = *(const f32x4*)(q + 1024);
;                 nv = *(const float*)(vb + (u + 1) * STEPB); }
;             const f32x2 v2 = {vv, vv}, c2 = {c, c};
;             const f32x2 tA = __builtin_elementwise_fma(v2, (f32x2){kd4[0], kd4[1]}, __builtin_elementwise_fma(-sA, (f32x2){e4[0], e4[1]}, sA));
;             const f32x2 tB = __builtin_elementwise_fma(v2, (f32x2){kd4[2], kd4[3]}, __builtin_elementwise_fma(-sB, (f32x2){e4[2], e4[3]}, sB));
;             sA = __builtin_elementwise_fma(-c2, (f32x2){ka4[0], ka4[1]}, tA);
;             sB = __builtin_elementwise_fma(-c2, (f32x2){ka4[2], ka4[3]}, tB);
;             const f32x2 yv = __builtin_elementwise_fma(sB, (f32x2){r4[2], r4[3]}, sA * (f32x2){r4[0], r4[1]});
;             float y = yv[0] + yv[1];
;             if (u + 1 < SCH) {
;                 const f32x2 cv = __builtin_elementwise_fma(sB, (f32x2){nkk[2], nkk[3]}, sA * (f32x2){nkk[0], nkk[1]});
;                 float cn = cv[0] + cv[1];
;                 cn = DPP_ADD(cn, 0xB1);  y = DPP_ADD(y, 0xB1);
;                 cn = DPP_ADD(cn, 0x4E);  y = DPP_ADD(y, 0x4E);
;                 cn = DPP_ADD(cn, 0x141); y = DPP_ADD(y, 0x141);
;                 cn = DPP_ADD(cn, 0x140); y = DPP_ADD(y, 0x140);
;                 c = cn;
;             } else y = red16(y);
;             if (ks == 0) yl[u * 16] = y;
;             e4 = ne; kd4 = nkd; ka4 = nka; r4 = nr; kk4 = nkk; vv = nv;
;         }
	v_pk_mul_f32 v[32:33], v[20:21], v[32:33]
	v_pk_mul_f32 v[64:65], v[20:21], v[64:65]
	v_pk_fma_f32 v[32:33], v[22:23], v[34:35], v[32:33]
	v_pk_fma_f32 v[64:65], v[22:23], v[66:67], v[64:65]
	v_add_f32_e32 v34, v32, v33
	v_add_f32_e32 v66, v64, v65
	v_pk_fma_f32 v[12:13], v[20:21], v[12:13], v[20:21] neg_lo:[1,0,0] neg_hi:[1,0,0]
	v_add_f32_dpp v35, v34, v34 quad_perm:[1,0,3,2] row_mask:0xf bank_mask:0xf bound_ctrl:1
	v_add_f32_dpp v67, v66, v66 quad_perm:[1,0,3,2] row_mask:0xf bank_mask:0xf bound_ctrl:1
	v_pk_fma_f32 v[14:15], v[22:23], v[14:15], v[22:23] neg_lo:[1,0,0] neg_hi:[1,0,0]
	v_add_f32_dpp v34, v35, v35 quad_perm:[2,3,0,1] row_mask:0xf bank_mask:0xf bound_ctrl:1
	v_add_f32_dpp v66, v67, v67 quad_perm:[2,3,0,1] row_mask:0xf bank_mask:0xf bound_ctrl:1
	v_pk_fma_f32 v[12:13], v[36:37], v[16:17], v[12:13] op_sel_hi:[0,1,1]
	v_add_f32_dpp v35, v34, v34 row_half_mirror row_mask:0xf bank_mask:0xf bound_ctrl:1
	v_add_f32_dpp v67, v66, v66 row_half_mirror row_mask:0xf bank_mask:0xf bound_ctrl:1
	v_pk_fma_f32 v[14:15], v[36:37], v[18:19], v[14:15] op_sel_hi:[0,1,1]
	v_add_f32_dpp v90, v35, v35 row_mirror row_mask:0xf bank_mask:0xf bound_ctrl:1
	v_add_f32_dpp v66, v67, v67 row_mirror row_mask:0xf bank_mask:0xf bound_ctrl:1
	ds_write_b32 v237, v66 offset:43328
	ds_read_b128 v[64:67], v235 offset:10176
	v_pk_fma_f32 v[20:21], v[90:91], v[24:25], v[12:13] op_sel_hi:[0,1,1] neg_lo:[1,0,0] neg_hi:[1,0,0]
	v_pk_fma_f32 v[22:23], v[90:91], v[26:27], v[14:15] op_sel_hi:[0,1,1] neg_lo:[1,0,0] neg_hi:[1,0,0]
	ds_read_b128 v[12:15], v235 offset:10752
	ds_read_b128 v[24:27], v235 offset:11264
	ds_read_b128 v[16:19], v235 offset:11008
	ds_read_b128 v[32:35], v235 offset:11776
	ds_read_b32 v36, v236 offset:12032
	s_waitcnt lgkmcnt(7)
	v_pk_mul_f32 v[94:95], v[20:21], v[94:95]
	v_pk_mul_f32 v[28:29], v[20:21], v[28:29]
	v_pk_fma_f32 v[94:95], v[22:23], v[96:97], v[94:95]
	v_pk_fma_f32 v[28:29], v[22:23], v[30:31], v[28:29]
	v_add_f32_e32 v96, v94, v95
	v_add_f32_e32 v30, v28, v29
	v_pk_fma_f32 v[40:41], v[20:21], v[40:41], v[20:21] neg_lo:[1,0,0] neg_hi:[1,0,0]
	v_add_f32_dpp v97, v96, v96 quad_perm:[1,0,3,2] row_mask:0xf bank_mask:0xf bound_ctrl:1
	v_add_f32_dpp v31, v30, v30 quad_perm:[1,0,3,2] row_mask:0xf bank_mask:0xf bound_ctrl:1
	v_pk_fma_f32 v[42:43], v[22:23], v[42:43], v[22:23] neg_lo:[1,0,0] neg_hi:[1,0,0]
	v_add_f32_dpp v96, v97, v97 quad_perm:[2,3,0,1] row_mask:0xf bank_mask:0xf bound_ctrl:1
	v_add_f32_dpp v30, v31, v31 quad_perm:[2,3,0,1] row_mask:0xf bank_mask:0xf bound_ctrl:1
	v_pk_fma_f32 v[40:41], v[38:39], v[44:45], v[40:41] op_sel_hi:[0,1,1]
	v_add_f32_dpp v97, v96, v96 row_half_mirror row_mask:0xf bank_mask:0xf bound_ctrl:1
	v_add_f32_dpp v31, v30, v30 row_half_mirror row_mask:0xf bank_mask:0xf bound_ctrl:1
	v_pk_fma_f32 v[42:43], v[38:39], v[46:47], v[42:43] op_sel_hi:[0,1,1]
	v_add_f32_dpp v90, v97, v97 row_mirror row_mask:0xf bank_mask:0xf bound_ctrl:1
	v_add_f32_dpp v30, v31, v31 row_mirror row_mask:0xf bank_mask:0xf bound_ctrl:1
	ds_write_b32 v237, v30 offset:43392
	ds_read_b128 v[28:31], v235 offset:11520
	v_pk_fma_f32 v[20:21], v[90:91], v[60:61], v[40:41] op_sel_hi:[0,1,1] neg_lo:[1,0,0] neg_hi:[1,0,0]
	v_pk_fma_f32 v[22:23], v[90:91], v[62:63], v[42:43] op_sel_hi:[0,1,1] neg_lo:[1,0,0] neg_hi:[1,0,0]
	ds_read_b128 v[40:43], v235 offset:12096
	ds_read_b128 v[60:63], v235 offset:12608
	ds_read_b128 v[44:47], v235 offset:12352
	ds_read_b128 v[94:97], v235 offset:13120
	ds_read_b32 v38, v236 offset:13376
	s_waitcnt lgkmcnt(7)
	v_pk_mul_f32 v[32:33], v[20:21], v[32:33]
	v_pk_mul_f32 v[64:65], v[20:21], v[64:65]
	v_pk_fma_f32 v[32:33], v[22:23], v[34:35], v[32:33]
	v_pk_fma_f32 v[64:65], v[22:23], v[66:67], v[64:65]
	v_add_f32_e32 v34, v32, v33
	v_add_f32_e32 v66, v64, v65
	v_pk_fma_f32 v[12:13], v[20:21], v[12:13], v[20:21] neg_lo:[1,0,0] neg_hi:[1,0,0]
	v_add_f32_dpp v35, v34, v34 quad_perm:[1,0,3,2] row_mask:0xf bank_mask:0xf bound_ctrl:1
	v_add_f32_dpp v67, v66, v66 quad_perm:[1,0,3,2] row_mask:0xf bank_mask:0xf bound_ctrl:1
	v_pk_fma_f32 v[14:15], v[22:23], v[14:15], v[22:23] neg_lo:[1,0,0] neg_hi:[1,0,0]
	v_add_f32_dpp v34, v35, v35 quad_perm:[2,3,0,1] row_mask:0xf bank_mask:0xf bound_ctrl:1
	v_add_f32_dpp v66, v67, v67 quad_perm:[2,3,0,1] row_mask:0xf bank_mask:0xf bound_ctrl:1
	v_pk_fma_f32 v[12:13], v[36:37], v[16:17], v[12:13] op_sel_hi:[0,1,1]
	v_add_f32_dpp v35, v34, v34 row_half_mirror row_mask:0xf bank_mask:0xf bound_ctrl:1
	v_add_f32_dpp v67, v66, v66 row_half_mirror row_mask:0xf bank_mask:0xf bound_ctrl:1
	v_pk_fma_f32 v[14:15], v[36:37], v[18:19], v[14:15] op_sel_hi:[0,1,1]
	v_add_f32_dpp v90, v35, v35 row_mirror row_mask:0xf bank_mask:0xf bound_ctrl:1
	v_add_f32_dpp v66, v67, v67 row_mirror row_mask:0xf bank_mask:0xf bound_ctrl:1
	ds_write_b32 v237, v66 offset:43456
	ds_read_b128 v[64:67], v235 offset:12864
	v_pk_fma_f32 v[20:21], v[90:91], v[24:25], v[12:13] op_sel_hi:[0,1,1] neg_lo:[1,0,0] neg_hi:[1,0,0]
	v_pk_fma_f32 v[22:23], v[90:91], v[26:27], v[14:15] op_sel_hi:[0,1,1] neg_lo:[1,0,0] neg_hi:[1,0,0]
	ds_read_b128 v[12:15], v235 offset:13440
	ds_read_b128 v[24:27], v235 offset:13952
	ds_read_b128 v[16:19], v235 offset:13696
	ds_read_b128 v[32:35], v235 offset:14464
	ds_read_b32 v36, v236 offset:14720
	s_waitcnt lgkmcnt(7)
; #define DPP_ADD(v, ctrl) ((v) + __builtin_bit_cast(float, __builtin_amdgcn_update_dpp(0, __builtin_bit_cast(int, (v)), (ctrl), 0xf, 0xf, true)))
; __device__ __forceinline__ void rwkv_scan_unit(const Params& p, int unit, char* smem) {
;     ...
;         for (int u = 0; u < SCH; ++u) {
;             f32x4 ne = e4, nkd = kd4, nka = ka4, nr = r4, nkk = kk4; float nv = vv;
;             if (u + 1 < SCH) { const char* q = lb + (u + 1) * STEPB;
;                 ne = *(const f32x4*)(q); nkd = *(const f32x4*)(q + 256); nka = *(const f32x4*)(q + 512); nr = *(const f32x4*)(q + 768); nkk = *(const f32x4*)(q + 1024);
;                 nv = *(const float*)(vb + (u + 1) * STEPB); }
;             const f32x2 v2 = {vv, vv}, c2 = {c, c};
;             const f32x2 tA = __builtin_elementwise_fma(v2, (f32x2){kd4[0], kd4[1]}, __builtin_elementwise_fma(-sA, (f32x2){e4[0], e4[1]}, sA));
;             const f32x2 tB = __builtin_elementwise_fma(v2, (f32x2){kd4[2], kd4[3]}, __builtin_elementwise_fma(-sB, (f32x2){e4[2], e4[3]}, sB));
;             sA = __builtin_elementwise_fma(-c2, (f32x2){ka4[0], ka4[1]}, tA);
;             sB = __builtin_elementwise_fma(-c2, (f32x2){ka4[2], ka4[3]}, tB);
;             const f32x2 yv = __builtin_elementwise_fma(sB, (f32x2){r4[2], r4[3]}, sA * (f32x2){r4[0], r4[1]});
;             float y = yv[0] + yv[1];
;             if (u + 1 < SCH) {
;                 const f32x2 cv = __builtin_elementwise_fma(sB, (f32x2){nkk[2], nkk[3]}, sA * (f32x2){nkk[0], nkk[1]});
;                 float cn = cv[0] + cv[1];
;                 cn = DPP_ADD(cn, 0xB1);  y = DPP_ADD(y, 0xB1);
;                 cn = DPP_ADD(cn, 0x4E);  y = DPP_ADD(y, 0x4E);
;                 cn = DPP_ADD(cn, 0x141); y = DPP_ADD(y, 0x141);
;                 cn = DPP_ADD(cn, 0x140); y = DPP_ADD(y, 0x140);
;                 c = cn;
;             } else y = red16(y);
;             if (ks == 0) yl[u * 16] = y;
;             e4 = ne; kd4 = nkd; ka4 = nka; r4 = nr; kk4 = nkk; vv = nv;
;         }
	v_pk_mul_f32 v[94:95], v[20:21], v[94:95]
	v_pk_mul_f32 v[28:29], v[20:21], v[28:29]
	v_pk_fma_f32 v[94:95], v[22:23], v[96:97], v[94:95]
	v_pk_fma_f32 v[28:29], v[22:23], v[30:31], v[28:29]
	v_add_f32_e32 v96, v94, v95
	v_add_f32_e32 v30, v28, v29
	v_pk_fma_f32 v[40:41], v[20:21], v[40:41], v[20:21] neg_lo:[1,0,0] neg_hi:[1,0,0]
	v_add_f32_dpp v97, v96, v96 quad_perm:[1,0,3,2] row_mask:0xf bank_mask:0xf bound_ctrl:1
	v_add_f32_dpp v31, v30, v30 quad_perm:[1,0,3,2] row_mask:0xf bank_mask:0xf bound_ctrl:1
	v_pk_fma_f32 v[42:43], v[22:23], v[42:43], v[22:23] neg_lo:[1,0,0] neg_hi:[1,0,0]
	v_add_f32_dpp v96, v97, v97 quad_perm:[2,3,0,1] row_mask:0xf bank_mask:0xf bound_ctrl:1
	v_add_f32_dpp v30, v31, v31 quad_perm:[2,3,0,1] row_mask:0xf bank_mask:0xf bound_ctrl:1
	v_pk_fma_f32 v[40:41], v[38:39], v[44:45], v[40:41] op_sel_hi:[0,1,1]
	v_add_f32_dpp v97, v96, v96 row_half_mirror row_mask:0xf bank_mask:0xf bound_ctrl:1
	v_add_f32_dpp v31, v30, v30 row_half_mirror row_mask:0xf bank_mask:0xf bound_ctrl:1
	v_pk_fma_f32 v[42:43], v[38:39], v[46:47], v[42:43] op_sel_hi:[0,1,1]
	v_add_f32_dpp v90, v97, v97 row_mirror row_mask:0xf bank_mask:0xf bound_ctrl:1
	v_add_f32_dpp v30, v31, v31 row_mirror row_mask:0xf bank_mask:0xf bound_ctrl:1
	ds_write_b32 v237, v30 offset:43520
	ds_read_b128 v[28:31], v235 offset:14208
	v_pk_fma_f32 v[20:21], v[90:91], v[60:61], v[40:41] op_sel_hi:[0,1,1] neg_lo:[1,0,0] neg_hi:[1,0,0]
	v_pk_fma_f32 v[22:23], v[90:91], v[62:63], v[42:43] op_sel_hi:[0,1,1] neg_lo:[1,0,0] neg_hi:[1,0,0]
	ds_read_b128 v[40:43], v235 offset:14784
	ds_read_b128 v[60:63], v235 offset:15296
	ds_read_b128 v[44:47], v235 offset:15040
	ds_read_b128 v[94:97], v235 offset:15808
	ds_read_b32 v38, v236 offset:16064
	s_waitcnt lgkmcnt(7)
	v_pk_mul_f32 v[32:33], v[20:21], v[32:33]
	v_pk_mul_f32 v[64:65], v[20:21], v[64:65]
	v_pk_fma_f32 v[32:33], v[22:23], v[34:35], v[32:33]
	v_pk_fma_f32 v[64:65], v[22:23], v[66:67], v[64:65]
	v_add_f32_e32 v34, v32, v33
	v_add_f32_e32 v66, v64, v65
	v_pk_fma_f32 v[12:13], v[20:21], v[12:13], v[20:21] neg_lo:[1,0,0] neg_hi:[1,0,0]
	v_add_f32_dpp v35, v34, v34 quad_perm:[1,0,3,2] row_mask:0xf bank_mask:0xf bound_ctrl:1
	v_add_f32_dpp v67, v66, v66 quad_perm:[1,0,3,2] row_mask:0xf bank_mask:0xf bound_ctrl:1
	v_pk_fma_f32 v[14:15], v[22:23], v[14:15], v[22:23] neg_lo:[1,0,0] neg_hi:[1,0,0]
	v_add_f32_dpp v34, v35, v35 quad_perm:[2,3,0,1] row_mask:0xf bank_mask:0xf bound_ctrl:1
	v_add_f32_dpp v66, v67, v67 quad_perm:[2,3,0,1] row_mask:0xf bank_mask:0xf bound_ctrl:1
	v_pk_fma_f32 v[12:13], v[36:37], v[16:17], v[12:13] op_sel_hi:[0,1,1]
	v_add_f32_dpp v35, v34, v34 row_half_mirror row_mask:0xf bank_mask:0xf bound_ctrl:1
	v_add_f32_dpp v67, v66, v66 row_half_mirror row_mask:0xf bank_mask:0xf bound_ctrl:1
	v_pk_fma_f32 v[14:15], v[36:37], v[18:19], v[14:15] op_sel_hi:[0,1,1]
	v_add_f32_dpp v90, v35, v35 row_mirror row_mask:0xf bank_mask:0xf bound_ctrl:1
	v_add_f32_dpp v66, v67, v67 row_mirror row_mask:0xf bank_mask:0xf bound_ctrl:1
	ds_write_b32 v237, v66 offset:43584
	ds_read_b128 v[64:67], v235 offset:15552
	v_pk_fma_f32 v[20:21], v[90:91], v[24:25], v[12:13] op_sel_hi:[0,1,1] neg_lo:[1,0,0] neg_hi:[1,0,0]
	v_pk_fma_f32 v[22:23], v[90:91], v[26:27], v[14:15] op_sel_hi:[0,1,1] neg_lo:[1,0,0] neg_hi:[1,0,0]
	ds_read_b128 v[12:15], v235 offset:16128
	ds_read_b128 v[24:27], v235 offset:16640
	ds_read_b128 v[16:19], v235 offset:16384
	ds_read_b128 v[32:35], v235 offset:17152
	ds_read_b32 v36, v236 offset:17408
	s_waitcnt lgkmcnt(7)
	v_pk_mul_f32 v[94:95], v[20:21], v[94:95]
	v_pk_mul_f32 v[28:29], v[20:21], v[28:29]
	v_pk_fma_f32 v[94:95], v[22:23], v[96:97], v[94:95]
	v_pk_fma_f32 v[28:29], v[22:23], v[30:31], v[28:29]
	v_add_f32_e32 v96, v94, v95
	v_add_f32_e32 v30, v28, v29
	v_pk_fma_f32 v[40:41], v[20:21], v[40:41], v[20:21] neg_lo:[1,0,0] neg_hi:[1,0,0]
	v_add_f32_dpp v97, v96, v96 quad_perm:[1,0,3,2] row_mask:0xf bank_mask:0xf bound_ctrl:1
	v_add_f32_dpp v31, v30, v30 quad_perm:[1,0,3,2] row_mask:0xf bank_mask:0xf bound_ctrl:1
	v_pk_fma_f32 v[42:43], v[22:23], v[42:43], v[22:23] neg_lo:[1,0,0] neg_hi:[1,0,0]
	v_add_f32_dpp v96, v97, v97 quad_perm:[2,3,0,1] row_mask:0xf bank_mask:0xf bound_ctrl:1
	v_add_f32_dpp v30, v31, v31 quad_perm:[2,3,0,1] row_mask:0xf bank_mask:0xf bound_ctrl:1
	v_pk_fma_f32 v[40:41], v[38:39], v[44:45], v[40:41] op_sel_hi:[0,1,1]
	v_add_f32_dpp v97, v96, v96 row_half_mirror row_mask:0xf bank_mask:0xf bound_ctrl:1
	v_add_f32_dpp v31, v30, v30 row_half_mirror row_mask:0xf bank_mask:0xf bound_ctrl:1
	v_pk_fma_f32 v[42:43], v[38:39], v[46:47], v[42:43] op_sel_hi:[0,1,1]
	v_add_f32_dpp v90, v97, v97 row_mirror row_mask:0xf bank_mask:0xf bound_ctrl:1
	v_add_f32_dpp v30, v31, v31 row_mirror row_mask:0xf bank_mask:0xf bound_ctrl:1
	ds_write_b32 v237, v30 offset:43648
	ds_read_b128 v[28:31], v235 offset:16896
	v_pk_fma_f32 v[20:21], v[90:91], v[60:61], v[40:41] op_sel_hi:[0,1,1] neg_lo:[1,0,0] neg_hi:[1,0,0]
	v_pk_fma_f32 v[22:23], v[90:91], v[62:63], v[42:43] op_sel_hi:[0,1,1] neg_lo:[1,0,0] neg_hi:[1,0,0]
	ds_read_b128 v[40:43], v235 offset:17472
	ds_read_b128 v[60:63], v235 offset:17984
	ds_read_b128 v[44:47], v235 offset:17728
	ds_read_b128 v[94:97], v235 offset:18496
	ds_read_b32 v38, v236 offset:18752
	s_waitcnt lgkmcnt(7)
; #define DPP_ADD(v, ctrl) ((v) + __builtin_bit_cast(float, __builtin_amdgcn_update_dpp(0, __builtin_bit_cast(int, (v)), (ctrl), 0xf, 0xf, true)))
; __device__ __forceinline__ void rwkv_scan_unit(const Params& p, int unit, char* smem) {
;     ...
;         for (int u = 0; u < SCH; ++u) {
;             f32x4 ne = e4, nkd = kd4, nka = ka4, nr = r4, nkk = kk4; float nv = vv;
;             if (u + 1 < SCH) { const char* q = lb + (u + 1) * STEPB;
;                 ne = *(const f32x4*)(q); nkd = *(const f32x4*)(q + 256); nka = *(const f32x4*)(q + 512); nr = *(const f32x4*)(q + 768); nkk = *(const f32x4*)(q + 1024);
;                 nv = *(const float*)(vb + (u + 1) * STEPB); }
;             const f32x2 v2 = {vv, vv}, c2 = {c, c};
;             const f32x2 tA = __builtin_elementwise_fma(v2, (f32x2){kd4[0], kd4[1]}, __builtin_elementwise_fma(-sA, (f32x2){e4[0], e4[1]}, sA));
;             const f32x2 tB = __builtin_elementwise_fma(v2, (f32x2){kd4[2], kd4[3]}, __builtin_elementwise_fma(-sB, (f32x2){e4[2], e4[3]}, sB));
;             sA = __builtin_elementwise_fma(-c2, (f32x2){ka4[0], ka4[1]}, tA);
;             sB = __builtin_elementwise_fma(-c2, (f32x2){ka4[2], ka4[3]}, tB);
;             const f32x2 yv = __builtin_elementwise_fma(sB, (f32x2){r4[2], r4[3]}, sA * (f32x2){r4[0], r4[1]});
;             float y = yv[0] + yv[1];
;             if (u + 1 < SCH) {
;                 const f32x2 cv = __builtin_elementwise_fma(sB, (f32x2){nkk[2], nkk[3]}, sA * (f32x2){nkk[0], nkk[1]});
;                 float cn = cv[0] + cv[1];
;                 cn = DPP_ADD(cn, 0xB1);  y = DPP_ADD(y, 0xB1);
;                 cn = DPP_ADD(cn, 0x4E);  y = DPP_ADD(y, 0x4E);
;                 cn = DPP_ADD(cn, 0x141); y = DPP_ADD(y, 0x141);
;                 cn = DPP_ADD(cn, 0x140); y = DPP_ADD(y, 0x140);
;                 c = cn;
;             } else y = red16(y);
;             if (ks == 0) yl[u * 16] = y;
;             e4 = ne; kd4 = nkd; ka4 = nka; r4 = nr; kk4 = nkk; vv = nv;
;         }
	v_pk_mul_f32 v[32:33], v[20:21], v[32:33]
	v_pk_mul_f32 v[64:65], v[20:21], v[64:65]
	v_pk_fma_f32 v[32:33], v[22:23], v[34:35], v[32:33]
	v_pk_fma_f32 v[64:65], v[22:23], v[66:67], v[64:65]
	v_add_f32_e32 v34, v32, v33
	v_add_f32_e32 v66, v64, v65
	v_pk_fma_f32 v[12:13], v[20:21], v[12:13], v[20:21] neg_lo:[1,0,0] neg_hi:[1,0,0]
	v_add_f32_dpp v35, v34, v34 quad_perm:[1,0,3,2] row_mask:0xf bank_mask:0xf bound_ctrl:1
	v_add_f32_dpp v67, v66, v66 quad_perm:[1,0,3,2] row_mask:0xf bank_mask:0xf bound_ctrl:1
	v_pk_fma_f32 v[14:15], v[22:23], v[14:15], v[22:23] neg_lo:[1,0,0] neg_hi:[1,0,0]
	v_add_f32_dpp v34, v35, v35 quad_perm:[2,3,0,1] row_mask:0xf bank_mask:0xf bound_ctrl:1
	v_add_f32_dpp v66, v67, v67 quad_perm:[2,3,0,1] row_mask:0xf bank_mask:0xf bound_ctrl:1
	v_pk_fma_f32 v[12:13], v[36:37], v[16:17], v[12:13] op_sel_hi:[0,1,1]
	v_add_f32_dpp v35, v34, v34 row_half_mirror row_mask:0xf bank_mask:0xf bound_ctrl:1
	v_add_f32_dpp v67, v66, v66 row_half_mirror row_mask:0xf bank_mask:0xf bound_ctrl:1
	v_pk_fma_f32 v[14:15], v[36:37], v[18:19], v[14:15] op_sel_hi:[0,1,1]
	v_add_f32_dpp v90, v35, v35 row_mirror row_mask:0xf bank_mask:0xf bound_ctrl:1
	v_add_f32_dpp v66, v67, v67 row_mirror row_mask:0xf bank_mask:0xf bound_ctrl:1
	ds_write_b32 v237, v66 offset:43712
	ds_read_b128 v[64:67], v235 offset:18240
	v_pk_fma_f32 v[20:21], v[90:91], v[24:25], v[12:13] op_sel_hi:[0,1,1] neg_lo:[1,0,0] neg_hi:[1,0,0]
	v_pk_fma_f32 v[22:23], v[90:91], v[26:27], v[14:15] op_sel_hi:[0,1,1] neg_lo:[1,0,0] neg_hi:[1,0,0]
	ds_read_b128 v[12:15], v235 offset:18816
	ds_read_b128 v[24:27], v235 offset:19328
	ds_read_b128 v[16:19], v235 offset:19072
	ds_read_b128 v[32:35], v235 offset:19840
	ds_read_b32 v36, v236 offset:20096
	s_waitcnt lgkmcnt(7)
	v_pk_mul_f32 v[94:95], v[20:21], v[94:95]
	v_pk_mul_f32 v[28:29], v[20:21], v[28:29]
	v_pk_fma_f32 v[94:95], v[22:23], v[96:97], v[94:95]
	v_pk_fma_f32 v[28:29], v[22:23], v[30:31], v[28:29]
	v_add_f32_e32 v96, v94, v95
	v_add_f32_e32 v30, v28, v29
	v_pk_fma_f32 v[40:41], v[20:21], v[40:41], v[20:21] neg_lo:[1,0,0] neg_hi:[1,0,0]
	v_add_f32_dpp v97, v96, v96 quad_perm:[1,0,3,2] row_mask:0xf bank_mask:0xf bound_ctrl:1
	v_add_f32_dpp v31, v30, v30 quad_perm:[1,0,3,2] row_mask:0xf bank_mask:0xf bound_ctrl:1
	v_pk_fma_f32 v[42:43], v[22:23], v[42:43], v[22:23] neg_lo:[1,0,0] neg_hi:[1,0,0]
	v_add_f32_dpp v96, v97, v97 quad_perm:[2,3,0,1] row_mask:0xf bank_mask:0xf bound_ctrl:1
	v_add_f32_dpp v30, v31, v31 quad_perm:[2,3,0,1] row_mask:0xf bank_mask:0xf bound_ctrl:1
	v_pk_fma_f32 v[40:41], v[38:39], v[44:45], v[40:41] op_sel_hi:[0,1,1]
	v_add_f32_dpp v97, v96, v96 row_half_mirror row_mask:0xf bank_mask:0xf bound_ctrl:1
	v_add_f32_dpp v31, v30, v30 row_half_mirror row_mask:0xf bank_mask:0xf bound_ctrl:1
	v_pk_fma_f32 v[42:43], v[38:39], v[46:47], v[42:43] op_sel_hi:[0,1,1]
	v_add_f32_dpp v90, v97, v97 row_mirror row_mask:0xf bank_mask:0xf bound_ctrl:1
	v_add_f32_dpp v30, v31, v31 row_mirror row_mask:0xf bank_mask:0xf bound_ctrl:1
	ds_write_b32 v237, v30 offset:43776
	ds_read_b128 v[28:31], v235 offset:19584
	v_pk_fma_f32 v[20:21], v[90:91], v[60:61], v[40:41] op_sel_hi:[0,1,1] neg_lo:[1,0,0] neg_hi:[1,0,0]
	v_pk_fma_f32 v[22:23], v[90:91], v[62:63], v[42:43] op_sel_hi:[0,1,1] neg_lo:[1,0,0] neg_hi:[1,0,0]
	ds_read_b128 v[40:43], v235 offset:20160
	ds_read_b128 v[60:63], v235 offset:20672
	ds_read_b128 v[44:47], v235 offset:20416
	ds_read_b128 v[94:97], v235 offset:21184
	ds_read_b32 v38, v236 offset:21440
	s_waitcnt lgkmcnt(7)
	v_pk_mul_f32 v[32:33], v[20:21], v[32:33]
	v_pk_mul_f32 v[64:65], v[20:21], v[64:65]
	v_pk_fma_f32 v[32:33], v[22:23], v[34:35], v[32:33]
	v_pk_fma_f32 v[64:65], v[22:23], v[66:67], v[64:65]
	v_add_f32_e32 v34, v32, v33
	v_add_f32_e32 v66, v64, v65
	v_pk_fma_f32 v[12:13], v[20:21], v[12:13], v[20:21] neg_lo:[1,0,0] neg_hi:[1,0,0]
	v_add_f32_dpp v35, v34, v34 quad_perm:[1,0,3,2] row_mask:0xf bank_mask:0xf bound_ctrl:1
	v_add_f32_dpp v67, v66, v66 quad_perm:[1,0,3,2] row_mask:0xf bank_mask:0xf bound_ctrl:1
	v_pk_fma_f32 v[14:15], v[22:23], v[14:15], v[22:23] neg_lo:[1,0,0] neg_hi:[1,0,0]
	v_add_f32_dpp v34, v35, v35 quad_perm:[2,3,0,1] row_mask:0xf bank_mask:0xf bound_ctrl:1
	v_add_f32_dpp v66, v67, v67 quad_perm:[2,3,0,1] row_mask:0xf bank_mask:0xf bound_ctrl:1
	v_pk_fma_f32 v[12:13], v[36:37], v[16:17], v[12:13] op_sel_hi:[0,1,1]
	v_add_f32_dpp v35, v34, v34 row_half_mirror row_mask:0xf bank_mask:0xf bound_ctrl:1
	v_add_f32_dpp v67, v66, v66 row_half_mirror row_mask:0xf bank_mask:0xf bound_ctrl:1
	v_pk_fma_f32 v[14:15], v[36:37], v[18:19], v[14:15] op_sel_hi:[0,1,1]
	v_add_f32_dpp v90, v35, v35 row_mirror row_mask:0xf bank_mask:0xf bound_ctrl:1
	v_add_f32_dpp v66, v67, v67 row_mirror row_mask:0xf bank_mask:0xf bound_ctrl:1
	ds_write_b32 v237, v66 offset:43840
	ds_read_b128 v[64:67], v235 offset:20928
	v_pk_fma_f32 v[20:21], v[90:91], v[24:25], v[12:13] op_sel_hi:[0,1,1] neg_lo:[1,0,0] neg_hi:[1,0,0]
	v_pk_fma_f32 v[22:23], v[90:91], v[26:27], v[14:15] op_sel_hi:[0,1,1] neg_lo:[1,0,0] neg_hi:[1,0,0]
	s_waitcnt lgkmcnt(2)
; #define SC_LSTORE(st_) { SC_S1(st_, 0, rg0) SC_S1(st_, 1, rg1) SC_S1(st_, 2, rg2) }
; __device__ __forceinline__ void rwkv_scan_unit(const Params& p, int unit, char* smem) {
;     ...
;         for (int u = 0; u < SCH; ++u) {
;             f32x4 ne = e4, nkd = kd4, nka = ka4, nr = r4, nkk = kk4; float nv = vv;
;             if (u + 1 < SCH) { const char* q = lb + (u + 1) * STEPB;
;                 ne = *(const f32x4*)(q); nkd = *(const f32x4*)(q + 256); nka = *(const f32x4*)(q + 512); nr = *(const f32x4*)(q + 768); nkk = *(const f32x4*)(q + 1024);
;                 nv = *(const float*)(vb + (u + 1) * STEPB); }
;             const f32x2 v2 = {vv, vv}, c2 = {c, c};
;             const f32x2 tA = __builtin_elementwise_fma(v2, (f32x2){kd4[0], kd4[1]}, __builtin_elementwise_fma(-sA, (f32x2){e4[0], e4[1]}, sA));
;             const f32x2 tB = __builtin_elementwise_fma(v2, (f32x2){kd4[2], kd4[3]}, __builtin_elementwise_fma(-sB, (f32x2){e4[2], e4[3]}, sB));
;             sA = __builtin_elementwise_fma(-c2, (f32x2){ka4[0], ka4[1]}, tA);
;             sB = __builtin_elementwise_fma(-c2, (f32x2){ka4[2], ka4[3]}, tB);
;             const f32x2 yv = __builtin_elementwise_fma(sB, (f32x2){r4[2], r4[3]}, sA * (f32x2){r4[0], r4[1]});
;             float y = yv[0] + yv[1];
;             if (u + 1 < SCH) {
;                 const f32x2 cv = __builtin_elementwise_fma(sB, (f32x2){nkk[2], nkk[3]}, sA * (f32x2){nkk[0], nkk[1]});
;                 float cn = cv[0] + cv[1];
;                 cn = DPP_ADD(cn, 0xB1);  y = DPP_ADD(y, 0xB1);
;                 cn = DPP_ADD(cn, 0x4E);  y = DPP_ADD(y, 0x4E);
;                 cn = DPP_ADD(cn, 0x141); y = DPP_ADD(y, 0x141);
;                 cn = DPP_ADD(cn, 0x140); y = DPP_ADD(y, 0x140);
;                 c = cn;
;             } else y = red16(y);
;             if (ks == 0) yl[u * 16] = y;
;             e4 = ne; kd4 = nkd; ka4 = nka; r4 = nr; kk4 = nkk; vv = nv;
;         }
;         s0 = sA[0]; s1 = sA[1]; s2 = sB[0]; s3 = sB[1];
;         __builtin_amdgcn_sched_barrier(0);
;         if (ci + 1 < NCH) { SC_LSTORE(((ci + 1) & 1) * STG) }
;         __syncthreads();
;         {
;             const int u = tid >> 4, r = tid & 15;
;             Yb[((size_t)b * TT + step_tok(ci * SCH + u, d)) * 1024 + r] = f2bf(*((const float*)(smem + YOFF + (ci & 1) * 1024) + u * 16 + r));
;         }
;     }
	v_pk_mul_f32 v[94:95], v[20:21], v[94:95]
	v_pk_mul_f32 v[28:29], v[20:21], v[28:29]
	v_pk_fma_f32 v[94:95], v[22:23], v[96:97], v[94:95]
	v_pk_fma_f32 v[28:29], v[22:23], v[30:31], v[28:29]
	v_add_f32_e32 v96, v94, v95
	v_add_f32_e32 v30, v28, v29
	v_pk_fma_f32 v[40:41], v[20:21], v[40:41], v[20:21] neg_lo:[1,0,0] neg_hi:[1,0,0]
	v_add_f32_dpp v97, v96, v96 quad_perm:[1,0,3,2] row_mask:0xf bank_mask:0xf bound_ctrl:1
	v_add_f32_dpp v31, v30, v30 quad_perm:[1,0,3,2] row_mask:0xf bank_mask:0xf bound_ctrl:1
	v_pk_fma_f32 v[42:43], v[22:23], v[42:43], v[22:23] neg_lo:[1,0,0] neg_hi:[1,0,0]
	v_add_f32_dpp v96, v97, v97 quad_perm:[2,3,0,1] row_mask:0xf bank_mask:0xf bound_ctrl:1
	v_add_f32_dpp v30, v31, v31 quad_perm:[2,3,0,1] row_mask:0xf bank_mask:0xf bound_ctrl:1
	v_pk_fma_f32 v[40:41], v[38:39], v[44:45], v[40:41] op_sel_hi:[0,1,1]
	v_add_f32_dpp v97, v96, v96 row_half_mirror row_mask:0xf bank_mask:0xf bound_ctrl:1
	v_add_f32_dpp v31, v30, v30 row_half_mirror row_mask:0xf bank_mask:0xf bound_ctrl:1
	v_pk_fma_f32 v[42:43], v[38:39], v[46:47], v[42:43] op_sel_hi:[0,1,1]
	v_add_f32_dpp v90, v97, v97 row_mirror row_mask:0xf bank_mask:0xf bound_ctrl:1
	v_add_f32_dpp v30, v31, v31 row_mirror row_mask:0xf bank_mask:0xf bound_ctrl:1
	ds_write_b32 v237, v30 offset:43904
	v_pk_fma_f32 v[20:21], v[90:91], v[60:61], v[40:41] op_sel_hi:[0,1,1] neg_lo:[1,0,0] neg_hi:[1,0,0]
	v_pk_fma_f32 v[22:23], v[90:91], v[62:63], v[42:43] op_sel_hi:[0,1,1] neg_lo:[1,0,0] neg_hi:[1,0,0]
	s_waitcnt lgkmcnt(1)
	v_pk_mul_f32 v[64:65], v[20:21], v[64:65]
	v_pk_fma_f32 v[64:65], v[22:23], v[66:67], v[64:65]
	s_nop 0
	v_add_f32_e32 v66, v64, v65
	s_nop 1
	v_add_f32_dpp v67, v66, v66 quad_perm:[1,0,3,2] row_mask:0xf bank_mask:0xf bound_ctrl:1
	s_nop 1
	v_add_f32_dpp v66, v67, v67 quad_perm:[2,3,0,1] row_mask:0xf bank_mask:0xf bound_ctrl:1
	s_nop 1
	v_add_f32_dpp v67, v66, v66 row_half_mirror row_mask:0xf bank_mask:0xf bound_ctrl:1
	s_nop 1
	v_add_f32_dpp v66, v67, v67 row_mirror row_mask:0xf bank_mask:0xf bound_ctrl:1
	ds_write_b32 v237, v66 offset:43968
	s_cmpk_eq_i32 s55, 0x10f0
	s_cbranch_scc1 .Lsc_p3_flush
	s_waitcnt vmcnt(12)
	v_cvt_f32_f16_sdwa v13, v160 dst_sel:DWORD dst_unused:UNUSED_PAD src0_sel:WORD_1
	v_cvt_f32_f16_e32 v12, v160
	v_cvt_f32_f16_sdwa v15, v161 dst_sel:DWORD dst_unused:UNUSED_PAD src0_sel:WORD_1
	v_cvt_f32_f16_e32 v14, v161
	ds_write_b128 v238, v[12:15]
	v_cvt_f32_f16_sdwa v13, v162 dst_sel:DWORD dst_unused:UNUSED_PAD src0_sel:WORD_1
	v_cvt_f32_f16_e32 v12, v162
	v_cvt_f32_f16_sdwa v15, v163 dst_sel:DWORD dst_unused:UNUSED_PAD src0_sel:WORD_1
	v_cvt_f32_f16_e32 v14, v163
	ds_write_b128 v238, v[12:15] offset:16
	v_cvt_f32_f16_sdwa v13, v164 dst_sel:DWORD dst_unused:UNUSED_PAD src0_sel:WORD_1
	v_cvt_f32_f16_e32 v12, v164
	v_cvt_f32_f16_sdwa v15, v165 dst_sel:DWORD dst_unused:UNUSED_PAD src0_sel:WORD_1
	v_cvt_f32_f16_e32 v14, v165
	ds_write_b128 v239, v[12:15]
	v_cvt_f32_f16_sdwa v13, v166 dst_sel:DWORD dst_unused:UNUSED_PAD src0_sel:WORD_1
	v_cvt_f32_f16_e32 v12, v166
	v_cvt_f32_f16_sdwa v15, v167 dst_sel:DWORD dst_unused:UNUSED_PAD src0_sel:WORD_1
	v_cvt_f32_f16_e32 v14, v167
	ds_write_b128 v239, v[12:15] offset:16
	v_cvt_f32_f16_sdwa v13, v168 dst_sel:DWORD dst_unused:UNUSED_PAD src0_sel:WORD_1
	v_cvt_f32_f16_e32 v12, v168
	v_cvt_f32_f16_sdwa v15, v169 dst_sel:DWORD dst_unused:UNUSED_PAD src0_sel:WORD_1
	v_cvt_f32_f16_e32 v14, v169
	ds_write_b128 v240, v[12:15]
	v_cvt_f32_f16_sdwa v13, v170 dst_sel:DWORD dst_unused:UNUSED_PAD src0_sel:WORD_1
	v_cvt_f32_f16_e32 v12, v170
	v_cvt_f32_f16_sdwa v15, v171 dst_sel:DWORD dst_unused:UNUSED_PAD src0_sel:WORD_1
	v_cvt_f32_f16_e32 v14, v171
	ds_write_b128 v240, v[12:15] offset:16
.Lsc_p3_flush:
	s_waitcnt lgkmcnt(0)
	s_barrier
	ds_read_b32 v12, v209 offset:43008
	s_cmpk_ge_u32 s55, 0x100
	s_movk_i32 s98, 0xff
	s_movk_i32 s99, 0x11ff
	s_cselect_b32 s98, s99, s98
	s_sub_u32 s98, s98, s55
	s_cmp_lg_u64 s[44:45], 0
	s_cselect_b32 s98, s55, s98
	s_lshl_b32 s98, s98, 11
	s_mov_b32 s99, 0
	s_movk_i32 s0, 0x7fff
	s_add_i32 s55, s55, 16
	s_waitcnt lgkmcnt(0)
	v_bfe_u32 v14, v12, 16, 1
	v_add3_u32 v14, v12, v14, s0
	v_lshl_add_u64 v[12:13], v[210:211], 0, s[98:99]
	s_add_i32 s64, s64, 1
	s_cmpk_lg_i32 s55, 0x1100
	global_store_short_d16_hi v[12:13], v14, off
	s_cbranch_scc0 .LBB0_420
	s_branch .Lsc_p0
